# pool mixer: pscale also staged in LDS; weight fragment ds_reads issued two n-tiles ahead (rolling), no global loads left in the MFMA part of a pool unit
# speedup vs baseline: 1.0373x; 1.0026x over previous
.LBB0_577:
	s_lshr_b32 s2, s70, 5
	v_readlane_b32 s0, v253, 38
	s_cmp_ge_i32 s0, s2
	s_cbranch_scc1 .LBB0_595
	s_lshl_b32 s68, s74, 9
	v_readlane_b32 s8, v253, 16
	s_lshr_b32 s4, s70, 7
	s_lshl_b64 s[0:1], s[68:69], 2
	v_readlane_b32 s22, v253, 30
	v_readlane_b32 s23, v253, 31
	s_add_u32 s30, s22, s0
	s_addc_u32 s31, s23, s1
	v_readlane_b32 s0, v255, 7
	s_add_u32 s34, s0, 0x510000
	v_readlane_b32 s1, v255, 8
	s_addc_u32 s35, s1, 0
	s_add_u32 s36, s0, 0x508000
	s_addc_u32 s37, s1, 0
	s_add_u32 s38, s0, 0x500000
	s_addc_u32 s39, s1, 0
	s_add_u32 s74, s0, 0x518000
	s_addc_u32 s75, s1, 0
	s_abs_i32 s46, s4
	v_cvt_f32_u32_e32 v0, s46
	s_sub_i32 s0, 0, s46
	v_readlane_b32 s65, v253, 38
	s_ashr_i32 s3, s4, 31
	v_rcp_iflag_f32_e32 v0, v0
	s_lshl_b32 s56, s4, 7
	s_lshl_b32 s64, s51, 7
	v_readlane_b32 s9, v253, 17
	v_mul_f32_e32 v0, 0x4f7ffffe, v0
	v_cvt_u32_f32_e32 v0, v0
	v_readlane_b32 s10, v253, 18
	v_readlane_b32 s11, v253, 19
	v_readlane_b32 s12, v253, 20
	v_readfirstlane_b32 s1, v0
	s_mul_i32 s0, s0, s1
	s_mul_hi_u32 s0, s1, s0
	s_add_i32 s47, s1, s0
	s_lshl_b32 s0, s65, 7
	v_readlane_b32 s1, v253, 40
	s_add_i32 s59, s1, s0
	v_readlane_b32 s13, v253, 21
	v_readlane_b32 s14, v253, 22
	v_readlane_b32 s15, v253, 23
	v_readlane_b32 s16, v253, 24
	v_readlane_b32 s17, v253, 25
	v_readlane_b32 s18, v253, 26
	v_readlane_b32 s19, v253, 27
	v_readlane_b32 s20, v253, 28
	v_readlane_b32 s21, v253, 29
	s_barrier
	v_lshlrev_b32_e32 v84, 4, v209
	s_mov_b64 s[98:99], s[38:39]
	global_load_dwordx4 v[88:91], v84, s[98:99]
	s_add_u32 s98, s98, 0x2000
	s_addc_u32 s99, s99, 0
	global_load_dwordx4 v[92:95], v84, s[98:99]
	s_add_u32 s98, s98, 0x2000
	s_addc_u32 s99, s99, 0
	global_load_dwordx4 v[96:99], v84, s[98:99]
	s_add_u32 s98, s98, 0x2000
	s_addc_u32 s99, s99, 0
	global_load_dwordx4 v[100:103], v84, s[98:99]
	s_add_u32 s98, s98, 0x2000
	s_addc_u32 s99, s99, 0
	global_load_dwordx4 v[104:107], v84, s[98:99]
	s_add_u32 s98, s98, 0x2000
	s_addc_u32 s99, s99, 0
	global_load_dwordx4 v[108:111], v84, s[98:99]
	s_add_u32 s98, s98, 0x2000
	s_addc_u32 s99, s99, 0
	global_load_dwordx4 v[112:115], v84, s[98:99]
	s_add_u32 s98, s98, 0x2000
	s_addc_u32 s99, s99, 0
	global_load_dwordx4 v[116:119], v84, s[98:99]
	s_add_u32 s98, s98, 0x2000
	s_addc_u32 s99, s99, 0
	global_load_dwordx4 v[120:123], v84, s[98:99]
	s_add_u32 s98, s98, 0x2000
	s_addc_u32 s99, s99, 0
	global_load_dwordx4 v[124:127], v84, s[98:99]
	s_add_u32 s98, s98, 0x2000
	s_addc_u32 s99, s99, 0
	global_load_dwordx4 v[128:131], v84, s[98:99]
	s_add_u32 s98, s98, 0x2000
	s_addc_u32 s99, s99, 0
	global_load_dwordx4 v[132:135], v84, s[98:99]
	s_add_u32 s98, s98, 0x2000
	s_addc_u32 s99, s99, 0
	global_load_dwordx4 v[136:139], v84, s[98:99]
	s_add_u32 s98, s98, 0x2000
	s_addc_u32 s99, s99, 0
	global_load_dwordx4 v[140:143], v84, s[98:99]
	s_add_u32 s98, s98, 0x2000
	s_addc_u32 s99, s99, 0
	global_load_dwordx4 v[144:147], v84, s[98:99]
	s_add_u32 s98, s98, 0x2000
	s_addc_u32 s99, s99, 0
	global_load_dwordx4 v[148:151], v84, s[98:99]
	v_lshrrev_b32_e32 v85, 4, v209
	v_and_b32_e32 v86, 15, v209
	v_mul_u32_u24_e32 v85, 0x110, v85
	v_lshl_add_u32 v85, v86, 4, v85
	v_add_u32_e32 v86, 0x11000, v85
	s_waitcnt vmcnt(0)
	ds_write_b128 v85, v[88:91]
	ds_write_b128 v85, v[92:95] offset:8704
	ds_write_b128 v85, v[96:99] offset:17408
	ds_write_b128 v85, v[100:103] offset:26112
	ds_write_b128 v85, v[104:107] offset:34816
	ds_write_b128 v85, v[108:111] offset:43520
	ds_write_b128 v85, v[112:115] offset:52224
	ds_write_b128 v85, v[116:119] offset:60928
	ds_write_b128 v86, v[120:123]
	ds_write_b128 v86, v[124:127] offset:8704
	ds_write_b128 v86, v[128:131] offset:17408
	ds_write_b128 v86, v[132:135] offset:26112
	ds_write_b128 v86, v[136:139] offset:34816
	ds_write_b128 v86, v[140:143] offset:43520
	ds_write_b128 v86, v[144:147] offset:52224
	ds_write_b128 v86, v[148:151] offset:60928
	s_waitcnt lgkmcnt(0)
	v_and_b32_e32 v87, 0x7f, v209
	v_lshlrev_b32_e32 v87, 4, v87
	global_load_dwordx4 v[88:91], v87, s[30:31]
	v_add_u32_e32 v87, 0x22000, v87
	s_waitcnt vmcnt(0)
	ds_write_b128 v87, v[88:91]
	s_waitcnt lgkmcnt(0)
	s_barrier
	s_branch .LBB0_580
.LBB0_579:
	v_lshlrev_b32_e32 v6, 2, v0
	v_add_u32_e32 v6, 0x22000, v6
	ds_read_b128 v[6:9], v6
	s_add_i32 s65, s65, s51
	s_add_i32 s59, s59, s64
	v_lshl_add_u64 v[10:11], v[0:1], 1, v[26:27]
	s_cmp_ge_i32 s65, s2
	s_waitcnt lgkmcnt(0)
	v_pk_mul_f32 v[4:5], v[4:5], v[8:9]
	v_pk_mul_f32 v[2:3], v[2:3], v[6:7]
	s_nop 0
	v_cvt_pk_bf16_f32 v2, v2, v3
	v_cvt_pk_bf16_f32 v3, v4, v5
	global_store_dwordx2 v[10:11], v[2:3], off
	s_cbranch_scc1 .LBB0_594

.LBB0_584:
	s_cmp_gt_i32 s16, 1
	s_cbranch_scc0 .LBB0_588
	s_cmp_eq_u32 s16, 2
	s_mov_b64 s[4:5], -1
	s_cbranch_scc0 .LBB0_587
	v_mov_b32_e32 v0, v209
	s_lshl_b32 s6, s56, 1
	v_readfirstlane_b32 s0, v0
	s_ashr_i32 s0, s0, 2
	v_and_b32_e32 v53, 15, v0
	v_bfi_b32 v32, -16, s0, v0
	v_bfe_u32 v51, v0, 4, 2
	v_subrev_u32_e32 v0, s6, v32
	v_add_u32_e32 v48, s59, v0
	s_mov_b32 s0, 0x38e38e39
	v_mul_hi_i32 v0, v48, s0
	v_lshrrev_b32_e32 v2, 31, v0
	v_ashrrev_i32_e32 v0, 13, v0
	v_add_u32_e32 v0, v0, v2
	v_mul_i32_i24_e32 v0, 0x9000, v0
	v_sub_u32_e32 v0, v48, v0
	s_mov_b32 s0, 0x8000
	v_cmp_gt_i32_e32 vcc, s0, v0
	v_lshlrev_b32_e32 v46, 4, v51
	v_mov_b32_e32 v47, v1
	v_cndmask_b32_e32 v2, v220, v221, vcc
	v_and_b32_e32 v56, v2, v0
	v_cndmask_b32_e32 v55, v217, v210, vcc
	v_add_u32_e32 v2, -4, v56
	v_add_u32_e32 v3, 4, v56
	v_max_i32_e32 v0, 0, v2
	v_min_u32_e32 v3, v3, v55
	v_sub_u32_e32 v0, v3, v0
	v_cvt_f32_i32_e32 v0, v0
	v_add_u32_e32 v10, -2, v56
	v_add_u32_e32 v14, -1, v56
	v_cmp_lt_u32_e64 s[4:5], v14, v55
	v_div_scale_f32 v3, s[0:1], v0, v0, 1.0
	v_rcp_f32_e32 v4, v3
	v_readlane_b32 s0, v253, 62
	v_readlane_b32 s1, v253, 63
	v_cndmask_b32_e64 v14, v56, v14, s[4:5]
	v_fma_f32 v5, -v3, v4, 1.0
	v_fmac_f32_e32 v4, v5, v4
	v_div_scale_f32 v5, vcc, 1.0, v0, 1.0
	v_mul_f32_e32 v6, v5, v4
	v_fma_f32 v7, -v3, v6, v5
	v_fmac_f32_e32 v6, v7, v4
	v_fma_f32 v3, -v3, v6, v5
	v_div_fmas_f32 v3, v3, v4, v6
	v_cmp_lt_u32_e32 vcc, v2, v55
	v_add_u32_e32 v6, -3, v56
	v_lshl_add_u64 v[30:31], s[0:1], 0, v[46:47]
	v_cndmask_b32_e64 v52, 0, 1.0, vcc
	v_cndmask_b32_e32 v2, v56, v2, vcc
	v_cmp_lt_u32_e32 vcc, v6, v55
	v_add_u32_e32 v2, v32, v2
	v_cmp_lt_u32_e64 s[0:1], v10, v55
	v_cndmask_b32_e32 v6, v56, v6, vcc
	v_subrev_u32_e32 v2, s6, v2
	v_add_u32_e32 v6, v32, v6
	v_cndmask_b32_e64 v10, v56, v10, s[0:1]
	v_sub_u32_e32 v2, v2, v56
	v_subrev_u32_e32 v6, s6, v6
	v_add_u32_e32 v10, v32, v10
	v_add_u32_e32 v22, 1, v56
	v_add_u32_e32 v2, s59, v2
	v_sub_u32_e32 v6, v6, v56
	v_subrev_u32_e32 v10, s6, v10
	v_add_u32_e32 v14, v32, v14
	v_cmp_lt_u32_e64 s[8:9], v22, v55
	v_add_u32_e32 v26, 2, v56
	v_div_fixup_f32 v50, v3, v0, 1.0
	v_ashrrev_i32_e32 v3, 31, v2
	v_add_u32_e32 v6, s59, v6
	v_sub_u32_e32 v10, v10, v56
	v_subrev_u32_e32 v14, s6, v14
	v_cndmask_b32_e64 v22, v56, v22, s[8:9]
	v_cmp_lt_u32_e64 s[10:11], v26, v55
	v_add_u32_e32 v33, 3, v56
	v_lshlrev_b64 v[2:3], 10, v[2:3]
	v_ashrrev_i32_e32 v7, 31, v6
	v_add_u32_e32 v10, s59, v10
	v_sub_u32_e32 v14, v14, v56
	v_add_u32_e32 v22, v32, v22
	v_cndmask_b32_e64 v26, v56, v26, s[10:11]
	v_cmp_lt_u32_e64 s[12:13], v33, v55
	v_lshl_add_u64 v[74:75], v[30:31], 0, v[2:3]
	v_lshlrev_b64 v[6:7], 10, v[6:7]
	v_ashrrev_i32_e32 v11, 31, v10
	v_add_u32_e32 v14, s59, v14
	v_subrev_u32_e32 v22, s6, v22
	v_add_u32_e32 v26, v32, v26
	v_cndmask_b32_e64 v33, v56, v33, s[12:13]
	global_load_dwordx4 v[2:5], v[74:75], off offset:512
	v_lshl_add_u64 v[72:73], v[30:31], 0, v[6:7]
	v_lshlrev_b64 v[10:11], 10, v[10:11]
	v_ashrrev_i32_e32 v15, 31, v14
	v_sub_u32_e32 v22, v22, v56
	v_subrev_u32_e32 v26, s6, v26
	v_add_u32_e32 v32, v32, v33
	v_ashrrev_i32_e32 v49, 31, v48
	global_load_dwordx4 v[6:9], v[72:73], off offset:512
	v_lshl_add_u64 v[70:71], v[30:31], 0, v[10:11]
	v_lshlrev_b64 v[14:15], 10, v[14:15]
	v_add_u32_e32 v22, s59, v22
	v_sub_u32_e32 v26, v26, v56
	v_subrev_u32_e32 v32, s6, v32
	v_lshlrev_b64 v[18:19], 10, v[48:49]
	global_load_dwordx4 v[10:13], v[70:71], off offset:512
	v_lshl_add_u64 v[68:69], v[30:31], 0, v[14:15]
	v_ashrrev_i32_e32 v23, 31, v22
	v_add_u32_e32 v26, s59, v26
	v_sub_u32_e32 v32, v32, v56
	global_load_dwordx4 v[14:17], v[68:69], off offset:512
	v_lshl_add_u64 v[38:39], v[30:31], 0, v[18:19]
	v_lshlrev_b64 v[22:23], 10, v[22:23]
	v_ashrrev_i32_e32 v27, 31, v26
	v_add_u32_e32 v32, s59, v32
	global_load_dwordx4 v[18:21], v[38:39], off offset:512
	v_lshl_add_u64 v[40:41], v[30:31], 0, v[22:23]
	v_lshlrev_b64 v[26:27], 10, v[26:27]
	v_ashrrev_i32_e32 v33, 31, v32
	global_load_dwordx4 v[22:25], v[40:41], off offset:512
	v_lshl_add_u64 v[42:43], v[30:31], 0, v[26:27]
	v_lshlrev_b64 v[32:33], 10, v[32:33]
	global_load_dwordx4 v[26:29], v[42:43], off offset:512
	v_lshl_add_u64 v[44:45], v[30:31], 0, v[32:33]
	global_load_dwordx4 v[30:33], v[44:45], off offset:512
	global_load_dwordx4 v[92:95], v[74:75], off offset:576
	global_load_dwordx4 v[96:99], v[72:73], off offset:576
	global_load_dwordx4 v[100:103], v[70:71], off offset:576
	global_load_dwordx4 v[104:107], v[68:69], off offset:576
	global_load_dwordx4 v[108:111], v[38:39], off offset:576
	global_load_dwordx4 v[112:115], v[40:41], off offset:576
	global_load_dwordx4 v[116:119], v[42:43], off offset:576
	global_load_dwordx4 v[120:123], v[44:45], off offset:576
	global_load_dwordx4 v[124:127], v[74:75], off offset:640
	global_load_dwordx4 v[128:131], v[72:73], off offset:640
	global_load_dwordx4 v[132:135], v[70:71], off offset:640
	global_load_dwordx4 v[136:139], v[68:69], off offset:640
	global_load_dwordx4 v[140:143], v[38:39], off offset:640
	global_load_dwordx4 v[144:147], v[40:41], off offset:640
	global_load_dwordx4 v[148:151], v[42:43], off offset:640
	global_load_dwordx4 v[152:155], v[44:45], off offset:640
	global_load_dwordx4 v[156:159], v[74:75], off offset:704
	global_load_dwordx4 v[160:163], v[72:73], off offset:704
	global_load_dwordx4 v[164:167], v[70:71], off offset:704
	global_load_dwordx4 v[168:171], v[68:69], off offset:704
	global_load_dwordx4 v[172:175], v[38:39], off offset:704
	global_load_dwordx4 v[176:179], v[40:41], off offset:704
	global_load_dwordx4 v[180:183], v[42:43], off offset:704
	global_load_dwordx4 v[184:187], v[44:45], off offset:704
	v_cndmask_b32_e64 v54, 0, 1.0, vcc
	v_cndmask_b32_e64 v58, 0, 1.0, s[0:1]
	v_cndmask_b32_e64 v66, 0, 1.0, s[4:5]
	v_cmp_lt_u32_e32 vcc, v56, v55
	v_cndmask_b32_e64 v62, 0, 1.0, s[8:9]
	v_cndmask_b32_e64 v60, 0, 1.0, s[10:11]
	v_cndmask_b32_e64 v64, 0, 1.0, vcc
	v_cndmask_b32_e64 v56, 0, 1.0, s[12:13]
	s_mov_b64 s[0:1], 0x400
	v_lshlrev_b32_e32 v0, 3, v51
	s_mov_b64 s[4:5], 0
	s_waitcnt vmcnt(31)
	v_lshlrev_b32_e32 v34, 16, v2
	v_and_b32_e32 v35, 0xffff0000, v2
	v_lshlrev_b32_e32 v36, 16, v3
	v_and_b32_e32 v37, 0xffff0000, v3
	v_pk_fma_f32 v[34:35], v[52:53], v[34:35], 0 op_sel_hi:[0, 1, 0]
	v_lshlrev_b32_e32 v76, 16, v4
	v_and_b32_e32 v77, 0xffff0000, v4
	v_lshlrev_b32_e32 v78, 16, v5
	s_waitcnt vmcnt(30)
	v_lshlrev_b32_e32 v2, 16, v6
	v_and_b32_e32 v3, 0xffff0000, v6
	v_pk_fma_f32 v[2:3], v[54:55], v[2:3], v[34:35] op_sel_hi:[0, 1, 1]
	v_and_b32_e32 v79, 0xffff0000, v5
	v_lshlrev_b32_e32 v4, 16, v7
	v_and_b32_e32 v5, 0xffff0000, v7
	v_lshlrev_b32_e32 v6, 16, v8
	s_waitcnt vmcnt(29)
	v_lshlrev_b32_e32 v80, 16, v10
	v_and_b32_e32 v81, 0xffff0000, v10
	v_pk_fma_f32 v[2:3], v[58:59], v[80:81], v[2:3] op_sel_hi:[0, 1, 1]
	v_lshlrev_b32_e32 v10, 16, v11
	v_and_b32_e32 v11, 0xffff0000, v11
	s_waitcnt vmcnt(28)
	v_lshlrev_b32_e32 v34, 16, v14
	v_and_b32_e32 v35, 0xffff0000, v14
	v_pk_fma_f32 v[2:3], v[66:67], v[34:35], v[2:3] op_sel_hi:[0, 1, 1]
	v_and_b32_e32 v7, 0xffff0000, v8
	v_lshlrev_b32_e32 v82, 16, v12
	s_waitcnt vmcnt(27)
	v_lshlrev_b32_e32 v34, 16, v18
	v_and_b32_e32 v35, 0xffff0000, v18
	v_pk_fma_f32 v[2:3], v[64:65], v[34:35], v[2:3] op_sel_hi:[0, 1, 1]
	v_and_b32_e32 v83, 0xffff0000, v12
	s_waitcnt vmcnt(26)
	v_lshlrev_b32_e32 v80, 16, v22
	v_and_b32_e32 v81, 0xffff0000, v22
	v_pk_fma_f32 v[2:3], v[62:63], v[80:81], v[2:3] op_sel_hi:[0, 1, 1]
	s_waitcnt vmcnt(25)
	v_lshlrev_b32_e32 v80, 16, v26
	v_and_b32_e32 v81, 0xffff0000, v26
	v_pk_fma_f32 v[2:3], v[60:61], v[80:81], v[2:3] op_sel_hi:[0, 1, 1]
	s_waitcnt vmcnt(24)
	v_lshlrev_b32_e32 v80, 16, v30
	v_and_b32_e32 v81, 0xffff0000, v30
	v_pk_fma_f32 v[2:3], v[56:57], v[80:81], v[2:3] op_sel_hi:[0, 1, 1]
	v_pk_fma_f32 v[2:3], v[50:51], v[2:3], v[34:35] op_sel_hi:[0, 1, 1] neg_lo:[0, 0, 1] neg_hi:[0, 0, 1]
	v_pk_fma_f32 v[34:35], v[52:53], v[36:37], 0 op_sel_hi:[0, 1, 0]
	v_pk_fma_f32 v[4:5], v[54:55], v[4:5], v[34:35] op_sel_hi:[0, 1, 1]
	v_pk_fma_f32 v[4:5], v[58:59], v[10:11], v[4:5] op_sel_hi:[0, 1, 1]
	v_lshlrev_b32_e32 v10, 16, v15
	v_and_b32_e32 v11, 0xffff0000, v15
	v_pk_fma_f32 v[4:5], v[66:67], v[10:11], v[4:5] op_sel_hi:[0, 1, 1]
	v_lshlrev_b32_e32 v10, 16, v19
	v_and_b32_e32 v11, 0xffff0000, v19
	v_pk_fma_f32 v[4:5], v[64:65], v[10:11], v[4:5] op_sel_hi:[0, 1, 1]
	v_lshlrev_b32_e32 v14, 16, v23
	v_and_b32_e32 v15, 0xffff0000, v23
	v_pk_fma_f32 v[4:5], v[62:63], v[14:15], v[4:5] op_sel_hi:[0, 1, 1]
	v_lshlrev_b32_e32 v14, 16, v27
	v_and_b32_e32 v15, 0xffff0000, v27
	v_pk_fma_f32 v[4:5], v[60:61], v[14:15], v[4:5] op_sel_hi:[0, 1, 1]
	v_lshlrev_b32_e32 v14, 16, v31
	v_and_b32_e32 v15, 0xffff0000, v31
	v_pk_fma_f32 v[4:5], v[56:57], v[14:15], v[4:5] op_sel_hi:[0, 1, 1]
	v_pk_fma_f32 v[4:5], v[50:51], v[4:5], v[10:11] op_sel_hi:[0, 1, 1] neg_lo:[0, 0, 1] neg_hi:[0, 0, 1]
	v_cvt_pk_bf16_f32 v2, v2, v3
	v_cvt_pk_bf16_f32 v3, v4, v5
	v_pk_fma_f32 v[4:5], v[52:53], v[76:77], 0 op_sel_hi:[0, 1, 0]
	v_pk_fma_f32 v[4:5], v[54:55], v[6:7], v[4:5] op_sel_hi:[0, 1, 1]
	v_pk_fma_f32 v[4:5], v[58:59], v[82:83], v[4:5] op_sel_hi:[0, 1, 1]
	v_lshlrev_b32_e32 v6, 16, v16
	v_and_b32_e32 v7, 0xffff0000, v16
	v_pk_fma_f32 v[4:5], v[66:67], v[6:7], v[4:5] op_sel_hi:[0, 1, 1]
	v_lshlrev_b32_e32 v6, 16, v20
	v_and_b32_e32 v7, 0xffff0000, v20
	v_pk_fma_f32 v[4:5], v[64:65], v[6:7], v[4:5] op_sel_hi:[0, 1, 1]
	v_lshlrev_b32_e32 v10, 16, v24
	v_and_b32_e32 v11, 0xffff0000, v24
	v_pk_fma_f32 v[4:5], v[62:63], v[10:11], v[4:5] op_sel_hi:[0, 1, 1]
	v_lshlrev_b32_e32 v10, 16, v28
	v_and_b32_e32 v11, 0xffff0000, v28
	v_pk_fma_f32 v[4:5], v[60:61], v[10:11], v[4:5] op_sel_hi:[0, 1, 1]
	v_lshlrev_b32_e32 v10, 16, v32
	v_and_b32_e32 v11, 0xffff0000, v32
	v_pk_fma_f32 v[4:5], v[56:57], v[10:11], v[4:5] op_sel_hi:[0, 1, 1]
	v_lshlrev_b32_e32 v8, 16, v9
	v_and_b32_e32 v9, 0xffff0000, v9
	v_pk_fma_f32 v[4:5], v[50:51], v[4:5], v[6:7] op_sel_hi:[0, 1, 1] neg_lo:[0, 0, 1] neg_hi:[0, 0, 1]
	v_pk_fma_f32 v[6:7], v[52:53], v[78:79], 0 op_sel_hi:[0, 1, 0]
	v_lshlrev_b32_e32 v12, 16, v13
	v_and_b32_e32 v13, 0xffff0000, v13
	v_pk_fma_f32 v[6:7], v[54:55], v[8:9], v[6:7] op_sel_hi:[0, 1, 1]
	v_pk_fma_f32 v[6:7], v[58:59], v[12:13], v[6:7] op_sel_hi:[0, 1, 1]
	v_lshlrev_b32_e32 v8, 16, v17
	v_and_b32_e32 v9, 0xffff0000, v17
	v_pk_fma_f32 v[6:7], v[66:67], v[8:9], v[6:7] op_sel_hi:[0, 1, 1]
	v_lshlrev_b32_e32 v8, 16, v21
	v_and_b32_e32 v9, 0xffff0000, v21
	v_pk_fma_f32 v[6:7], v[64:65], v[8:9], v[6:7] op_sel_hi:[0, 1, 1]
	v_lshlrev_b32_e32 v10, 16, v25
	v_and_b32_e32 v11, 0xffff0000, v25
	v_pk_fma_f32 v[6:7], v[62:63], v[10:11], v[6:7] op_sel_hi:[0, 1, 1]
	v_lshlrev_b32_e32 v10, 16, v29
	v_and_b32_e32 v11, 0xffff0000, v29
	v_pk_fma_f32 v[6:7], v[60:61], v[10:11], v[6:7] op_sel_hi:[0, 1, 1]
	v_lshlrev_b32_e32 v10, 16, v33
	v_and_b32_e32 v11, 0xffff0000, v33
	v_pk_fma_f32 v[6:7], v[56:57], v[10:11], v[6:7] op_sel_hi:[0, 1, 1]
	v_pk_fma_f32 v[6:7], v[50:51], v[6:7], v[8:9] op_sel_hi:[0, 1, 1] neg_lo:[0, 0, 1] neg_hi:[0, 0, 1]
	v_cvt_pk_bf16_f32 v4, v4, v5
	v_cvt_pk_bf16_f32 v5, v6, v7
	s_nop 0
	s_nop 0
	s_nop 0
	s_nop 0
	s_nop 0
	s_nop 0
	s_nop 0
	s_nop 0
	s_waitcnt vmcnt(23)
	v_lshlrev_b32_e32 v76, 16, v92
	v_and_b32_e32 v77, 0xffff0000, v92
	v_lshlrev_b32_e32 v78, 16, v93
	v_and_b32_e32 v79, 0xffff0000, v93
	s_waitcnt vmcnt(22)
	v_lshlrev_b32_e32 v6, 16, v96
	v_and_b32_e32 v7, 0xffff0000, v96
	v_pk_fma_f32 v[76:77], v[52:53], v[76:77], 0 op_sel_hi:[0, 1, 0]
	s_waitcnt vmcnt(21)
	v_lshlrev_b32_e32 v84, 16, v100
	v_and_b32_e32 v85, 0xffff0000, v100
	v_pk_fma_f32 v[6:7], v[54:55], v[6:7], v[76:77] op_sel_hi:[0, 1, 1]
	v_pk_fma_f32 v[6:7], v[58:59], v[84:85], v[6:7] op_sel_hi:[0, 1, 1]
	s_waitcnt vmcnt(20)
	v_lshlrev_b32_e32 v76, 16, v104
	v_and_b32_e32 v77, 0xffff0000, v104
	v_pk_fma_f32 v[6:7], v[66:67], v[76:77], v[6:7] op_sel_hi:[0, 1, 1]
	s_waitcnt vmcnt(19)
	v_lshlrev_b32_e32 v76, 16, v108
	v_and_b32_e32 v77, 0xffff0000, v108
	v_pk_fma_f32 v[6:7], v[64:65], v[76:77], v[6:7] op_sel_hi:[0, 1, 1]
	s_waitcnt vmcnt(18)
	v_lshlrev_b32_e32 v84, 16, v112
	v_and_b32_e32 v85, 0xffff0000, v112
	v_pk_fma_f32 v[6:7], v[62:63], v[84:85], v[6:7] op_sel_hi:[0, 1, 1]
	s_waitcnt vmcnt(17)
	v_lshlrev_b32_e32 v84, 16, v116
	v_and_b32_e32 v85, 0xffff0000, v116
	v_pk_fma_f32 v[6:7], v[60:61], v[84:85], v[6:7] op_sel_hi:[0, 1, 1]
	s_waitcnt vmcnt(16)
	v_lshlrev_b32_e32 v84, 16, v120
	v_and_b32_e32 v85, 0xffff0000, v120
	v_pk_fma_f32 v[6:7], v[56:57], v[84:85], v[6:7] op_sel_hi:[0, 1, 1]
	v_lshlrev_b32_e32 v80, 16, v94
	v_and_b32_e32 v81, 0xffff0000, v94
	v_lshlrev_b32_e32 v82, 16, v95
	v_and_b32_e32 v83, 0xffff0000, v95
	v_lshlrev_b32_e32 v8, 16, v97
	v_and_b32_e32 v9, 0xffff0000, v97
	v_pk_fma_f32 v[6:7], v[50:51], v[6:7], v[76:77] op_sel_hi:[0, 1, 1] neg_lo:[0, 0, 1] neg_hi:[0, 0, 1]
	v_pk_fma_f32 v[76:77], v[52:53], v[78:79], 0 op_sel_hi:[0, 1, 0]
	v_lshlrev_b32_e32 v22, 16, v101
	v_and_b32_e32 v23, 0xffff0000, v101
	v_pk_fma_f32 v[8:9], v[54:55], v[8:9], v[76:77] op_sel_hi:[0, 1, 1]
	v_pk_fma_f32 v[8:9], v[58:59], v[22:23], v[8:9] op_sel_hi:[0, 1, 1]
	v_lshlrev_b32_e32 v14, 16, v105
	v_and_b32_e32 v15, 0xffff0000, v105
	v_pk_fma_f32 v[8:9], v[66:67], v[14:15], v[8:9] op_sel_hi:[0, 1, 1]
	v_lshlrev_b32_e32 v14, 16, v109
	v_and_b32_e32 v15, 0xffff0000, v109
	v_pk_fma_f32 v[8:9], v[64:65], v[14:15], v[8:9] op_sel_hi:[0, 1, 1]
	v_lshlrev_b32_e32 v18, 16, v113
	v_and_b32_e32 v19, 0xffff0000, v113
	v_pk_fma_f32 v[8:9], v[62:63], v[18:19], v[8:9] op_sel_hi:[0, 1, 1]
	v_lshlrev_b32_e32 v18, 16, v117
	v_and_b32_e32 v19, 0xffff0000, v117
	v_pk_fma_f32 v[8:9], v[60:61], v[18:19], v[8:9] op_sel_hi:[0, 1, 1]
	v_lshlrev_b32_e32 v18, 16, v121
	v_and_b32_e32 v19, 0xffff0000, v121
	v_pk_fma_f32 v[8:9], v[56:57], v[18:19], v[8:9] op_sel_hi:[0, 1, 1]
	v_pk_fma_f32 v[8:9], v[50:51], v[8:9], v[14:15] op_sel_hi:[0, 1, 1] neg_lo:[0, 0, 1] neg_hi:[0, 0, 1]
	v_lshlrev_b32_e32 v10, 16, v98
	v_and_b32_e32 v11, 0xffff0000, v98
	v_cvt_pk_bf16_f32 v6, v6, v7
	v_cvt_pk_bf16_f32 v7, v8, v9
	v_pk_fma_f32 v[8:9], v[52:53], v[80:81], 0 op_sel_hi:[0, 1, 0]
	v_lshlrev_b32_e32 v86, 16, v102
	v_and_b32_e32 v87, 0xffff0000, v102
	v_pk_fma_f32 v[8:9], v[54:55], v[10:11], v[8:9] op_sel_hi:[0, 1, 1]
	v_pk_fma_f32 v[8:9], v[58:59], v[86:87], v[8:9] op_sel_hi:[0, 1, 1]
	v_lshlrev_b32_e32 v10, 16, v106
	v_and_b32_e32 v11, 0xffff0000, v106
	v_pk_fma_f32 v[8:9], v[66:67], v[10:11], v[8:9] op_sel_hi:[0, 1, 1]
	v_lshlrev_b32_e32 v10, 16, v110
	v_and_b32_e32 v11, 0xffff0000, v110
	v_pk_fma_f32 v[8:9], v[64:65], v[10:11], v[8:9] op_sel_hi:[0, 1, 1]
	v_lshlrev_b32_e32 v14, 16, v114
	v_and_b32_e32 v15, 0xffff0000, v114
	v_pk_fma_f32 v[8:9], v[62:63], v[14:15], v[8:9] op_sel_hi:[0, 1, 1]
	v_lshlrev_b32_e32 v14, 16, v118
	v_and_b32_e32 v15, 0xffff0000, v118
	v_pk_fma_f32 v[8:9], v[60:61], v[14:15], v[8:9] op_sel_hi:[0, 1, 1]
	v_lshlrev_b32_e32 v14, 16, v122
	v_and_b32_e32 v15, 0xffff0000, v122
	v_pk_fma_f32 v[8:9], v[56:57], v[14:15], v[8:9] op_sel_hi:[0, 1, 1]
	v_lshlrev_b32_e32 v12, 16, v99
	v_and_b32_e32 v13, 0xffff0000, v99
	v_pk_fma_f32 v[8:9], v[50:51], v[8:9], v[10:11] op_sel_hi:[0, 1, 1] neg_lo:[0, 0, 1] neg_hi:[0, 0, 1]
	v_pk_fma_f32 v[10:11], v[52:53], v[82:83], 0 op_sel_hi:[0, 1, 0]
	v_lshlrev_b32_e32 v24, 16, v103
	v_and_b32_e32 v25, 0xffff0000, v103
	v_pk_fma_f32 v[10:11], v[54:55], v[12:13], v[10:11] op_sel_hi:[0, 1, 1]
	v_pk_fma_f32 v[10:11], v[58:59], v[24:25], v[10:11] op_sel_hi:[0, 1, 1]
	v_lshlrev_b32_e32 v12, 16, v107
	v_and_b32_e32 v13, 0xffff0000, v107
	v_pk_fma_f32 v[10:11], v[66:67], v[12:13], v[10:11] op_sel_hi:[0, 1, 1]
	v_lshlrev_b32_e32 v12, 16, v111
	v_and_b32_e32 v13, 0xffff0000, v111
	v_pk_fma_f32 v[10:11], v[64:65], v[12:13], v[10:11] op_sel_hi:[0, 1, 1]
	v_lshlrev_b32_e32 v14, 16, v115
	v_and_b32_e32 v15, 0xffff0000, v115
	v_pk_fma_f32 v[10:11], v[62:63], v[14:15], v[10:11] op_sel_hi:[0, 1, 1]
	v_lshlrev_b32_e32 v14, 16, v119
	v_and_b32_e32 v15, 0xffff0000, v119
	v_pk_fma_f32 v[10:11], v[60:61], v[14:15], v[10:11] op_sel_hi:[0, 1, 1]
	v_lshlrev_b32_e32 v14, 16, v123
	v_and_b32_e32 v15, 0xffff0000, v123
	v_pk_fma_f32 v[10:11], v[56:57], v[14:15], v[10:11] op_sel_hi:[0, 1, 1]
	v_pk_fma_f32 v[10:11], v[50:51], v[10:11], v[12:13] op_sel_hi:[0, 1, 1] neg_lo:[0, 0, 1] neg_hi:[0, 0, 1]
	v_cvt_pk_bf16_f32 v8, v8, v9
	v_cvt_pk_bf16_f32 v9, v10, v11
	s_nop 0
	s_nop 0
	s_nop 0
	s_nop 0
	s_nop 0
	s_nop 0
	s_nop 0
	s_nop 0
	s_waitcnt vmcnt(15)
	v_lshlrev_b32_e32 v80, 16, v124
	v_and_b32_e32 v81, 0xffff0000, v124
	v_lshlrev_b32_e32 v82, 16, v125
	v_and_b32_e32 v83, 0xffff0000, v125
	s_waitcnt vmcnt(14)
	v_lshlrev_b32_e32 v10, 16, v128
	v_and_b32_e32 v11, 0xffff0000, v128
	v_pk_fma_f32 v[80:81], v[52:53], v[80:81], 0 op_sel_hi:[0, 1, 0]
	s_waitcnt vmcnt(13)
	v_lshlrev_b32_e32 v88, 16, v132
	v_and_b32_e32 v89, 0xffff0000, v132
	v_pk_fma_f32 v[10:11], v[54:55], v[10:11], v[80:81] op_sel_hi:[0, 1, 1]
	v_pk_fma_f32 v[10:11], v[58:59], v[88:89], v[10:11] op_sel_hi:[0, 1, 1]
	s_waitcnt vmcnt(12)
	v_lshlrev_b32_e32 v80, 16, v136
	v_and_b32_e32 v81, 0xffff0000, v136
	v_pk_fma_f32 v[10:11], v[66:67], v[80:81], v[10:11] op_sel_hi:[0, 1, 1]
	s_waitcnt vmcnt(11)
	v_lshlrev_b32_e32 v80, 16, v140
	v_and_b32_e32 v81, 0xffff0000, v140
	v_pk_fma_f32 v[10:11], v[64:65], v[80:81], v[10:11] op_sel_hi:[0, 1, 1]
	s_waitcnt vmcnt(10)
	v_lshlrev_b32_e32 v88, 16, v144
	v_and_b32_e32 v89, 0xffff0000, v144
	v_pk_fma_f32 v[10:11], v[62:63], v[88:89], v[10:11] op_sel_hi:[0, 1, 1]
	s_waitcnt vmcnt(9)
	v_lshlrev_b32_e32 v88, 16, v148
	v_and_b32_e32 v89, 0xffff0000, v148
	v_pk_fma_f32 v[10:11], v[60:61], v[88:89], v[10:11] op_sel_hi:[0, 1, 1]
	s_waitcnt vmcnt(8)
	v_lshlrev_b32_e32 v88, 16, v152
	v_and_b32_e32 v89, 0xffff0000, v152
	v_pk_fma_f32 v[10:11], v[56:57], v[88:89], v[10:11] op_sel_hi:[0, 1, 1]
	v_lshlrev_b32_e32 v84, 16, v126
	v_and_b32_e32 v85, 0xffff0000, v126
	v_lshlrev_b32_e32 v86, 16, v127
	v_and_b32_e32 v87, 0xffff0000, v127
	v_lshlrev_b32_e32 v12, 16, v129
	v_and_b32_e32 v13, 0xffff0000, v129
	v_pk_fma_f32 v[10:11], v[50:51], v[10:11], v[80:81] op_sel_hi:[0, 1, 1] neg_lo:[0, 0, 1] neg_hi:[0, 0, 1]
	v_pk_fma_f32 v[80:81], v[52:53], v[82:83], 0 op_sel_hi:[0, 1, 0]
	v_lshlrev_b32_e32 v18, 16, v133
	v_and_b32_e32 v19, 0xffff0000, v133
	v_pk_fma_f32 v[12:13], v[54:55], v[12:13], v[80:81] op_sel_hi:[0, 1, 1]
	v_pk_fma_f32 v[12:13], v[58:59], v[18:19], v[12:13] op_sel_hi:[0, 1, 1]
	v_lshlrev_b32_e32 v18, 16, v137
	v_and_b32_e32 v19, 0xffff0000, v137
	v_pk_fma_f32 v[12:13], v[66:67], v[18:19], v[12:13] op_sel_hi:[0, 1, 1]
	v_lshlrev_b32_e32 v18, 16, v141
	v_and_b32_e32 v19, 0xffff0000, v141
	v_pk_fma_f32 v[12:13], v[64:65], v[18:19], v[12:13] op_sel_hi:[0, 1, 1]
	v_lshlrev_b32_e32 v22, 16, v145
	v_and_b32_e32 v23, 0xffff0000, v145
	v_pk_fma_f32 v[12:13], v[62:63], v[22:23], v[12:13] op_sel_hi:[0, 1, 1]
	v_lshlrev_b32_e32 v22, 16, v149
	v_and_b32_e32 v23, 0xffff0000, v149
	v_pk_fma_f32 v[12:13], v[60:61], v[22:23], v[12:13] op_sel_hi:[0, 1, 1]
	v_lshlrev_b32_e32 v22, 16, v153
	v_and_b32_e32 v23, 0xffff0000, v153
	v_pk_fma_f32 v[12:13], v[56:57], v[22:23], v[12:13] op_sel_hi:[0, 1, 1]
	v_pk_fma_f32 v[12:13], v[50:51], v[12:13], v[18:19] op_sel_hi:[0, 1, 1] neg_lo:[0, 0, 1] neg_hi:[0, 0, 1]
	v_lshlrev_b32_e32 v14, 16, v130
	v_and_b32_e32 v15, 0xffff0000, v130
	v_cvt_pk_bf16_f32 v10, v10, v11
	v_cvt_pk_bf16_f32 v11, v12, v13
	v_pk_fma_f32 v[12:13], v[52:53], v[84:85], 0 op_sel_hi:[0, 1, 0]
	v_lshlrev_b32_e32 v90, 16, v134
	v_and_b32_e32 v91, 0xffff0000, v134
	v_pk_fma_f32 v[12:13], v[54:55], v[14:15], v[12:13] op_sel_hi:[0, 1, 1]
	v_pk_fma_f32 v[12:13], v[58:59], v[90:91], v[12:13] op_sel_hi:[0, 1, 1]
	v_lshlrev_b32_e32 v14, 16, v138
	v_and_b32_e32 v15, 0xffff0000, v138
	v_pk_fma_f32 v[12:13], v[66:67], v[14:15], v[12:13] op_sel_hi:[0, 1, 1]
	v_lshlrev_b32_e32 v14, 16, v142
	v_and_b32_e32 v15, 0xffff0000, v142
	v_pk_fma_f32 v[12:13], v[64:65], v[14:15], v[12:13] op_sel_hi:[0, 1, 1]
	v_lshlrev_b32_e32 v18, 16, v146
	v_and_b32_e32 v19, 0xffff0000, v146
	v_pk_fma_f32 v[12:13], v[62:63], v[18:19], v[12:13] op_sel_hi:[0, 1, 1]
	v_lshlrev_b32_e32 v18, 16, v150
	v_and_b32_e32 v19, 0xffff0000, v150
	v_pk_fma_f32 v[12:13], v[60:61], v[18:19], v[12:13] op_sel_hi:[0, 1, 1]
	v_lshlrev_b32_e32 v18, 16, v154
	v_and_b32_e32 v19, 0xffff0000, v154
	v_pk_fma_f32 v[12:13], v[56:57], v[18:19], v[12:13] op_sel_hi:[0, 1, 1]
	v_lshlrev_b32_e32 v16, 16, v131
	v_and_b32_e32 v17, 0xffff0000, v131
	v_pk_fma_f32 v[12:13], v[50:51], v[12:13], v[14:15] op_sel_hi:[0, 1, 1] neg_lo:[0, 0, 1] neg_hi:[0, 0, 1]
	v_pk_fma_f32 v[14:15], v[52:53], v[86:87], 0 op_sel_hi:[0, 1, 0]
	v_lshlrev_b32_e32 v20, 16, v135
	v_and_b32_e32 v21, 0xffff0000, v135
	v_pk_fma_f32 v[14:15], v[54:55], v[16:17], v[14:15] op_sel_hi:[0, 1, 1]
	v_pk_fma_f32 v[14:15], v[58:59], v[20:21], v[14:15] op_sel_hi:[0, 1, 1]
	v_lshlrev_b32_e32 v16, 16, v139
	v_and_b32_e32 v17, 0xffff0000, v139
	v_pk_fma_f32 v[14:15], v[66:67], v[16:17], v[14:15] op_sel_hi:[0, 1, 1]
	v_lshlrev_b32_e32 v16, 16, v143
	v_and_b32_e32 v17, 0xffff0000, v143
	v_pk_fma_f32 v[14:15], v[64:65], v[16:17], v[14:15] op_sel_hi:[0, 1, 1]
	v_lshlrev_b32_e32 v18, 16, v147
	v_and_b32_e32 v19, 0xffff0000, v147
	v_pk_fma_f32 v[14:15], v[62:63], v[18:19], v[14:15] op_sel_hi:[0, 1, 1]
	v_lshlrev_b32_e32 v18, 16, v151
	v_and_b32_e32 v19, 0xffff0000, v151
	v_pk_fma_f32 v[14:15], v[60:61], v[18:19], v[14:15] op_sel_hi:[0, 1, 1]
	v_lshlrev_b32_e32 v18, 16, v155
	v_and_b32_e32 v19, 0xffff0000, v155
	v_pk_fma_f32 v[14:15], v[56:57], v[18:19], v[14:15] op_sel_hi:[0, 1, 1]
	v_pk_fma_f32 v[14:15], v[50:51], v[14:15], v[16:17] op_sel_hi:[0, 1, 1] neg_lo:[0, 0, 1] neg_hi:[0, 0, 1]
	v_cvt_pk_bf16_f32 v12, v12, v13
	v_cvt_pk_bf16_f32 v13, v14, v15
	s_nop 0
	s_nop 0
	s_nop 0
	s_nop 0
	s_nop 0
	s_nop 0
	s_nop 0
	s_nop 0
	s_nop 0
	s_nop 0
	s_waitcnt vmcnt(7)
	v_lshlrev_b32_e32 v68, 16, v156
	v_and_b32_e32 v69, 0xffff0000, v156
	v_lshlrev_b32_e32 v70, 16, v157
	v_and_b32_e32 v71, 0xffff0000, v157
	s_waitcnt vmcnt(6)
	v_lshlrev_b32_e32 v14, 16, v160
	v_and_b32_e32 v15, 0xffff0000, v160
	v_pk_fma_f32 v[68:69], v[52:53], v[68:69], 0 op_sel_hi:[0, 1, 0]
	s_waitcnt vmcnt(5)
	v_lshlrev_b32_e32 v76, 16, v164
	v_and_b32_e32 v77, 0xffff0000, v164
	v_pk_fma_f32 v[14:15], v[54:55], v[14:15], v[68:69] op_sel_hi:[0, 1, 1]
	v_pk_fma_f32 v[14:15], v[58:59], v[76:77], v[14:15] op_sel_hi:[0, 1, 1]
	s_waitcnt vmcnt(4)
	v_lshlrev_b32_e32 v68, 16, v168
	v_and_b32_e32 v69, 0xffff0000, v168
	v_pk_fma_f32 v[14:15], v[66:67], v[68:69], v[14:15] op_sel_hi:[0, 1, 1]
	s_waitcnt vmcnt(3)
	v_lshlrev_b32_e32 v68, 16, v172
	v_and_b32_e32 v69, 0xffff0000, v172
	v_pk_fma_f32 v[14:15], v[64:65], v[68:69], v[14:15] op_sel_hi:[0, 1, 1]
	s_waitcnt vmcnt(2)
	v_lshlrev_b32_e32 v76, 16, v176
	v_and_b32_e32 v77, 0xffff0000, v176
	v_pk_fma_f32 v[14:15], v[62:63], v[76:77], v[14:15] op_sel_hi:[0, 1, 1]
	s_waitcnt vmcnt(1)
	v_lshlrev_b32_e32 v76, 16, v180
	v_and_b32_e32 v77, 0xffff0000, v180
	v_pk_fma_f32 v[14:15], v[60:61], v[76:77], v[14:15] op_sel_hi:[0, 1, 1]
	s_waitcnt vmcnt(0)
	v_lshlrev_b32_e32 v76, 16, v184
	v_and_b32_e32 v77, 0xffff0000, v184
	v_pk_fma_f32 v[14:15], v[56:57], v[76:77], v[14:15] op_sel_hi:[0, 1, 1]
	v_lshlrev_b32_e32 v72, 16, v158
	v_and_b32_e32 v73, 0xffff0000, v158
	v_lshlrev_b32_e32 v74, 16, v159
	v_and_b32_e32 v75, 0xffff0000, v159
	v_lshlrev_b32_e32 v16, 16, v161
	v_and_b32_e32 v17, 0xffff0000, v161
	v_pk_fma_f32 v[14:15], v[50:51], v[14:15], v[68:69] op_sel_hi:[0, 1, 1] neg_lo:[0, 0, 1] neg_hi:[0, 0, 1]
	v_pk_fma_f32 v[68:69], v[52:53], v[70:71], 0 op_sel_hi:[0, 1, 0]
	v_lshlrev_b32_e32 v30, 16, v165
	v_and_b32_e32 v31, 0xffff0000, v165
	v_pk_fma_f32 v[16:17], v[54:55], v[16:17], v[68:69] op_sel_hi:[0, 1, 1]
	v_pk_fma_f32 v[16:17], v[58:59], v[30:31], v[16:17] op_sel_hi:[0, 1, 1]
	v_lshlrev_b32_e32 v22, 16, v169
	v_and_b32_e32 v23, 0xffff0000, v169
	v_pk_fma_f32 v[16:17], v[66:67], v[22:23], v[16:17] op_sel_hi:[0, 1, 1]
	v_lshlrev_b32_e32 v22, 16, v173
	v_and_b32_e32 v23, 0xffff0000, v173
	v_pk_fma_f32 v[16:17], v[64:65], v[22:23], v[16:17] op_sel_hi:[0, 1, 1]
	v_lshlrev_b32_e32 v26, 16, v177
	v_and_b32_e32 v27, 0xffff0000, v177
	v_pk_fma_f32 v[16:17], v[62:63], v[26:27], v[16:17] op_sel_hi:[0, 1, 1]
	v_lshlrev_b32_e32 v26, 16, v181
	v_and_b32_e32 v27, 0xffff0000, v181
	v_pk_fma_f32 v[16:17], v[60:61], v[26:27], v[16:17] op_sel_hi:[0, 1, 1]
	v_lshlrev_b32_e32 v26, 16, v185
	v_and_b32_e32 v27, 0xffff0000, v185
	v_pk_fma_f32 v[16:17], v[56:57], v[26:27], v[16:17] op_sel_hi:[0, 1, 1]
	v_pk_fma_f32 v[16:17], v[50:51], v[16:17], v[22:23] op_sel_hi:[0, 1, 1] neg_lo:[0, 0, 1] neg_hi:[0, 0, 1]
	v_lshlrev_b32_e32 v18, 16, v162
	v_and_b32_e32 v19, 0xffff0000, v162
	v_cvt_pk_bf16_f32 v14, v14, v15
	v_cvt_pk_bf16_f32 v15, v16, v17
	v_pk_fma_f32 v[16:17], v[52:53], v[72:73], 0 op_sel_hi:[0, 1, 0]
	v_lshlrev_b32_e32 v78, 16, v166
	v_and_b32_e32 v79, 0xffff0000, v166
	v_pk_fma_f32 v[16:17], v[54:55], v[18:19], v[16:17] op_sel_hi:[0, 1, 1]
	v_pk_fma_f32 v[16:17], v[58:59], v[78:79], v[16:17] op_sel_hi:[0, 1, 1]
	v_lshlrev_b32_e32 v18, 16, v170
	v_and_b32_e32 v19, 0xffff0000, v170
	v_pk_fma_f32 v[16:17], v[66:67], v[18:19], v[16:17] op_sel_hi:[0, 1, 1]
	v_lshlrev_b32_e32 v18, 16, v174
	v_and_b32_e32 v19, 0xffff0000, v174
	v_pk_fma_f32 v[16:17], v[64:65], v[18:19], v[16:17] op_sel_hi:[0, 1, 1]
	v_lshlrev_b32_e32 v22, 16, v178
	v_and_b32_e32 v23, 0xffff0000, v178
	v_pk_fma_f32 v[16:17], v[62:63], v[22:23], v[16:17] op_sel_hi:[0, 1, 1]
	v_lshlrev_b32_e32 v22, 16, v182
	v_and_b32_e32 v23, 0xffff0000, v182
	v_pk_fma_f32 v[16:17], v[60:61], v[22:23], v[16:17] op_sel_hi:[0, 1, 1]
	v_lshlrev_b32_e32 v22, 16, v186
	v_and_b32_e32 v23, 0xffff0000, v186
	v_pk_fma_f32 v[16:17], v[56:57], v[22:23], v[16:17] op_sel_hi:[0, 1, 1]
	v_lshlrev_b32_e32 v20, 16, v163
	v_and_b32_e32 v21, 0xffff0000, v163
	v_pk_fma_f32 v[16:17], v[50:51], v[16:17], v[18:19] op_sel_hi:[0, 1, 1] neg_lo:[0, 0, 1] neg_hi:[0, 0, 1]
	v_pk_fma_f32 v[18:19], v[52:53], v[74:75], 0 op_sel_hi:[0, 1, 0]
	v_lshlrev_b32_e32 v32, 16, v167
	v_and_b32_e32 v33, 0xffff0000, v167
	v_pk_fma_f32 v[18:19], v[54:55], v[20:21], v[18:19] op_sel_hi:[0, 1, 1]
	v_pk_fma_f32 v[18:19], v[58:59], v[32:33], v[18:19] op_sel_hi:[0, 1, 1]
	v_lshlrev_b32_e32 v20, 16, v171
	v_and_b32_e32 v21, 0xffff0000, v171
	v_pk_fma_f32 v[18:19], v[66:67], v[20:21], v[18:19] op_sel_hi:[0, 1, 1]
	v_lshlrev_b32_e32 v20, 16, v175
	v_and_b32_e32 v21, 0xffff0000, v175
	v_pk_fma_f32 v[18:19], v[64:65], v[20:21], v[18:19] op_sel_hi:[0, 1, 1]
	v_lshlrev_b32_e32 v22, 16, v179
	v_and_b32_e32 v23, 0xffff0000, v179
	v_pk_fma_f32 v[18:19], v[62:63], v[22:23], v[18:19] op_sel_hi:[0, 1, 1]
	v_lshlrev_b32_e32 v22, 16, v183
	v_and_b32_e32 v23, 0xffff0000, v183
	v_pk_fma_f32 v[18:19], v[60:61], v[22:23], v[18:19] op_sel_hi:[0, 1, 1]
	v_lshlrev_b32_e32 v22, 16, v187
	v_and_b32_e32 v23, 0xffff0000, v187
	v_pk_fma_f32 v[18:19], v[56:57], v[22:23], v[18:19] op_sel_hi:[0, 1, 1]
	v_pk_fma_f32 v[18:19], v[50:51], v[18:19], v[20:21] op_sel_hi:[0, 1, 1] neg_lo:[0, 0, 1] neg_hi:[0, 0, 1]
	v_lshlrev_b64 v[20:21], 11, v[48:49]
	v_cvt_pk_bf16_f32 v16, v16, v17
	v_cvt_pk_bf16_f32 v17, v18, v19
	v_lshl_add_u64 v[18:19], s[34:35], 0, v[46:47]
	v_lshl_add_u64 v[30:31], s[84:85], 0, v[20:21]
	v_lshlrev_b32_e32 v20, 8, v53
	v_mov_b32_e32 v21, v1
	v_lshl_add_u64 v[28:29], v[18:19], 0, v[20:21]
	v_add_co_u32_e32 v56, vcc, 0x1000, v28
	s_nop 1
	v_addc_co_u32_e32 v57, vcc, 0, v29, vcc
	v_add_co_u32_e32 v58, vcc, 0x3000, v28
	s_nop 1
	v_addc_co_u32_e32 v59, vcc, 0, v29, vcc
	v_add_co_u32_e32 v60, vcc, 0x5000, v28
	s_nop 1
	v_addc_co_u32_e32 v61, vcc, 0, v29, vcc
	v_add_co_u32_e32 v62, vcc, 0x7000, v28
	s_nop 1
	v_addc_co_u32_e32 v63, vcc, 0, v29, vcc
	v_and_b32_e32 v56, 15, v209
	v_bfe_u32 v57, v209, 4, 2
	v_mul_u32_u24_e32 v56, 0x110, v56
	v_lshl_add_u32 v56, v57, 4, v56
	v_add_u32_e32 v56, 0x11000, v56
	v_add_u32_e32 v57, 0x22000, v46
	ds_read_b128 v[100:103], v57 offset:1024
	ds_read_b128 v[120:123], v57 offset:1088
	ds_read_b128 v[140:143], v57 offset:1152
	ds_read_b128 v[160:163], v57 offset:1216
	ds_read_b128 v[180:183], v57 offset:1280
	ds_read_b128 v[200:203], v57 offset:1344
	ds_read_b128 v[234:237], v57 offset:1408
	ds_read_b128 v[84:87], v56 offset:0
	ds_read_b128 v[88:91], v56 offset:64
	ds_read_b128 v[92:95], v56 offset:128
	ds_read_b128 v[96:99], v56 offset:192
	ds_read_b128 v[104:107], v56 offset:4352
	ds_read_b128 v[108:111], v56 offset:4416
	ds_read_b128 v[112:115], v56 offset:4480
	ds_read_b128 v[116:119], v56 offset:4544
	s_nop 0
	s_nop 0
	s_waitcnt lgkmcnt(4)
	v_mfma_f32_16x16x32_bf16 v[18:21], v[84:87], v[2:5], 0
	v_lshl_add_u64 v[26:27], v[30:31], 0, s[0:1]
	s_movk_i32 s0, 0x1000
	v_mfma_f32_16x16x32_bf16 v[18:21], v[88:91], v[6:9], v[18:21]
	s_nop 0
	v_mfma_f32_16x16x32_bf16 v[18:21], v[92:95], v[10:13], v[18:21]
	s_nop 0
	v_mfma_f32_16x16x32_bf16 v[18:21], v[96:99], v[14:17], v[18:21]
	ds_read_b128 v[124:127], v56 offset:8704
	ds_read_b128 v[128:131], v56 offset:8768
	ds_read_b128 v[132:135], v56 offset:8832
	ds_read_b128 v[136:139], v56 offset:8896
	s_nop 0
	s_nop 0
	s_nop 5
	v_pk_mul_f32 v[20:21], v[20:21], v[102:103]
	v_add_co_u32_e32 v24, vcc, s0, v28
	v_pk_mul_f32 v[18:19], v[18:19], v[100:101]
	s_nop 0
	v_addc_co_u32_e32 v25, vcc, 0, v29, vcc
	s_movk_i32 s0, 0x2000
	v_cvt_pk_bf16_f32 v22, v18, v19
	v_cvt_pk_bf16_f32 v23, v20, v21
	v_lshl_add_u64 v[18:19], v[30:31], 0, v[0:1]
	v_add_co_u32_e32 v34, vcc, s0, v28
	global_store_dwordx2 v[18:19], v[22:23], off offset:1536
	s_nop 0
	v_addc_co_u32_e32 v35, vcc, 0, v29, vcc
	s_nop 0
	s_nop 0
	s_waitcnt lgkmcnt(4)
	v_mfma_f32_16x16x32_bf16 v[20:23], v[104:107], v[2:5], 0
	s_movk_i32 s0, 0x3000
	v_mov_b32_e32 v0, 0x170
	v_lshl_or_b32 v0, v51, 2, v0
	v_mfma_f32_16x16x32_bf16 v[20:23], v[108:111], v[6:9], v[20:23]
	s_nop 0
	v_mfma_f32_16x16x32_bf16 v[20:23], v[112:115], v[10:13], v[20:23]
	s_nop 0
	v_add_co_u32_e32 v24, vcc, s0, v28
	v_mfma_f32_16x16x32_bf16 v[20:23], v[116:119], v[14:17], v[20:23]
	ds_read_b128 v[144:147], v56 offset:13056
	ds_read_b128 v[148:151], v56 offset:13120
	ds_read_b128 v[152:155], v56 offset:13184
	ds_read_b128 v[156:159], v56 offset:13248
	s_nop 0
	v_addc_co_u32_e32 v25, vcc, 0, v29, vcc
	s_movk_i32 s0, 0x4000
	s_nop 0
	s_nop 3
	v_pk_mul_f32 v[22:23], v[22:23], v[122:123]
	v_pk_mul_f32 v[20:21], v[20:21], v[120:121]
	s_nop 0
	v_cvt_pk_bf16_f32 v20, v20, v21
	v_cvt_pk_bf16_f32 v21, v22, v23
	global_store_dwordx2 v[18:19], v[20:21], off offset:1568
	s_nop 0
	s_nop 0
	s_nop 0
	s_waitcnt lgkmcnt(4)
	v_mfma_f32_16x16x32_bf16 v[20:23], v[124:127], v[2:5], 0
	v_mfma_f32_16x16x32_bf16 v[20:23], v[128:131], v[6:9], v[20:23]
	s_nop 0
	v_mfma_f32_16x16x32_bf16 v[20:23], v[132:135], v[10:13], v[20:23]
	s_nop 0
	v_add_co_u32_e32 v34, vcc, s0, v28
	v_mfma_f32_16x16x32_bf16 v[20:23], v[136:139], v[14:17], v[20:23]
	ds_read_b128 v[164:167], v56 offset:17408
	ds_read_b128 v[168:171], v56 offset:17472
	ds_read_b128 v[172:175], v56 offset:17536
	ds_read_b128 v[176:179], v56 offset:17600
	s_nop 0
	v_addc_co_u32_e32 v35, vcc, 0, v29, vcc
	s_movk_i32 s0, 0x5000
	s_nop 0
	s_nop 3
	v_pk_mul_f32 v[22:23], v[22:23], v[142:143]
	v_pk_mul_f32 v[20:21], v[20:21], v[140:141]
	s_nop 0
	v_cvt_pk_bf16_f32 v20, v20, v21
	v_cvt_pk_bf16_f32 v21, v22, v23
	global_store_dwordx2 v[18:19], v[20:21], off offset:1600
	s_nop 0
	s_nop 0
	s_nop 0
	s_waitcnt lgkmcnt(4)
	v_mfma_f32_16x16x32_bf16 v[20:23], v[144:147], v[2:5], 0
	v_mfma_f32_16x16x32_bf16 v[20:23], v[148:151], v[6:9], v[20:23]
	s_nop 0
	v_mfma_f32_16x16x32_bf16 v[20:23], v[152:155], v[10:13], v[20:23]
	s_nop 0
	v_add_co_u32_e32 v24, vcc, s0, v28
	v_mfma_f32_16x16x32_bf16 v[20:23], v[156:159], v[14:17], v[20:23]
	ds_read_b128 v[184:187], v56 offset:21760
	ds_read_b128 v[188:191], v56 offset:21824
	ds_read_b128 v[192:195], v56 offset:21888
	ds_read_b128 v[196:199], v56 offset:21952
	s_nop 0
	v_addc_co_u32_e32 v25, vcc, 0, v29, vcc
	s_movk_i32 s0, 0x6000
	s_nop 0
	s_nop 3
	v_pk_mul_f32 v[22:23], v[22:23], v[162:163]
	v_pk_mul_f32 v[20:21], v[20:21], v[160:161]
	s_nop 0
	v_cvt_pk_bf16_f32 v20, v20, v21
	v_cvt_pk_bf16_f32 v21, v22, v23
	global_store_dwordx2 v[18:19], v[20:21], off offset:1632
	s_nop 0
	s_nop 0
	s_nop 0
	s_waitcnt lgkmcnt(4)
	v_mfma_f32_16x16x32_bf16 v[20:23], v[164:167], v[2:5], 0
	v_mfma_f32_16x16x32_bf16 v[20:23], v[168:171], v[6:9], v[20:23]
	s_nop 0
	v_mfma_f32_16x16x32_bf16 v[20:23], v[172:175], v[10:13], v[20:23]
	s_nop 0
	v_add_co_u32_e32 v34, vcc, s0, v28
	v_mfma_f32_16x16x32_bf16 v[20:23], v[176:179], v[14:17], v[20:23]
	ds_read_b128 v[204:207], v56 offset:26112
	ds_read_b128 v[222:225], v56 offset:26176
	ds_read_b128 v[226:229], v56 offset:26240
	ds_read_b128 v[230:233], v56 offset:26304
	s_nop 0
	v_addc_co_u32_e32 v35, vcc, 0, v29, vcc
	s_nop 0
	s_nop 4
	v_pk_mul_f32 v[22:23], v[22:23], v[182:183]
	v_pk_mul_f32 v[20:21], v[20:21], v[180:181]
	s_nop 0
	v_cvt_pk_bf16_f32 v20, v20, v21
	v_cvt_pk_bf16_f32 v21, v22, v23
	global_store_dwordx2 v[18:19], v[20:21], off offset:1664
	s_nop 0
	s_nop 0
	s_nop 0
	s_waitcnt lgkmcnt(4)
	v_mfma_f32_16x16x32_bf16 v[20:23], v[184:187], v[2:5], 0
	v_mfma_f32_16x16x32_bf16 v[20:23], v[188:191], v[6:9], v[20:23]
	s_nop 0
	v_mfma_f32_16x16x32_bf16 v[20:23], v[192:195], v[10:13], v[20:23]
	s_nop 0
	v_mfma_f32_16x16x32_bf16 v[20:23], v[196:199], v[14:17], v[20:23]
	ds_read_b128 v[238:241], v56 offset:30464
	ds_read_b128 v[242:245], v56 offset:30528
	ds_read_b128 v[246:249], v56 offset:30592
	ds_read_b128 v[52:55], v56 offset:30656
	s_nop 0
	s_nop 0
	s_nop 5
	v_pk_mul_f32 v[22:23], v[22:23], v[202:203]
	v_pk_mul_f32 v[20:21], v[20:21], v[200:201]
	s_nop 0
	v_cvt_pk_bf16_f32 v20, v20, v21
	v_cvt_pk_bf16_f32 v21, v22, v23
	global_store_dwordx2 v[18:19], v[20:21], off offset:1696
	s_nop 0
	s_nop 0
	s_nop 0
	s_waitcnt lgkmcnt(4)
	v_mfma_f32_16x16x32_bf16 v[20:23], v[204:207], v[2:5], 0
	v_mfma_f32_16x16x32_bf16 v[20:23], v[222:225], v[6:9], v[20:23]
	s_nop 0
	v_mfma_f32_16x16x32_bf16 v[20:23], v[226:229], v[10:13], v[20:23]
	s_nop 0
	v_mfma_f32_16x16x32_bf16 v[20:23], v[230:233], v[14:17], v[20:23]
	s_nop 0
	s_nop 0
	s_nop 5
	v_pk_mul_f32 v[22:23], v[22:23], v[236:237]
	v_pk_mul_f32 v[20:21], v[20:21], v[234:235]
	s_nop 0
	v_cvt_pk_bf16_f32 v20, v20, v21
	v_cvt_pk_bf16_f32 v21, v22, v23
	v_add_co_u32_e32 v22, vcc, 0x7000, v28
	global_store_dwordx2 v[18:19], v[20:21], off offset:1728
	s_nop 0
	v_addc_co_u32_e32 v23, vcc, 0, v29, vcc
	s_nop 0
	s_waitcnt lgkmcnt(0)
	v_mfma_f32_16x16x32_bf16 v[2:5], v[238:241], v[2:5], 0
	s_nop 0
	v_mfma_f32_16x16x32_bf16 v[2:5], v[242:245], v[6:9], v[2:5]
	s_nop 0
	v_mfma_f32_16x16x32_bf16 v[2:5], v[246:249], v[10:13], v[2:5]
	s_nop 0
	v_mfma_f32_16x16x32_bf16 v[2:5], v[52:55], v[14:17], v[2:5]

.LBB0_588:
	s_and_b64 vcc, exec, s[0:1]
	s_cbranch_vccz .LBB0_590
	v_mov_b32_e32 v0, v209
	v_mov_b32_e32 v29, v1
	v_readfirstlane_b32 s0, v0
	s_ashr_i32 s0, s0, 2
	v_and_b32_e32 v21, 15, v0
	v_bfi_b32 v23, -16, s0, v0
	v_bfe_u32 v36, v0, 4, 2
	v_subrev_u32_e32 v0, s56, v23
	v_add_u32_e32 v18, s59, v0
	s_mov_b32 s0, 0x38e38e39
	v_mul_hi_i32 v0, v18, s0
	v_lshrrev_b32_e32 v2, 31, v0
	v_ashrrev_i32_e32 v0, 13, v0
	v_add_u32_e32 v0, v0, v2
	v_mul_i32_i24_e32 v0, 0x9000, v0
	v_sub_u32_e32 v0, v18, v0
	s_mov_b32 s0, 0x8000
	v_cmp_gt_i32_e32 vcc, s0, v0
	v_lshlrev_b32_e32 v28, 4, v36
	v_ashrrev_i32_e32 v19, 31, v18
	v_cndmask_b32_e32 v2, v220, v221, vcc
	v_and_b32_e32 v37, v2, v0
	v_cndmask_b32_e32 v31, v217, v210, vcc
	v_add_u32_e32 v2, -2, v37
	v_add_u32_e32 v3, 2, v37
	v_max_i32_e32 v0, 0, v2
	v_min_u32_e32 v3, v3, v31
	v_sub_u32_e32 v0, v3, v0
	v_cvt_f32_i32_e32 v0, v0
	v_add_u32_e32 v26, 1, v37
	v_lshlrev_b64 v[10:11], 10, v[18:19]
	v_lshlrev_b64 v[18:19], 11, v[18:19]
	v_div_scale_f32 v3, s[0:1], v0, v0, 1.0
	v_rcp_f32_e32 v4, v3
	v_readlane_b32 s0, v253, 62
	v_readlane_b32 s1, v253, 63
	v_fma_f32 v5, -v3, v4, 1.0
	v_fmac_f32_e32 v4, v5, v4
	v_div_scale_f32 v5, vcc, 1.0, v0, 1.0
	v_mul_f32_e32 v6, v5, v4
	v_fma_f32 v7, -v3, v6, v5
	v_fmac_f32_e32 v6, v7, v4
	v_fma_f32 v3, -v3, v6, v5
	v_div_fmas_f32 v3, v3, v4, v6
	v_cmp_lt_u32_e32 vcc, v2, v31
	v_add_u32_e32 v6, -1, v37
	v_lshl_add_u64 v[24:25], s[0:1], 0, v[28:29]
	v_cndmask_b32_e64 v22, 0, 1.0, vcc
	v_cndmask_b32_e32 v2, v37, v2, vcc
	v_cmp_lt_u32_e32 vcc, v6, v31
	v_add_u32_e32 v2, v23, v2
	v_subrev_u32_e32 v2, s56, v2
	v_cndmask_b32_e32 v6, v37, v6, vcc
	v_add_u32_e32 v6, v23, v6
	v_cmp_lt_u32_e64 s[0:1], v26, v31
	v_sub_u32_e32 v2, v2, v37
	v_subrev_u32_e32 v6, s56, v6
	v_cndmask_b32_e64 v26, v37, v26, s[0:1]
	v_add_u32_e32 v2, s59, v2
	v_sub_u32_e32 v6, v6, v37
	v_add_u32_e32 v23, v23, v26
	v_div_fixup_f32 v20, v3, v0, 1.0
	v_ashrrev_i32_e32 v3, 31, v2
	v_add_u32_e32 v6, s59, v6
	v_subrev_u32_e32 v23, s56, v23
	v_lshlrev_b64 v[2:3], 10, v[2:3]
	v_ashrrev_i32_e32 v7, 31, v6
	v_sub_u32_e32 v23, v23, v37
	v_lshl_add_u64 v[14:15], v[24:25], 0, v[2:3]
	v_lshlrev_b64 v[6:7], 10, v[6:7]
	v_add_u32_e32 v26, s59, v23
	global_load_dwordx4 v[2:5], v[14:15], off offset:256
	v_lshl_add_u64 v[34:35], v[24:25], 0, v[6:7]
	v_ashrrev_i32_e32 v27, 31, v26
	global_load_dwordx4 v[6:9], v[34:35], off offset:256
	v_lshl_add_u64 v[16:17], v[24:25], 0, v[10:11]
	v_lshlrev_b64 v[26:27], 10, v[26:27]
	global_load_dwordx4 v[10:13], v[16:17], off offset:256
	v_lshl_add_u64 v[32:33], v[24:25], 0, v[26:27]
	global_load_dwordx4 v[38:41], v[32:33], off offset:256
	global_load_dwordx4 v[92:95], v[14:15], off offset:320
	global_load_dwordx4 v[96:99], v[34:35], off offset:320
	global_load_dwordx4 v[100:103], v[16:17], off offset:320
	global_load_dwordx4 v[104:107], v[32:33], off offset:320
	global_load_dwordx4 v[108:111], v[14:15], off offset:384
	global_load_dwordx4 v[112:115], v[34:35], off offset:384
	global_load_dwordx4 v[116:119], v[16:17], off offset:384
	global_load_dwordx4 v[120:123], v[32:33], off offset:384
	global_load_dwordx4 v[124:127], v[14:15], off offset:448
	global_load_dwordx4 v[128:131], v[34:35], off offset:448
	global_load_dwordx4 v[132:135], v[16:17], off offset:448
	global_load_dwordx4 v[136:139], v[32:33], off offset:448
	v_cndmask_b32_e64 v30, 0, 1.0, vcc
	v_cmp_lt_u32_e32 vcc, v37, v31
	v_cndmask_b32_e64 v24, 0, 1.0, s[0:1]
	s_mov_b64 s[0:1], 0x400
	v_cndmask_b32_e64 v26, 0, 1.0, vcc
	v_lshlrev_b32_e32 v0, 3, v36
	s_waitcnt vmcnt(15)
	v_lshlrev_b32_e32 v42, 16, v2
	v_and_b32_e32 v43, 0xffff0000, v2
	v_pk_fma_f32 v[42:43], v[22:23], v[42:43], 0 op_sel_hi:[0, 1, 0]
	s_waitcnt vmcnt(14)
	v_lshlrev_b32_e32 v44, 16, v6
	v_and_b32_e32 v45, 0xffff0000, v6
	v_pk_fma_f32 v[42:43], v[30:31], v[44:45], v[42:43] op_sel_hi:[0, 1, 1]
	s_waitcnt vmcnt(13)
	v_lshlrev_b32_e32 v44, 16, v10
	v_and_b32_e32 v45, 0xffff0000, v10
	v_pk_fma_f32 v[42:43], v[26:27], v[44:45], v[42:43] op_sel_hi:[0, 1, 1]
	s_waitcnt vmcnt(12)
	v_lshlrev_b32_e32 v46, 16, v38
	v_and_b32_e32 v47, 0xffff0000, v38
	v_pk_fma_f32 v[42:43], v[24:25], v[46:47], v[42:43] op_sel_hi:[0, 1, 1]
	v_pk_fma_f32 v[42:43], v[20:21], v[42:43], v[44:45] op_sel_hi:[0, 1, 1] neg_lo:[0, 0, 1] neg_hi:[0, 0, 1]
	v_cvt_pk_bf16_f32 v2, v42, v43
	v_lshlrev_b32_e32 v42, 16, v3
	v_and_b32_e32 v43, 0xffff0000, v3
	v_pk_fma_f32 v[42:43], v[22:23], v[42:43], 0 op_sel_hi:[0, 1, 0]
	v_lshlrev_b32_e32 v6, 16, v7
	v_and_b32_e32 v7, 0xffff0000, v7
	v_pk_fma_f32 v[6:7], v[30:31], v[6:7], v[42:43] op_sel_hi:[0, 1, 1]
	v_lshlrev_b32_e32 v10, 16, v11
	v_and_b32_e32 v11, 0xffff0000, v11
	v_pk_fma_f32 v[6:7], v[26:27], v[10:11], v[6:7] op_sel_hi:[0, 1, 1]
	v_lshlrev_b32_e32 v38, 16, v39
	v_and_b32_e32 v39, 0xffff0000, v39
	v_pk_fma_f32 v[6:7], v[24:25], v[38:39], v[6:7] op_sel_hi:[0, 1, 1]
	v_pk_fma_f32 v[6:7], v[20:21], v[6:7], v[10:11] op_sel_hi:[0, 1, 1] neg_lo:[0, 0, 1] neg_hi:[0, 0, 1]
	v_cvt_pk_bf16_f32 v3, v6, v7
	v_lshlrev_b32_e32 v6, 16, v4
	v_and_b32_e32 v7, 0xffff0000, v4
	v_pk_fma_f32 v[6:7], v[22:23], v[6:7], 0 op_sel_hi:[0, 1, 0]
	v_lshlrev_b32_e32 v10, 16, v8
	v_and_b32_e32 v11, 0xffff0000, v8
	v_pk_fma_f32 v[6:7], v[30:31], v[10:11], v[6:7] op_sel_hi:[0, 1, 1]
	v_lshlrev_b32_e32 v10, 16, v12
	v_and_b32_e32 v11, 0xffff0000, v12
	v_pk_fma_f32 v[6:7], v[26:27], v[10:11], v[6:7] op_sel_hi:[0, 1, 1]
	v_lshlrev_b32_e32 v38, 16, v40
	v_and_b32_e32 v39, 0xffff0000, v40
	v_pk_fma_f32 v[6:7], v[24:25], v[38:39], v[6:7] op_sel_hi:[0, 1, 1]
	v_pk_fma_f32 v[6:7], v[20:21], v[6:7], v[10:11] op_sel_hi:[0, 1, 1] neg_lo:[0, 0, 1] neg_hi:[0, 0, 1]
	v_cvt_pk_bf16_f32 v4, v6, v7
	v_lshlrev_b32_e32 v6, 16, v5
	v_and_b32_e32 v7, 0xffff0000, v5
	v_pk_fma_f32 v[6:7], v[22:23], v[6:7], 0 op_sel_hi:[0, 1, 0]
	v_lshlrev_b32_e32 v8, 16, v9
	v_and_b32_e32 v9, 0xffff0000, v9
	v_pk_fma_f32 v[6:7], v[30:31], v[8:9], v[6:7] op_sel_hi:[0, 1, 1]
	v_lshlrev_b32_e32 v8, 16, v13
	v_and_b32_e32 v9, 0xffff0000, v13
	v_pk_fma_f32 v[6:7], v[26:27], v[8:9], v[6:7] op_sel_hi:[0, 1, 1]
	v_lshlrev_b32_e32 v10, 16, v41
	v_and_b32_e32 v11, 0xffff0000, v41
	v_pk_fma_f32 v[6:7], v[24:25], v[10:11], v[6:7] op_sel_hi:[0, 1, 1]
	v_pk_fma_f32 v[6:7], v[20:21], v[6:7], v[8:9] op_sel_hi:[0, 1, 1] neg_lo:[0, 0, 1] neg_hi:[0, 0, 1]
	v_cvt_pk_bf16_f32 v5, v6, v7
	s_nop 0
	s_nop 0
	s_nop 0
	s_nop 0
	s_waitcnt vmcnt(11)
	v_lshlrev_b32_e32 v46, 16, v92
	v_and_b32_e32 v47, 0xffff0000, v92
	v_pk_fma_f32 v[46:47], v[22:23], v[46:47], 0 op_sel_hi:[0, 1, 0]
	s_waitcnt vmcnt(10)
	v_lshlrev_b32_e32 v48, 16, v96
	v_and_b32_e32 v49, 0xffff0000, v96
	v_pk_fma_f32 v[46:47], v[30:31], v[48:49], v[46:47] op_sel_hi:[0, 1, 1]
	s_waitcnt vmcnt(9)
	v_lshlrev_b32_e32 v48, 16, v100
	v_and_b32_e32 v49, 0xffff0000, v100
	v_pk_fma_f32 v[46:47], v[26:27], v[48:49], v[46:47] op_sel_hi:[0, 1, 1]
	s_waitcnt vmcnt(8)
	v_lshlrev_b32_e32 v50, 16, v104
	v_and_b32_e32 v51, 0xffff0000, v104
	v_pk_fma_f32 v[46:47], v[24:25], v[50:51], v[46:47] op_sel_hi:[0, 1, 1]
	v_pk_fma_f32 v[46:47], v[20:21], v[46:47], v[48:49] op_sel_hi:[0, 1, 1] neg_lo:[0, 0, 1] neg_hi:[0, 0, 1]
	v_lshlrev_b32_e32 v10, 16, v93
	v_and_b32_e32 v11, 0xffff0000, v93
	v_cvt_pk_bf16_f32 v6, v46, v47
	v_pk_fma_f32 v[10:11], v[22:23], v[10:11], 0 op_sel_hi:[0, 1, 0]
	v_lshlrev_b32_e32 v46, 16, v97
	v_and_b32_e32 v47, 0xffff0000, v97
	v_pk_fma_f32 v[10:11], v[30:31], v[46:47], v[10:11] op_sel_hi:[0, 1, 1]
	v_lshlrev_b32_e32 v38, 16, v101
	v_and_b32_e32 v39, 0xffff0000, v101
	v_pk_fma_f32 v[10:11], v[26:27], v[38:39], v[10:11] op_sel_hi:[0, 1, 1]
	v_lshlrev_b32_e32 v42, 16, v105
	v_and_b32_e32 v43, 0xffff0000, v105
	v_pk_fma_f32 v[10:11], v[24:25], v[42:43], v[10:11] op_sel_hi:[0, 1, 1]
	v_pk_fma_f32 v[10:11], v[20:21], v[10:11], v[38:39] op_sel_hi:[0, 1, 1] neg_lo:[0, 0, 1] neg_hi:[0, 0, 1]
	v_cvt_pk_bf16_f32 v7, v10, v11
	v_lshlrev_b32_e32 v10, 16, v94
	v_and_b32_e32 v11, 0xffff0000, v94
	v_pk_fma_f32 v[10:11], v[22:23], v[10:11], 0 op_sel_hi:[0, 1, 0]
	v_lshlrev_b32_e32 v38, 16, v98
	v_and_b32_e32 v39, 0xffff0000, v98
	v_pk_fma_f32 v[10:11], v[30:31], v[38:39], v[10:11] op_sel_hi:[0, 1, 1]
	v_lshlrev_b32_e32 v38, 16, v102
	v_and_b32_e32 v39, 0xffff0000, v102
	v_pk_fma_f32 v[10:11], v[26:27], v[38:39], v[10:11] op_sel_hi:[0, 1, 1]
	v_lshlrev_b32_e32 v42, 16, v106
	v_and_b32_e32 v43, 0xffff0000, v106
	v_pk_fma_f32 v[10:11], v[24:25], v[42:43], v[10:11] op_sel_hi:[0, 1, 1]
	v_pk_fma_f32 v[10:11], v[20:21], v[10:11], v[38:39] op_sel_hi:[0, 1, 1] neg_lo:[0, 0, 1] neg_hi:[0, 0, 1]
	v_cvt_pk_bf16_f32 v8, v10, v11
	v_lshlrev_b32_e32 v10, 16, v95
	v_and_b32_e32 v11, 0xffff0000, v95
	v_pk_fma_f32 v[10:11], v[22:23], v[10:11], 0 op_sel_hi:[0, 1, 0]
	v_lshlrev_b32_e32 v12, 16, v99
	v_and_b32_e32 v13, 0xffff0000, v99
	v_pk_fma_f32 v[10:11], v[30:31], v[12:13], v[10:11] op_sel_hi:[0, 1, 1]
	v_lshlrev_b32_e32 v12, 16, v103
	v_and_b32_e32 v13, 0xffff0000, v103
	v_pk_fma_f32 v[10:11], v[26:27], v[12:13], v[10:11] op_sel_hi:[0, 1, 1]
	v_lshlrev_b32_e32 v38, 16, v107
	v_and_b32_e32 v39, 0xffff0000, v107
	v_pk_fma_f32 v[10:11], v[24:25], v[38:39], v[10:11] op_sel_hi:[0, 1, 1]
	v_pk_fma_f32 v[10:11], v[20:21], v[10:11], v[12:13] op_sel_hi:[0, 1, 1] neg_lo:[0, 0, 1] neg_hi:[0, 0, 1]
	v_cvt_pk_bf16_f32 v9, v10, v11
	s_nop 0
	s_nop 0
	s_nop 0
	s_nop 0
	s_waitcnt vmcnt(7)
	v_lshlrev_b32_e32 v50, 16, v108
	v_and_b32_e32 v51, 0xffff0000, v108
	v_pk_fma_f32 v[50:51], v[22:23], v[50:51], 0 op_sel_hi:[0, 1, 0]
	s_waitcnt vmcnt(6)
	v_lshlrev_b32_e32 v52, 16, v112
	v_and_b32_e32 v53, 0xffff0000, v112
	v_pk_fma_f32 v[50:51], v[30:31], v[52:53], v[50:51] op_sel_hi:[0, 1, 1]
	s_waitcnt vmcnt(5)
	v_lshlrev_b32_e32 v52, 16, v116
	v_and_b32_e32 v53, 0xffff0000, v116
	v_pk_fma_f32 v[50:51], v[26:27], v[52:53], v[50:51] op_sel_hi:[0, 1, 1]
	s_waitcnt vmcnt(4)
	v_lshlrev_b32_e32 v54, 16, v120
	v_and_b32_e32 v55, 0xffff0000, v120
	v_pk_fma_f32 v[50:51], v[24:25], v[54:55], v[50:51] op_sel_hi:[0, 1, 1]
	v_pk_fma_f32 v[50:51], v[20:21], v[50:51], v[52:53] op_sel_hi:[0, 1, 1] neg_lo:[0, 0, 1] neg_hi:[0, 0, 1]
	v_cvt_pk_bf16_f32 v10, v50, v51
	v_lshlrev_b32_e32 v50, 16, v109
	v_and_b32_e32 v51, 0xffff0000, v109
	v_pk_fma_f32 v[50:51], v[22:23], v[50:51], 0 op_sel_hi:[0, 1, 0]
	v_lshlrev_b32_e32 v38, 16, v113
	v_and_b32_e32 v39, 0xffff0000, v113
	v_pk_fma_f32 v[38:39], v[30:31], v[38:39], v[50:51] op_sel_hi:[0, 1, 1]
	v_lshlrev_b32_e32 v42, 16, v117
	v_and_b32_e32 v43, 0xffff0000, v117
	v_pk_fma_f32 v[38:39], v[26:27], v[42:43], v[38:39] op_sel_hi:[0, 1, 1]
	v_lshlrev_b32_e32 v46, 16, v121
	v_and_b32_e32 v47, 0xffff0000, v121
	v_pk_fma_f32 v[38:39], v[24:25], v[46:47], v[38:39] op_sel_hi:[0, 1, 1]
	v_pk_fma_f32 v[38:39], v[20:21], v[38:39], v[42:43] op_sel_hi:[0, 1, 1] neg_lo:[0, 0, 1] neg_hi:[0, 0, 1]
	v_cvt_pk_bf16_f32 v11, v38, v39
	v_lshlrev_b32_e32 v38, 16, v110
	v_and_b32_e32 v39, 0xffff0000, v110
	v_pk_fma_f32 v[38:39], v[22:23], v[38:39], 0 op_sel_hi:[0, 1, 0]
	v_lshlrev_b32_e32 v42, 16, v114
	v_and_b32_e32 v43, 0xffff0000, v114
	v_pk_fma_f32 v[38:39], v[30:31], v[42:43], v[38:39] op_sel_hi:[0, 1, 1]
	v_lshlrev_b32_e32 v42, 16, v118
	v_and_b32_e32 v43, 0xffff0000, v118
	v_pk_fma_f32 v[38:39], v[26:27], v[42:43], v[38:39] op_sel_hi:[0, 1, 1]
	v_lshlrev_b32_e32 v46, 16, v122
	v_and_b32_e32 v47, 0xffff0000, v122
	v_pk_fma_f32 v[38:39], v[24:25], v[46:47], v[38:39] op_sel_hi:[0, 1, 1]
	v_pk_fma_f32 v[38:39], v[20:21], v[38:39], v[42:43] op_sel_hi:[0, 1, 1] neg_lo:[0, 0, 1] neg_hi:[0, 0, 1]
	v_cvt_pk_bf16_f32 v12, v38, v39
	v_lshlrev_b32_e32 v38, 16, v111
	v_and_b32_e32 v39, 0xffff0000, v111
	v_pk_fma_f32 v[38:39], v[22:23], v[38:39], 0 op_sel_hi:[0, 1, 0]
	v_lshlrev_b32_e32 v40, 16, v115
	v_and_b32_e32 v41, 0xffff0000, v115
	v_pk_fma_f32 v[38:39], v[30:31], v[40:41], v[38:39] op_sel_hi:[0, 1, 1]
	v_lshlrev_b32_e32 v40, 16, v119
	v_and_b32_e32 v41, 0xffff0000, v119
	v_pk_fma_f32 v[38:39], v[26:27], v[40:41], v[38:39] op_sel_hi:[0, 1, 1]
	v_lshlrev_b32_e32 v42, 16, v123
	v_and_b32_e32 v43, 0xffff0000, v123
	v_pk_fma_f32 v[38:39], v[24:25], v[42:43], v[38:39] op_sel_hi:[0, 1, 1]
	v_pk_fma_f32 v[38:39], v[20:21], v[38:39], v[40:41] op_sel_hi:[0, 1, 1] neg_lo:[0, 0, 1] neg_hi:[0, 0, 1]
	v_cvt_pk_bf16_f32 v13, v38, v39
	s_nop 0
	s_nop 0
	s_nop 0
	s_nop 0
	s_nop 0
	s_nop 0
	s_waitcnt vmcnt(3)
	v_lshlrev_b32_e32 v46, 16, v124
	v_and_b32_e32 v47, 0xffff0000, v124
	v_lshlrev_b32_e32 v38, 16, v125
	v_and_b32_e32 v39, 0xffff0000, v125
	s_waitcnt vmcnt(2)
	v_lshlrev_b32_e32 v48, 16, v128
	v_and_b32_e32 v49, 0xffff0000, v128
	v_pk_fma_f32 v[38:39], v[22:23], v[38:39], 0 op_sel_hi:[0, 1, 0]
	v_lshlrev_b32_e32 v42, 16, v129
	v_and_b32_e32 v43, 0xffff0000, v129
	v_pk_fma_f32 v[38:39], v[30:31], v[42:43], v[38:39] op_sel_hi:[0, 1, 1]
	s_waitcnt vmcnt(1)
	v_lshlrev_b32_e32 v42, 16, v133
	v_and_b32_e32 v43, 0xffff0000, v133
	s_waitcnt vmcnt(0)
	v_lshlrev_b32_e32 v50, 16, v136
	v_and_b32_e32 v51, 0xffff0000, v136
	v_pk_fma_f32 v[38:39], v[26:27], v[42:43], v[38:39] op_sel_hi:[0, 1, 1]
	v_lshlrev_b32_e32 v32, 16, v137
	v_and_b32_e32 v33, 0xffff0000, v137
	v_pk_fma_f32 v[32:33], v[24:25], v[32:33], v[38:39] op_sel_hi:[0, 1, 1]
	v_pk_fma_f32 v[32:33], v[20:21], v[32:33], v[42:43] op_sel_hi:[0, 1, 1] neg_lo:[0, 0, 1] neg_hi:[0, 0, 1]
	v_cvt_pk_bf16_f32 v15, v32, v33
	v_lshlrev_b32_e32 v32, 16, v126
	v_and_b32_e32 v33, 0xffff0000, v126
	v_pk_fma_f32 v[32:33], v[22:23], v[32:33], 0 op_sel_hi:[0, 1, 0]
	v_lshlrev_b32_e32 v38, 16, v130
	v_and_b32_e32 v39, 0xffff0000, v130
	v_pk_fma_f32 v[32:33], v[30:31], v[38:39], v[32:33] op_sel_hi:[0, 1, 1]
	v_lshlrev_b32_e32 v38, 16, v134
	v_and_b32_e32 v39, 0xffff0000, v134
	v_pk_fma_f32 v[32:33], v[26:27], v[38:39], v[32:33] op_sel_hi:[0, 1, 1]
	v_lshlrev_b32_e32 v42, 16, v138
	v_and_b32_e32 v43, 0xffff0000, v138
	v_pk_fma_f32 v[32:33], v[24:25], v[42:43], v[32:33] op_sel_hi:[0, 1, 1]
	v_pk_fma_f32 v[32:33], v[20:21], v[32:33], v[38:39] op_sel_hi:[0, 1, 1] neg_lo:[0, 0, 1] neg_hi:[0, 0, 1]
	v_cvt_pk_bf16_f32 v16, v32, v33
	v_lshlrev_b32_e32 v32, 16, v127
	v_and_b32_e32 v33, 0xffff0000, v127
	v_pk_fma_f32 v[46:47], v[22:23], v[46:47], 0 op_sel_hi:[0, 1, 0]
	v_pk_fma_f32 v[22:23], v[22:23], v[32:33], 0 op_sel_hi:[0, 1, 0]
	v_lshlrev_b32_e32 v32, 16, v131
	v_and_b32_e32 v33, 0xffff0000, v131
	v_pk_fma_f32 v[46:47], v[30:31], v[48:49], v[46:47] op_sel_hi:[0, 1, 1]
	v_lshlrev_b32_e32 v48, 16, v132
	v_and_b32_e32 v49, 0xffff0000, v132
	v_pk_fma_f32 v[22:23], v[30:31], v[32:33], v[22:23] op_sel_hi:[0, 1, 1]
	v_lshlrev_b32_e32 v30, 16, v135
	v_and_b32_e32 v31, 0xffff0000, v135
	v_pk_fma_f32 v[46:47], v[26:27], v[48:49], v[46:47] op_sel_hi:[0, 1, 1]
	v_pk_fma_f32 v[22:23], v[26:27], v[30:31], v[22:23] op_sel_hi:[0, 1, 1]
	v_lshlrev_b32_e32 v26, 16, v139
	v_and_b32_e32 v27, 0xffff0000, v139
	v_pk_fma_f32 v[22:23], v[24:25], v[26:27], v[22:23] op_sel_hi:[0, 1, 1]
	v_pk_fma_f32 v[22:23], v[20:21], v[22:23], v[30:31] op_sel_hi:[0, 1, 1] neg_lo:[0, 0, 1] neg_hi:[0, 0, 1]
	v_cvt_pk_bf16_f32 v17, v22, v23
	v_lshl_add_u64 v[22:23], s[36:37], 0, v[28:29]
	v_lshl_add_u64 v[32:33], s[84:85], 0, v[18:19]
	v_lshlrev_b32_e32 v18, 8, v21
	v_mov_b32_e32 v19, v1
	v_pk_fma_f32 v[46:47], v[24:25], v[50:51], v[46:47] op_sel_hi:[0, 1, 1]
	v_lshl_add_u64 v[30:31], v[22:23], 0, v[18:19]
	v_pk_fma_f32 v[46:47], v[20:21], v[46:47], v[48:49] op_sel_hi:[0, 1, 1] neg_lo:[0, 0, 1] neg_hi:[0, 0, 1]
	v_add_co_u32_e32 v56, vcc, 0x1000, v30
	s_nop 1
	v_addc_co_u32_e32 v57, vcc, 0, v31, vcc
	v_add_co_u32_e32 v58, vcc, 0x3000, v30
	s_nop 1
	v_addc_co_u32_e32 v59, vcc, 0, v31, vcc
	v_add_co_u32_e32 v60, vcc, 0x5000, v30
	s_nop 1
	v_addc_co_u32_e32 v61, vcc, 0, v31, vcc
	v_add_co_u32_e32 v62, vcc, 0x7000, v30
	s_nop 1
	v_addc_co_u32_e32 v63, vcc, 0, v31, vcc
	v_and_b32_e32 v56, 15, v209
	v_bfe_u32 v57, v209, 4, 2
	v_mul_u32_u24_e32 v56, 0x110, v56
	v_lshl_add_u32 v56, v57, 4, v56
	v_add_u32_e32 v56, 0x8800, v56
	v_add_u32_e32 v57, 0x22000, v28
	ds_read_b128 v[100:103], v57 offset:512
	ds_read_b128 v[120:123], v57 offset:576
	ds_read_b128 v[140:143], v57 offset:640
	ds_read_b128 v[160:163], v57 offset:704
	ds_read_b128 v[180:183], v57 offset:768
	ds_read_b128 v[200:203], v57 offset:832
	ds_read_b128 v[234:237], v57 offset:896
	ds_read_b128 v[84:87], v56 offset:0
	ds_read_b128 v[88:91], v56 offset:64
	ds_read_b128 v[92:95], v56 offset:128
	ds_read_b128 v[96:99], v56 offset:192
	ds_read_b128 v[104:107], v56 offset:4352
	ds_read_b128 v[108:111], v56 offset:4416
	ds_read_b128 v[112:115], v56 offset:4480
	ds_read_b128 v[116:119], v56 offset:4544
	s_nop 0
	s_nop 0
	s_waitcnt lgkmcnt(4)
	v_mfma_f32_16x16x32_bf16 v[18:21], v[84:87], v[2:5], 0
	v_cvt_pk_bf16_f32 v14, v46, v47
	v_lshl_add_u64 v[26:27], v[32:33], 0, s[0:1]
	s_movk_i32 s0, 0x1000
	v_mfma_f32_16x16x32_bf16 v[18:21], v[88:91], v[6:9], v[18:21]
	s_nop 0
	v_mfma_f32_16x16x32_bf16 v[18:21], v[92:95], v[10:13], v[18:21]
	s_nop 0
	v_mfma_f32_16x16x32_bf16 v[18:21], v[96:99], v[14:17], v[18:21]
	ds_read_b128 v[124:127], v56 offset:8704
	ds_read_b128 v[128:131], v56 offset:8768
	ds_read_b128 v[132:135], v56 offset:8832
	ds_read_b128 v[136:139], v56 offset:8896
	s_nop 0
	s_nop 0
	s_nop 5
	v_pk_mul_f32 v[20:21], v[20:21], v[102:103]
	v_add_co_u32_e32 v24, vcc, s0, v30
	v_pk_mul_f32 v[18:19], v[18:19], v[100:101]
	s_nop 0
	v_addc_co_u32_e32 v25, vcc, 0, v31, vcc
	s_movk_i32 s0, 0x2000
	v_cvt_pk_bf16_f32 v22, v18, v19
	v_cvt_pk_bf16_f32 v23, v20, v21
	v_lshl_add_u64 v[18:19], v[32:33], 0, v[0:1]
	v_add_co_u32_e32 v38, vcc, s0, v30
	global_store_dwordx2 v[18:19], v[22:23], off offset:1280
	s_nop 0
	v_addc_co_u32_e32 v39, vcc, 0, v31, vcc
	s_nop 0
	s_nop 0
	s_waitcnt lgkmcnt(4)
	v_mfma_f32_16x16x32_bf16 v[20:23], v[104:107], v[2:5], 0
	s_movk_i32 s0, 0x3000
	v_mov_b32_e32 v0, 0xf0
	v_lshl_or_b32 v0, v36, 2, v0
	v_mfma_f32_16x16x32_bf16 v[20:23], v[108:111], v[6:9], v[20:23]
	s_nop 0
	v_mfma_f32_16x16x32_bf16 v[20:23], v[112:115], v[10:13], v[20:23]
	s_nop 0
	v_add_co_u32_e32 v24, vcc, s0, v30
	v_mfma_f32_16x16x32_bf16 v[20:23], v[116:119], v[14:17], v[20:23]
	ds_read_b128 v[144:147], v56 offset:13056
	ds_read_b128 v[148:151], v56 offset:13120
	ds_read_b128 v[152:155], v56 offset:13184
	ds_read_b128 v[156:159], v56 offset:13248
	s_nop 0
	v_addc_co_u32_e32 v25, vcc, 0, v31, vcc
	s_movk_i32 s0, 0x4000
	s_nop 0
	s_nop 3
	v_pk_mul_f32 v[22:23], v[22:23], v[122:123]
	v_pk_mul_f32 v[20:21], v[20:21], v[120:121]
	s_nop 0
	v_cvt_pk_bf16_f32 v20, v20, v21
	v_cvt_pk_bf16_f32 v21, v22, v23
	global_store_dwordx2 v[18:19], v[20:21], off offset:1312
	s_nop 0
	s_nop 0
	s_nop 0
	s_waitcnt lgkmcnt(4)
	v_mfma_f32_16x16x32_bf16 v[20:23], v[124:127], v[2:5], 0
	v_mfma_f32_16x16x32_bf16 v[20:23], v[128:131], v[6:9], v[20:23]
	s_nop 0
	v_mfma_f32_16x16x32_bf16 v[20:23], v[132:135], v[10:13], v[20:23]
	s_nop 0
	v_add_co_u32_e32 v38, vcc, s0, v30
	v_mfma_f32_16x16x32_bf16 v[20:23], v[136:139], v[14:17], v[20:23]
	ds_read_b128 v[164:167], v56 offset:17408
	ds_read_b128 v[168:171], v56 offset:17472
	ds_read_b128 v[172:175], v56 offset:17536
	ds_read_b128 v[176:179], v56 offset:17600
	s_nop 0
	v_addc_co_u32_e32 v39, vcc, 0, v31, vcc
	s_movk_i32 s0, 0x5000
	s_nop 0
	s_nop 3
	v_pk_mul_f32 v[22:23], v[22:23], v[142:143]
	v_pk_mul_f32 v[20:21], v[20:21], v[140:141]
	s_nop 0
	v_cvt_pk_bf16_f32 v20, v20, v21
	v_cvt_pk_bf16_f32 v21, v22, v23
	global_store_dwordx2 v[18:19], v[20:21], off offset:1344
	s_nop 0
	s_nop 0
	s_nop 0
	s_waitcnt lgkmcnt(4)
	v_mfma_f32_16x16x32_bf16 v[20:23], v[144:147], v[2:5], 0
	v_mfma_f32_16x16x32_bf16 v[20:23], v[148:151], v[6:9], v[20:23]
	s_nop 0
	v_mfma_f32_16x16x32_bf16 v[20:23], v[152:155], v[10:13], v[20:23]
	s_nop 0
	v_add_co_u32_e32 v24, vcc, s0, v30
	v_mfma_f32_16x16x32_bf16 v[20:23], v[156:159], v[14:17], v[20:23]
	ds_read_b128 v[184:187], v56 offset:21760
	ds_read_b128 v[188:191], v56 offset:21824
	ds_read_b128 v[192:195], v56 offset:21888
	ds_read_b128 v[196:199], v56 offset:21952
	s_nop 0
	v_addc_co_u32_e32 v25, vcc, 0, v31, vcc
	s_movk_i32 s0, 0x6000
	s_nop 0
	s_nop 3
	v_pk_mul_f32 v[22:23], v[22:23], v[162:163]
	v_pk_mul_f32 v[20:21], v[20:21], v[160:161]
	s_nop 0
	v_cvt_pk_bf16_f32 v20, v20, v21
	v_cvt_pk_bf16_f32 v21, v22, v23
	global_store_dwordx2 v[18:19], v[20:21], off offset:1376
	s_nop 0
	s_nop 0
	s_nop 0
	s_waitcnt lgkmcnt(4)
	v_mfma_f32_16x16x32_bf16 v[20:23], v[164:167], v[2:5], 0
	v_mfma_f32_16x16x32_bf16 v[20:23], v[168:171], v[6:9], v[20:23]
	s_nop 0
	v_mfma_f32_16x16x32_bf16 v[20:23], v[172:175], v[10:13], v[20:23]
	s_nop 0
	v_add_co_u32_e32 v38, vcc, s0, v30
	v_mfma_f32_16x16x32_bf16 v[20:23], v[176:179], v[14:17], v[20:23]
	ds_read_b128 v[204:207], v56 offset:26112
	ds_read_b128 v[222:225], v56 offset:26176
	ds_read_b128 v[226:229], v56 offset:26240
	ds_read_b128 v[230:233], v56 offset:26304
	s_nop 0
	v_addc_co_u32_e32 v39, vcc, 0, v31, vcc
	s_nop 0
	s_nop 4
	v_pk_mul_f32 v[22:23], v[22:23], v[182:183]
	v_pk_mul_f32 v[20:21], v[20:21], v[180:181]
	s_nop 0
	v_cvt_pk_bf16_f32 v20, v20, v21
	v_cvt_pk_bf16_f32 v21, v22, v23
	global_store_dwordx2 v[18:19], v[20:21], off offset:1408
	s_nop 0
	s_nop 0
	s_nop 0
	s_waitcnt lgkmcnt(4)
	v_mfma_f32_16x16x32_bf16 v[20:23], v[184:187], v[2:5], 0
	v_mfma_f32_16x16x32_bf16 v[20:23], v[188:191], v[6:9], v[20:23]
	s_nop 0
	v_mfma_f32_16x16x32_bf16 v[20:23], v[192:195], v[10:13], v[20:23]
	s_nop 0
	v_mfma_f32_16x16x32_bf16 v[20:23], v[196:199], v[14:17], v[20:23]
	ds_read_b128 v[238:241], v56 offset:30464
	ds_read_b128 v[242:245], v56 offset:30528
	ds_read_b128 v[246:249], v56 offset:30592
	ds_read_b128 v[52:55], v56 offset:30656
	s_nop 0
	s_nop 0
	s_nop 5
	v_pk_mul_f32 v[22:23], v[22:23], v[202:203]
	v_pk_mul_f32 v[20:21], v[20:21], v[200:201]
	s_nop 0
	v_cvt_pk_bf16_f32 v20, v20, v21
	v_cvt_pk_bf16_f32 v21, v22, v23
	global_store_dwordx2 v[18:19], v[20:21], off offset:1440
	s_nop 0
	s_nop 0
	s_nop 0
	s_waitcnt lgkmcnt(4)
	v_mfma_f32_16x16x32_bf16 v[20:23], v[204:207], v[2:5], 0
	v_mfma_f32_16x16x32_bf16 v[20:23], v[222:225], v[6:9], v[20:23]
	s_nop 0
	v_mfma_f32_16x16x32_bf16 v[20:23], v[226:229], v[10:13], v[20:23]
	s_nop 0
	v_mfma_f32_16x16x32_bf16 v[20:23], v[230:233], v[14:17], v[20:23]
	s_nop 0
	s_nop 0
	s_nop 5
	v_pk_mul_f32 v[22:23], v[22:23], v[236:237]
	v_pk_mul_f32 v[20:21], v[20:21], v[234:235]
	s_nop 0
	v_cvt_pk_bf16_f32 v20, v20, v21
	v_cvt_pk_bf16_f32 v21, v22, v23
	v_add_co_u32_e32 v22, vcc, 0x7000, v30
	global_store_dwordx2 v[18:19], v[20:21], off offset:1472
	s_nop 0
	v_addc_co_u32_e32 v23, vcc, 0, v31, vcc
	s_nop 0
	s_waitcnt lgkmcnt(0)
	v_mfma_f32_16x16x32_bf16 v[2:5], v[238:241], v[2:5], 0
	s_nop 0
	v_mfma_f32_16x16x32_bf16 v[2:5], v[242:245], v[6:9], v[2:5]
	s_nop 0
	v_mfma_f32_16x16x32_bf16 v[2:5], v[246:249], v[10:13], v[2:5]
	s_nop 0
	v_mfma_f32_16x16x32_bf16 v[2:5], v[52:55], v[14:17], v[2:5]

.LBB0_592:
	v_mov_b32_e32 v0, v209
	s_mul_i32 s6, s56, s16
	v_readfirstlane_b32 s0, v0
	s_ashr_i32 s0, s0, 2
	v_and_b32_e32 v85, 15, v0
	v_bfi_b32 v64, -16, s0, v0
	v_bfe_u32 v83, v0, 4, 2
	v_subrev_u32_e32 v0, s6, v64
	v_add_u32_e32 v80, s59, v0
	s_mov_b32 s0, 0x38e38e39
	v_mul_hi_i32 v0, v80, s0
	v_lshrrev_b32_e32 v2, 31, v0
	v_ashrrev_i32_e32 v0, 13, v0
	v_add_u32_e32 v0, v0, v2
	v_mul_i32_i24_e32 v0, 0x9000, v0
	v_sub_u32_e32 v0, v80, v0
	s_mov_b32 s0, 0x8000
	v_cmp_gt_i32_e32 vcc, s0, v0
	v_lshlrev_b32_e32 v78, 4, v83
	v_mov_b32_e32 v79, v1
	v_cndmask_b32_e32 v2, v220, v221, vcc
	v_and_b32_e32 v88, v2, v0
	v_cndmask_b32_e32 v87, v217, v210, vcc
	v_add_u32_e32 v4, -8, v88
	v_add_u32_e32 v2, 8, v88
	v_max_i32_e32 v0, 0, v4
	v_min_u32_e32 v2, v2, v87
	v_sub_u32_e32 v0, v2, v0
	v_cvt_f32_i32_e32 v0, v0
	v_add_u32_e32 v10, 1, v88
	v_add_u32_e32 v50, 4, v88
	v_cmp_lt_u32_e64 s[14:15], v50, v87
	v_div_scale_f32 v2, s[0:1], v0, v0, 1.0
	v_rcp_f32_e32 v3, v2
	v_readlane_b32 s0, v253, 62
	v_readlane_b32 s1, v253, 63
	v_add_u32_e32 v54, 5, v88
	v_fma_f32 v5, -v2, v3, 1.0
	v_fmac_f32_e32 v3, v5, v3
	v_div_scale_f32 v5, vcc, 1.0, v0, 1.0
	v_mul_f32_e32 v6, v5, v3
	v_fma_f32 v7, -v2, v6, v5
	v_fmac_f32_e32 v6, v7, v3
	v_fma_f32 v2, -v2, v6, v5
	v_div_fmas_f32 v2, v2, v3, v6
	v_cmp_lt_u32_e32 vcc, v4, v87
	v_lshl_add_u64 v[62:63], s[0:1], 0, v[78:79]
	v_cmp_lt_u32_e64 s[0:1], v10, v87
	v_cndmask_b32_e32 v4, v88, v4, vcc
	v_add_u32_e32 v4, v64, v4
	v_subrev_u32_e32 v4, s6, v4
	v_sub_u32_e32 v4, v4, v88
	v_add_u32_e32 v4, s59, v4
	v_ashrrev_i32_e32 v5, 31, v4
	v_lshlrev_b64 v[4:5], 10, v[4:5]
	v_lshl_add_u64 v[126:127], v[62:63], 0, v[4:5]
	v_add_u32_e32 v4, -7, v88
	v_cmp_lt_u32_e64 s[8:9], v4, v87
	v_cndmask_b32_e64 v10, v88, v10, s[0:1]
	v_add_u32_e32 v10, v64, v10
	v_cndmask_b32_e64 v4, v88, v4, s[8:9]
	v_add_u32_e32 v4, v64, v4
	v_subrev_u32_e32 v4, s6, v4
	v_sub_u32_e32 v4, v4, v88
	v_add_u32_e32 v4, s59, v4
	v_ashrrev_i32_e32 v5, 31, v4
	v_lshlrev_b64 v[4:5], 10, v[4:5]
	v_lshl_add_u64 v[128:129], v[62:63], 0, v[4:5]
	v_add_u32_e32 v4, -6, v88
	v_cmp_lt_u32_e64 s[12:13], v4, v87
	v_subrev_u32_e32 v10, s6, v10
	v_sub_u32_e32 v10, v10, v88
	v_cndmask_b32_e64 v4, v88, v4, s[12:13]
	v_add_u32_e32 v4, v64, v4
	v_subrev_u32_e32 v4, s6, v4
	v_sub_u32_e32 v4, v4, v88
	v_add_u32_e32 v4, s59, v4
	v_ashrrev_i32_e32 v5, 31, v4
	v_lshlrev_b64 v[4:5], 10, v[4:5]
	v_lshl_add_u64 v[130:131], v[62:63], 0, v[4:5]
	v_add_u32_e32 v4, -5, v88
	v_cmp_lt_u32_e64 s[16:17], v4, v87
	v_add_u32_e32 v10, s59, v10
	v_ashrrev_i32_e32 v11, 31, v10
	v_cndmask_b32_e64 v4, v88, v4, s[16:17]
	v_add_u32_e32 v4, v64, v4
	v_subrev_u32_e32 v4, s6, v4
	v_sub_u32_e32 v4, v4, v88
	v_add_u32_e32 v4, s59, v4
	v_ashrrev_i32_e32 v5, 31, v4
	v_lshlrev_b64 v[4:5], 10, v[4:5]
	v_lshl_add_u64 v[132:133], v[62:63], 0, v[4:5]
	v_add_u32_e32 v4, -4, v88
	v_cmp_lt_u32_e64 s[20:21], v4, v87
	v_lshlrev_b64 v[10:11], 10, v[10:11]
	v_lshl_add_u64 v[76:77], v[62:63], 0, v[10:11]
	v_cndmask_b32_e64 v4, v88, v4, s[20:21]
	v_add_u32_e32 v4, v64, v4
	v_subrev_u32_e32 v4, s6, v4
	v_sub_u32_e32 v4, v4, v88
	v_add_u32_e32 v4, s59, v4
	v_ashrrev_i32_e32 v5, 31, v4
	v_lshlrev_b64 v[4:5], 10, v[4:5]
	v_lshl_add_u64 v[134:135], v[62:63], 0, v[4:5]
	v_add_u32_e32 v4, -3, v88
	v_cmp_lt_u32_e64 s[24:25], v4, v87
	v_add_u32_e32 v10, 2, v88
	global_load_dwordx4 v[6:9], v[126:127], off offset:768
	v_cndmask_b32_e64 v4, v88, v4, s[24:25]
	v_add_u32_e32 v4, v64, v4
	v_subrev_u32_e32 v4, s6, v4
	v_sub_u32_e32 v4, v4, v88
	v_add_u32_e32 v4, s59, v4
	v_ashrrev_i32_e32 v5, 31, v4
	v_lshlrev_b64 v[4:5], 10, v[4:5]
	v_lshl_add_u64 v[136:137], v[62:63], 0, v[4:5]
	v_add_u32_e32 v4, -2, v88
	v_cmp_lt_u32_e64 s[28:29], v4, v87
	v_cmp_lt_u32_e64 s[4:5], v10, v87
	global_load_dwordx4 v[14:17], v[128:129], off offset:768
	global_load_dwordx4 v[18:21], v[130:131], off offset:768
	v_cndmask_b32_e64 v4, v88, v4, s[28:29]
	v_add_u32_e32 v4, v64, v4
	v_subrev_u32_e32 v4, s6, v4
	v_sub_u32_e32 v4, v4, v88
	v_add_u32_e32 v4, s59, v4
	v_cndmask_b32_e64 v10, v88, v10, s[4:5]
	v_ashrrev_i32_e32 v5, 31, v4
	v_add_u32_e32 v10, v64, v10
	global_load_dwordx4 v[22:25], v[132:133], off offset:768
	global_load_dwordx4 v[26:29], v[134:135], off offset:768
	v_lshlrev_b64 v[4:5], 10, v[4:5]
	v_subrev_u32_e32 v10, s6, v10
	v_lshl_add_u64 v[138:139], v[62:63], 0, v[4:5]
	v_add_u32_e32 v4, -1, v88
	v_sub_u32_e32 v10, v10, v88
	v_cndmask_b32_e64 v84, 0, 1.0, vcc
	global_load_dwordx4 v[30:33], v[136:137], off offset:768
	global_load_dwordx4 v[34:37], v[138:139], off offset:768
	v_cmp_lt_u32_e32 vcc, v4, v87
	v_add_u32_e32 v10, s59, v10
	v_ashrrev_i32_e32 v11, 31, v10
	v_cndmask_b32_e32 v4, v88, v4, vcc
	v_add_u32_e32 v4, v64, v4
	v_lshlrev_b64 v[10:11], 10, v[10:11]
	v_subrev_u32_e32 v4, s6, v4
	v_lshl_add_u64 v[74:75], v[62:63], 0, v[10:11]
	v_add_u32_e32 v10, 3, v88
	v_sub_u32_e32 v4, v4, v88
	v_cmp_lt_u32_e64 s[10:11], v10, v87
	v_add_u32_e32 v4, s59, v4
	v_ashrrev_i32_e32 v5, 31, v4
	v_cndmask_b32_e64 v10, v88, v10, s[10:11]
	v_add_u32_e32 v10, v64, v10
	v_cndmask_b32_e64 v50, v88, v50, s[14:15]
	v_cmp_lt_u32_e64 s[18:19], v54, v87
	v_add_u32_e32 v58, 6, v88
	v_ashrrev_i32_e32 v81, 31, v80
	v_lshlrev_b64 v[4:5], 10, v[4:5]
	v_subrev_u32_e32 v10, s6, v10
	v_add_u32_e32 v50, v64, v50
	v_cndmask_b32_e64 v54, v88, v54, s[18:19]
	v_cmp_lt_u32_e64 s[22:23], v58, v87
	v_add_u32_e32 v65, 7, v88
	v_div_fixup_f32 v82, v2, v0, 1.0
	v_lshlrev_b64 v[2:3], 10, v[80:81]
	v_lshl_add_u64 v[122:123], v[62:63], 0, v[4:5]
	v_sub_u32_e32 v10, v10, v88
	v_subrev_u32_e32 v50, s6, v50
	v_add_u32_e32 v54, v64, v54
	v_cndmask_b32_e64 v58, v88, v58, s[22:23]
	v_cmp_lt_u32_e64 s[26:27], v65, v87
	global_load_dwordx4 v[38:41], v[122:123], off offset:768
	v_lshl_add_u64 v[124:125], v[62:63], 0, v[2:3]
	v_add_u32_e32 v10, s59, v10
	v_sub_u32_e32 v50, v50, v88
	v_subrev_u32_e32 v54, s6, v54
	v_add_u32_e32 v58, v64, v58
	v_cndmask_b32_e64 v65, v88, v65, s[26:27]
	global_load_dwordx4 v[2:5], v[124:125], off offset:768
	v_ashrrev_i32_e32 v11, 31, v10
	v_add_u32_e32 v50, s59, v50
	v_sub_u32_e32 v54, v54, v88
	v_subrev_u32_e32 v58, s6, v58
	v_add_u32_e32 v64, v64, v65
	global_load_dwordx4 v[42:45], v[76:77], off offset:768
	global_load_dwordx4 v[46:49], v[74:75], off offset:768
	v_lshlrev_b64 v[10:11], 10, v[10:11]
	v_ashrrev_i32_e32 v51, 31, v50
	v_add_u32_e32 v54, s59, v54
	v_sub_u32_e32 v58, v58, v88
	v_subrev_u32_e32 v64, s6, v64
	v_lshl_add_u64 v[70:71], v[62:63], 0, v[10:11]
	v_lshlrev_b64 v[50:51], 10, v[50:51]
	v_ashrrev_i32_e32 v55, 31, v54
	v_add_u32_e32 v58, s59, v58
	v_sub_u32_e32 v64, v64, v88
	global_load_dwordx4 v[10:13], v[70:71], off offset:768
	v_lshl_add_u64 v[72:73], v[62:63], 0, v[50:51]
	v_lshlrev_b64 v[54:55], 10, v[54:55]
	v_ashrrev_i32_e32 v59, 31, v58
	v_add_u32_e32 v64, s59, v64
	global_load_dwordx4 v[50:53], v[72:73], off offset:768
	v_lshl_add_u64 v[116:117], v[62:63], 0, v[54:55]
	v_lshlrev_b64 v[58:59], 10, v[58:59]
	v_ashrrev_i32_e32 v65, 31, v64
	global_load_dwordx4 v[54:57], v[116:117], off offset:768
	v_lshl_add_u64 v[118:119], v[62:63], 0, v[58:59]
	v_lshlrev_b64 v[64:65], 10, v[64:65]
	global_load_dwordx4 v[58:61], v[118:119], off offset:768
	v_lshl_add_u64 v[120:121], v[62:63], 0, v[64:65]
	global_load_dwordx4 v[62:65], v[120:121], off offset:768
	global_load_dwordx4 v[148:151], v[126:127], off offset:832
	global_load_dwordx4 v[152:155], v[128:129], off offset:832
	global_load_dwordx4 v[156:159], v[130:131], off offset:832
	global_load_dwordx4 v[160:163], v[132:133], off offset:832
	global_load_dwordx4 v[164:167], v[134:135], off offset:832
	global_load_dwordx4 v[168:171], v[136:137], off offset:832
	global_load_dwordx4 v[172:175], v[138:139], off offset:832
	global_load_dwordx4 v[176:179], v[122:123], off offset:832
	global_load_dwordx4 v[180:183], v[124:125], off offset:832
	global_load_dwordx4 v[184:187], v[76:77], off offset:832
	global_load_dwordx4 v[188:191], v[74:75], off offset:832
	global_load_dwordx4 v[192:195], v[70:71], off offset:832
	global_load_dwordx4 v[196:199], v[72:73], off offset:832
	global_load_dwordx4 v[200:203], v[116:117], off offset:832
	global_load_dwordx4 v[204:207], v[118:119], off offset:832
	global_load_dwordx4 v[222:225], v[120:121], off offset:832
	global_load_dwordx4 v[226:229], v[126:127], off offset:896
	global_load_dwordx4 v[230:233], v[128:129], off offset:896
	global_load_dwordx4 v[234:237], v[130:131], off offset:896
	global_load_dwordx4 v[238:241], v[132:133], off offset:896
	global_load_dwordx4 v[242:245], v[134:135], off offset:896
	global_load_dwordx4 v[246:249], v[136:137], off offset:896
	s_waitcnt vmcnt(37)
	v_lshlrev_b32_e32 v66, 16, v6
	v_and_b32_e32 v67, 0xffff0000, v6
	v_lshlrev_b32_e32 v6, 16, v7
	v_and_b32_e32 v7, 0xffff0000, v7
	v_cndmask_b32_e64 v114, 0, 1.0, s[8:9]
	s_waitcnt vmcnt(36)
	v_lshlrev_b32_e32 v68, 16, v14
	v_and_b32_e32 v69, 0xffff0000, v14
	v_pk_fma_f32 v[6:7], v[84:85], v[6:7], 0 op_sel_hi:[0, 1, 0]
	v_lshlrev_b32_e32 v14, 16, v15
	v_and_b32_e32 v15, 0xffff0000, v15
	v_cndmask_b32_e64 v112, 0, 1.0, s[12:13]
	v_pk_fma_f32 v[6:7], v[114:115], v[14:15], v[6:7] op_sel_hi:[0, 1, 1]
	s_waitcnt vmcnt(35)
	v_lshlrev_b32_e32 v14, 16, v19
	v_and_b32_e32 v15, 0xffff0000, v19
	v_cndmask_b32_e64 v110, 0, 1.0, s[16:17]
	v_pk_fma_f32 v[6:7], v[112:113], v[14:15], v[6:7] op_sel_hi:[0, 1, 1]
	s_waitcnt vmcnt(34)
	v_lshlrev_b32_e32 v14, 16, v23
	v_and_b32_e32 v15, 0xffff0000, v23
	v_cndmask_b32_e64 v108, 0, 1.0, s[20:21]
	v_pk_fma_f32 v[6:7], v[110:111], v[14:15], v[6:7] op_sel_hi:[0, 1, 1]
	s_waitcnt vmcnt(33)
	v_lshlrev_b32_e32 v14, 16, v27
	v_and_b32_e32 v15, 0xffff0000, v27
	v_cndmask_b32_e64 v106, 0, 1.0, s[24:25]
	v_pk_fma_f32 v[6:7], v[108:109], v[14:15], v[6:7] op_sel_hi:[0, 1, 1]
	s_waitcnt vmcnt(32)
	v_lshlrev_b32_e32 v14, 16, v31
	v_and_b32_e32 v15, 0xffff0000, v31
	v_cndmask_b32_e64 v104, 0, 1.0, s[28:29]
	v_pk_fma_f32 v[6:7], v[106:107], v[14:15], v[6:7] op_sel_hi:[0, 1, 1]
	s_waitcnt vmcnt(31)
	v_lshlrev_b32_e32 v14, 16, v35
	v_and_b32_e32 v15, 0xffff0000, v35
	v_pk_fma_f32 v[66:67], v[84:85], v[66:67], 0 op_sel_hi:[0, 1, 0]
	v_pk_fma_f32 v[6:7], v[104:105], v[14:15], v[6:7] op_sel_hi:[0, 1, 1]
	v_lshlrev_b32_e32 v14, 16, v8
	v_and_b32_e32 v15, 0xffff0000, v8
	v_lshlrev_b32_e32 v8, 16, v9
	v_and_b32_e32 v9, 0xffff0000, v9
	v_pk_fma_f32 v[66:67], v[114:115], v[68:69], v[66:67] op_sel_hi:[0, 1, 1]
	v_lshlrev_b32_e32 v68, 16, v18
	v_and_b32_e32 v69, 0xffff0000, v18
	v_lshlrev_b32_e32 v18, 16, v16
	v_and_b32_e32 v19, 0xffff0000, v16
	v_pk_fma_f32 v[8:9], v[84:85], v[8:9], 0 op_sel_hi:[0, 1, 0]
	v_lshlrev_b32_e32 v16, 16, v17
	v_and_b32_e32 v17, 0xffff0000, v17
	v_pk_fma_f32 v[8:9], v[114:115], v[16:17], v[8:9] op_sel_hi:[0, 1, 1]
	v_lshlrev_b32_e32 v16, 16, v21
	v_and_b32_e32 v17, 0xffff0000, v21
	v_pk_fma_f32 v[66:67], v[112:113], v[68:69], v[66:67] op_sel_hi:[0, 1, 1]
	v_lshlrev_b32_e32 v68, 16, v22
	v_and_b32_e32 v69, 0xffff0000, v22
	v_pk_fma_f32 v[8:9], v[112:113], v[16:17], v[8:9] op_sel_hi:[0, 1, 1]
	v_lshlrev_b32_e32 v16, 16, v25
	v_and_b32_e32 v17, 0xffff0000, v25
	v_pk_fma_f32 v[66:67], v[110:111], v[68:69], v[66:67] op_sel_hi:[0, 1, 1]
	v_lshlrev_b32_e32 v68, 16, v26
	v_and_b32_e32 v69, 0xffff0000, v26
	v_pk_fma_f32 v[8:9], v[110:111], v[16:17], v[8:9] op_sel_hi:[0, 1, 1]
	v_lshlrev_b32_e32 v16, 16, v29
	v_and_b32_e32 v17, 0xffff0000, v29
	v_pk_fma_f32 v[66:67], v[108:109], v[68:69], v[66:67] op_sel_hi:[0, 1, 1]
	v_lshlrev_b32_e32 v68, 16, v30
	v_and_b32_e32 v69, 0xffff0000, v30
	v_pk_fma_f32 v[8:9], v[108:109], v[16:17], v[8:9] op_sel_hi:[0, 1, 1]
	v_lshlrev_b32_e32 v16, 16, v33
	v_and_b32_e32 v17, 0xffff0000, v33
	v_pk_fma_f32 v[66:67], v[106:107], v[68:69], v[66:67] op_sel_hi:[0, 1, 1]
	v_lshlrev_b32_e32 v68, 16, v34
	v_and_b32_e32 v69, 0xffff0000, v34
	v_pk_fma_f32 v[14:15], v[84:85], v[14:15], 0 op_sel_hi:[0, 1, 0]
	v_pk_fma_f32 v[8:9], v[106:107], v[16:17], v[8:9] op_sel_hi:[0, 1, 1]
	v_lshlrev_b32_e32 v16, 16, v37
	v_and_b32_e32 v17, 0xffff0000, v37
	v_pk_fma_f32 v[66:67], v[104:105], v[68:69], v[66:67] op_sel_hi:[0, 1, 1]
	v_pk_fma_f32 v[14:15], v[114:115], v[18:19], v[14:15] op_sel_hi:[0, 1, 1]
	v_lshlrev_b32_e32 v18, 16, v20
	v_and_b32_e32 v19, 0xffff0000, v20
	v_pk_fma_f32 v[8:9], v[104:105], v[16:17], v[8:9] op_sel_hi:[0, 1, 1]
	v_cndmask_b32_e64 v86, 0, 1.0, vcc
	s_waitcnt vmcnt(30)
	v_lshlrev_b32_e32 v16, 16, v38
	v_and_b32_e32 v17, 0xffff0000, v38
	v_cmp_lt_u32_e32 vcc, v88, v87
	v_pk_fma_f32 v[14:15], v[112:113], v[18:19], v[14:15] op_sel_hi:[0, 1, 1]
	v_lshlrev_b32_e32 v18, 16, v24
	v_and_b32_e32 v19, 0xffff0000, v24
	v_lshlrev_b32_e32 v20, 16, v40
	v_and_b32_e32 v21, 0xffff0000, v40
	v_lshlrev_b32_e32 v22, 16, v41
	v_and_b32_e32 v23, 0xffff0000, v41
	v_cndmask_b32_e64 v88, 0, 1.0, vcc
	v_pk_fma_f32 v[16:17], v[86:87], v[16:17], v[66:67] op_sel_hi:[0, 1, 1]
	s_waitcnt vmcnt(29)
	v_lshlrev_b32_e32 v40, 16, v2
	v_and_b32_e32 v41, 0xffff0000, v2
	v_pk_fma_f32 v[14:15], v[110:111], v[18:19], v[14:15] op_sel_hi:[0, 1, 1]
	v_lshlrev_b32_e32 v18, 16, v28
	v_and_b32_e32 v19, 0xffff0000, v28
	v_cndmask_b32_e64 v90, 0, 1.0, s[0:1]
	s_waitcnt vmcnt(28)
	v_lshlrev_b32_e32 v24, 16, v42
	v_and_b32_e32 v25, 0xffff0000, v42
	v_pk_fma_f32 v[16:17], v[88:89], v[40:41], v[16:17] op_sel_hi:[0, 1, 1]
	v_pk_fma_f32 v[14:15], v[108:109], v[18:19], v[14:15] op_sel_hi:[0, 1, 1]
	v_lshlrev_b32_e32 v18, 16, v32
	v_and_b32_e32 v19, 0xffff0000, v32
	v_cndmask_b32_e64 v94, 0, 1.0, s[4:5]
	s_waitcnt vmcnt(27)
	v_lshlrev_b32_e32 v32, 16, v46
	v_and_b32_e32 v33, 0xffff0000, v46
	v_pk_fma_f32 v[16:17], v[90:91], v[24:25], v[16:17] op_sel_hi:[0, 1, 1]
	v_cndmask_b32_e64 v102, 0, 1.0, s[10:11]
	v_pk_fma_f32 v[16:17], v[94:95], v[32:33], v[16:17] op_sel_hi:[0, 1, 1]
	s_waitcnt vmcnt(26)
	v_lshlrev_b32_e32 v24, 16, v10
	v_and_b32_e32 v25, 0xffff0000, v10
	v_cndmask_b32_e64 v100, 0, 1.0, s[14:15]
	v_pk_fma_f32 v[16:17], v[102:103], v[24:25], v[16:17] op_sel_hi:[0, 1, 1]
	s_waitcnt vmcnt(25)
	v_lshlrev_b32_e32 v24, 16, v50
	v_and_b32_e32 v25, 0xffff0000, v50
	v_cndmask_b32_e64 v98, 0, 1.0, s[18:19]
	v_pk_fma_f32 v[16:17], v[100:101], v[24:25], v[16:17] op_sel_hi:[0, 1, 1]
	s_waitcnt vmcnt(24)
	v_lshlrev_b32_e32 v24, 16, v54
	v_and_b32_e32 v25, 0xffff0000, v54
	v_cndmask_b32_e64 v96, 0, 1.0, s[22:23]
	v_pk_fma_f32 v[16:17], v[98:99], v[24:25], v[16:17] op_sel_hi:[0, 1, 1]
	s_waitcnt vmcnt(23)
	v_lshlrev_b32_e32 v24, 16, v58
	v_and_b32_e32 v25, 0xffff0000, v58
	v_cndmask_b32_e64 v92, 0, 1.0, s[26:27]
	v_pk_fma_f32 v[16:17], v[96:97], v[24:25], v[16:17] op_sel_hi:[0, 1, 1]
	s_waitcnt vmcnt(22)
	v_lshlrev_b32_e32 v24, 16, v62
	v_and_b32_e32 v25, 0xffff0000, v62
	v_pk_fma_f32 v[14:15], v[106:107], v[18:19], v[14:15] op_sel_hi:[0, 1, 1]
	v_lshlrev_b32_e32 v18, 16, v36
	v_and_b32_e32 v19, 0xffff0000, v36
	v_pk_fma_f32 v[16:17], v[92:93], v[24:25], v[16:17] op_sel_hi:[0, 1, 1]
	v_pk_fma_f32 v[14:15], v[104:105], v[18:19], v[14:15] op_sel_hi:[0, 1, 1]
	v_lshlrev_b32_e32 v18, 16, v39
	v_and_b32_e32 v19, 0xffff0000, v39
	v_pk_fma_f32 v[16:17], v[82:83], v[16:17], v[40:41] op_sel_hi:[0, 1, 1] neg_lo:[0, 0, 1] neg_hi:[0, 0, 1]
	v_cvt_pk_bf16_f32 v2, v16, v17
	v_pk_fma_f32 v[6:7], v[86:87], v[18:19], v[6:7] op_sel_hi:[0, 1, 1]
	v_lshlrev_b32_e32 v16, 16, v3
	v_and_b32_e32 v17, 0xffff0000, v3
	v_lshlrev_b32_e32 v26, 16, v43
	v_and_b32_e32 v27, 0xffff0000, v43
	v_pk_fma_f32 v[6:7], v[88:89], v[16:17], v[6:7] op_sel_hi:[0, 1, 1]
	v_lshlrev_b32_e32 v34, 16, v47
	v_and_b32_e32 v35, 0xffff0000, v47
	v_pk_fma_f32 v[6:7], v[90:91], v[26:27], v[6:7] op_sel_hi:[0, 1, 1]
	v_pk_fma_f32 v[6:7], v[94:95], v[34:35], v[6:7] op_sel_hi:[0, 1, 1]
	v_lshlrev_b32_e32 v10, 16, v11
	v_and_b32_e32 v11, 0xffff0000, v11
	v_pk_fma_f32 v[6:7], v[102:103], v[10:11], v[6:7] op_sel_hi:[0, 1, 1]
	v_lshlrev_b32_e32 v10, 16, v51
	v_and_b32_e32 v11, 0xffff0000, v51
	v_pk_fma_f32 v[6:7], v[100:101], v[10:11], v[6:7] op_sel_hi:[0, 1, 1]
	v_lshlrev_b32_e32 v10, 16, v55
	v_and_b32_e32 v11, 0xffff0000, v55
	v_pk_fma_f32 v[6:7], v[98:99], v[10:11], v[6:7] op_sel_hi:[0, 1, 1]
	v_lshlrev_b32_e32 v10, 16, v59
	v_and_b32_e32 v11, 0xffff0000, v59
	v_pk_fma_f32 v[6:7], v[96:97], v[10:11], v[6:7] op_sel_hi:[0, 1, 1]
	v_lshlrev_b32_e32 v10, 16, v63
	v_and_b32_e32 v11, 0xffff0000, v63
	v_pk_fma_f32 v[6:7], v[92:93], v[10:11], v[6:7] op_sel_hi:[0, 1, 1]
	v_pk_fma_f32 v[6:7], v[82:83], v[6:7], v[16:17] op_sel_hi:[0, 1, 1] neg_lo:[0, 0, 1] neg_hi:[0, 0, 1]
	v_cvt_pk_bf16_f32 v3, v6, v7
	v_pk_fma_f32 v[6:7], v[86:87], v[20:21], v[14:15] op_sel_hi:[0, 1, 1]
	v_lshlrev_b32_e32 v10, 16, v4
	v_and_b32_e32 v11, 0xffff0000, v4
	v_lshlrev_b32_e32 v28, 16, v44
	v_and_b32_e32 v29, 0xffff0000, v44
	v_pk_fma_f32 v[6:7], v[88:89], v[10:11], v[6:7] op_sel_hi:[0, 1, 1]
	v_lshlrev_b32_e32 v36, 16, v48
	v_and_b32_e32 v37, 0xffff0000, v48
	v_pk_fma_f32 v[6:7], v[90:91], v[28:29], v[6:7] op_sel_hi:[0, 1, 1]
	v_pk_fma_f32 v[6:7], v[94:95], v[36:37], v[6:7] op_sel_hi:[0, 1, 1]
	v_lshlrev_b32_e32 v14, 16, v12
	v_and_b32_e32 v15, 0xffff0000, v12
	v_pk_fma_f32 v[6:7], v[102:103], v[14:15], v[6:7] op_sel_hi:[0, 1, 1]
	v_lshlrev_b32_e32 v14, 16, v52
	v_and_b32_e32 v15, 0xffff0000, v52
	v_pk_fma_f32 v[6:7], v[100:101], v[14:15], v[6:7] op_sel_hi:[0, 1, 1]
	v_lshlrev_b32_e32 v14, 16, v56
	v_and_b32_e32 v15, 0xffff0000, v56
	v_pk_fma_f32 v[6:7], v[98:99], v[14:15], v[6:7] op_sel_hi:[0, 1, 1]
	v_lshlrev_b32_e32 v14, 16, v60
	v_and_b32_e32 v15, 0xffff0000, v60
	v_pk_fma_f32 v[6:7], v[96:97], v[14:15], v[6:7] op_sel_hi:[0, 1, 1]
	v_lshlrev_b32_e32 v14, 16, v64
	v_and_b32_e32 v15, 0xffff0000, v64
	v_pk_fma_f32 v[6:7], v[92:93], v[14:15], v[6:7] op_sel_hi:[0, 1, 1]
	v_pk_fma_f32 v[6:7], v[82:83], v[6:7], v[10:11] op_sel_hi:[0, 1, 1] neg_lo:[0, 0, 1] neg_hi:[0, 0, 1]
	v_cvt_pk_bf16_f32 v4, v6, v7
	v_pk_fma_f32 v[6:7], v[86:87], v[22:23], v[8:9] op_sel_hi:[0, 1, 1]
	v_lshlrev_b32_e32 v8, 16, v5
	v_and_b32_e32 v9, 0xffff0000, v5
	v_lshlrev_b32_e32 v30, 16, v45
	v_and_b32_e32 v31, 0xffff0000, v45
	v_pk_fma_f32 v[6:7], v[88:89], v[8:9], v[6:7] op_sel_hi:[0, 1, 1]
	v_lshlrev_b32_e32 v38, 16, v49
	v_and_b32_e32 v39, 0xffff0000, v49
	v_pk_fma_f32 v[6:7], v[90:91], v[30:31], v[6:7] op_sel_hi:[0, 1, 1]
	v_pk_fma_f32 v[6:7], v[94:95], v[38:39], v[6:7] op_sel_hi:[0, 1, 1]
	v_lshlrev_b32_e32 v10, 16, v13
	v_and_b32_e32 v11, 0xffff0000, v13
	v_pk_fma_f32 v[6:7], v[102:103], v[10:11], v[6:7] op_sel_hi:[0, 1, 1]
	v_lshlrev_b32_e32 v10, 16, v53
	v_and_b32_e32 v11, 0xffff0000, v53
	v_pk_fma_f32 v[6:7], v[100:101], v[10:11], v[6:7] op_sel_hi:[0, 1, 1]
	v_lshlrev_b32_e32 v10, 16, v57
	v_and_b32_e32 v11, 0xffff0000, v57
	v_pk_fma_f32 v[6:7], v[98:99], v[10:11], v[6:7] op_sel_hi:[0, 1, 1]
	v_lshlrev_b32_e32 v10, 16, v61
	v_and_b32_e32 v11, 0xffff0000, v61
	v_pk_fma_f32 v[6:7], v[96:97], v[10:11], v[6:7] op_sel_hi:[0, 1, 1]
	v_lshlrev_b32_e32 v10, 16, v65
	v_and_b32_e32 v11, 0xffff0000, v65
	v_pk_fma_f32 v[6:7], v[92:93], v[10:11], v[6:7] op_sel_hi:[0, 1, 1]
	v_pk_fma_f32 v[6:7], v[82:83], v[6:7], v[8:9] op_sel_hi:[0, 1, 1] neg_lo:[0, 0, 1] neg_hi:[0, 0, 1]
	v_cvt_pk_bf16_f32 v5, v6, v7
	s_nop 0
	s_nop 0
	s_nop 0
	s_nop 0
	s_nop 0
	s_nop 0
	s_nop 0
	s_nop 0
	s_nop 0
	s_nop 0
	s_nop 0
	s_nop 0
	s_nop 0
	s_nop 0
	s_nop 0
	s_nop 0
	s_mov_b64 s[0:1], 0x400
	v_lshlrev_b32_e32 v0, 3, v83
	s_waitcnt vmcnt(21)
	v_lshlrev_b32_e32 v140, 16, v148
	v_and_b32_e32 v141, 0xffff0000, v148
	v_lshlrev_b32_e32 v6, 16, v149
	v_and_b32_e32 v7, 0xffff0000, v149
	s_waitcnt vmcnt(20)
	v_lshlrev_b32_e32 v142, 16, v152
	v_and_b32_e32 v143, 0xffff0000, v152
	v_pk_fma_f32 v[6:7], v[84:85], v[6:7], 0 op_sel_hi:[0, 1, 0]
	v_lshlrev_b32_e32 v10, 16, v153
	v_and_b32_e32 v11, 0xffff0000, v153
	v_pk_fma_f32 v[6:7], v[114:115], v[10:11], v[6:7] op_sel_hi:[0, 1, 1]
	s_waitcnt vmcnt(19)
	v_lshlrev_b32_e32 v10, 16, v157
	v_and_b32_e32 v11, 0xffff0000, v157
	v_pk_fma_f32 v[6:7], v[112:113], v[10:11], v[6:7] op_sel_hi:[0, 1, 1]
	s_waitcnt vmcnt(18)
	v_lshlrev_b32_e32 v10, 16, v161
	v_and_b32_e32 v11, 0xffff0000, v161
	v_pk_fma_f32 v[6:7], v[110:111], v[10:11], v[6:7] op_sel_hi:[0, 1, 1]
	s_waitcnt vmcnt(17)
	v_lshlrev_b32_e32 v10, 16, v165
	v_and_b32_e32 v11, 0xffff0000, v165
	v_pk_fma_f32 v[6:7], v[108:109], v[10:11], v[6:7] op_sel_hi:[0, 1, 1]
	s_waitcnt vmcnt(16)
	v_lshlrev_b32_e32 v10, 16, v169
	v_and_b32_e32 v11, 0xffff0000, v169
	v_pk_fma_f32 v[6:7], v[106:107], v[10:11], v[6:7] op_sel_hi:[0, 1, 1]
	s_waitcnt vmcnt(15)
	v_lshlrev_b32_e32 v10, 16, v173
	v_and_b32_e32 v11, 0xffff0000, v173
	v_pk_fma_f32 v[140:141], v[84:85], v[140:141], 0 op_sel_hi:[0, 1, 0]
	v_pk_fma_f32 v[10:11], v[104:105], v[10:11], v[6:7] op_sel_hi:[0, 1, 1]
	v_lshlrev_b32_e32 v6, 16, v150
	v_and_b32_e32 v7, 0xffff0000, v150
	v_pk_fma_f32 v[140:141], v[114:115], v[142:143], v[140:141] op_sel_hi:[0, 1, 1]
	v_lshlrev_b32_e32 v142, 16, v156
	v_and_b32_e32 v143, 0xffff0000, v156
	v_pk_fma_f32 v[6:7], v[84:85], v[6:7], 0 op_sel_hi:[0, 1, 0]
	v_lshlrev_b32_e32 v14, 16, v154
	v_and_b32_e32 v15, 0xffff0000, v154
	v_pk_fma_f32 v[6:7], v[114:115], v[14:15], v[6:7] op_sel_hi:[0, 1, 1]
	v_lshlrev_b32_e32 v14, 16, v158
	v_and_b32_e32 v15, 0xffff0000, v158
	v_pk_fma_f32 v[6:7], v[112:113], v[14:15], v[6:7] op_sel_hi:[0, 1, 1]
	v_lshlrev_b32_e32 v14, 16, v162
	v_and_b32_e32 v15, 0xffff0000, v162
	v_pk_fma_f32 v[6:7], v[110:111], v[14:15], v[6:7] op_sel_hi:[0, 1, 1]
	v_lshlrev_b32_e32 v14, 16, v166
	v_and_b32_e32 v15, 0xffff0000, v166
	v_pk_fma_f32 v[6:7], v[108:109], v[14:15], v[6:7] op_sel_hi:[0, 1, 1]
	v_lshlrev_b32_e32 v14, 16, v170
	v_and_b32_e32 v15, 0xffff0000, v170
	v_pk_fma_f32 v[6:7], v[106:107], v[14:15], v[6:7] op_sel_hi:[0, 1, 1]
	v_lshlrev_b32_e32 v14, 16, v174
	v_and_b32_e32 v15, 0xffff0000, v174
	v_pk_fma_f32 v[14:15], v[104:105], v[14:15], v[6:7] op_sel_hi:[0, 1, 1]
	v_lshlrev_b32_e32 v6, 16, v151
	v_and_b32_e32 v7, 0xffff0000, v151
	v_pk_fma_f32 v[6:7], v[84:85], v[6:7], 0 op_sel_hi:[0, 1, 0]
	v_lshlrev_b32_e32 v8, 16, v155
	v_and_b32_e32 v9, 0xffff0000, v155
	v_pk_fma_f32 v[6:7], v[114:115], v[8:9], v[6:7] op_sel_hi:[0, 1, 1]
	v_lshlrev_b32_e32 v8, 16, v159
	v_and_b32_e32 v9, 0xffff0000, v159
	v_pk_fma_f32 v[140:141], v[112:113], v[142:143], v[140:141] op_sel_hi:[0, 1, 1]
	v_lshlrev_b32_e32 v142, 16, v160
	v_and_b32_e32 v143, 0xffff0000, v160
	v_pk_fma_f32 v[6:7], v[112:113], v[8:9], v[6:7] op_sel_hi:[0, 1, 1]
	v_lshlrev_b32_e32 v8, 16, v163
	v_and_b32_e32 v9, 0xffff0000, v163
	v_pk_fma_f32 v[140:141], v[110:111], v[142:143], v[140:141] op_sel_hi:[0, 1, 1]
	v_lshlrev_b32_e32 v142, 16, v164
	v_and_b32_e32 v143, 0xffff0000, v164
	v_pk_fma_f32 v[6:7], v[110:111], v[8:9], v[6:7] op_sel_hi:[0, 1, 1]
	v_lshlrev_b32_e32 v8, 16, v167
	v_and_b32_e32 v9, 0xffff0000, v167
	v_pk_fma_f32 v[140:141], v[108:109], v[142:143], v[140:141] op_sel_hi:[0, 1, 1]
	v_lshlrev_b32_e32 v142, 16, v168
	v_and_b32_e32 v143, 0xffff0000, v168
	v_pk_fma_f32 v[6:7], v[108:109], v[8:9], v[6:7] op_sel_hi:[0, 1, 1]
	v_lshlrev_b32_e32 v8, 16, v171
	v_and_b32_e32 v9, 0xffff0000, v171
	v_pk_fma_f32 v[140:141], v[106:107], v[142:143], v[140:141] op_sel_hi:[0, 1, 1]
	v_lshlrev_b32_e32 v142, 16, v172
	v_and_b32_e32 v143, 0xffff0000, v172
	v_pk_fma_f32 v[6:7], v[106:107], v[8:9], v[6:7] op_sel_hi:[0, 1, 1]
	v_lshlrev_b32_e32 v8, 16, v175
	v_and_b32_e32 v9, 0xffff0000, v175
	v_pk_fma_f32 v[140:141], v[104:105], v[142:143], v[140:141] op_sel_hi:[0, 1, 1]
	v_pk_fma_f32 v[12:13], v[104:105], v[8:9], v[6:7] op_sel_hi:[0, 1, 1]
	s_waitcnt vmcnt(14)
	v_lshlrev_b32_e32 v6, 16, v176
	v_and_b32_e32 v7, 0xffff0000, v176
	v_lshlrev_b32_e32 v16, 16, v178
	v_and_b32_e32 v17, 0xffff0000, v178
	v_lshlrev_b32_e32 v18, 16, v179
	v_and_b32_e32 v19, 0xffff0000, v179
	v_pk_fma_f32 v[6:7], v[86:87], v[6:7], v[140:141] op_sel_hi:[0, 1, 1]
	s_waitcnt vmcnt(13)
	v_lshlrev_b32_e32 v40, 16, v180
	v_and_b32_e32 v41, 0xffff0000, v180
	s_waitcnt vmcnt(12)
	v_lshlrev_b32_e32 v20, 16, v184
	v_and_b32_e32 v21, 0xffff0000, v184
	v_pk_fma_f32 v[6:7], v[88:89], v[40:41], v[6:7] op_sel_hi:[0, 1, 1]
	s_waitcnt vmcnt(11)
	v_lshlrev_b32_e32 v28, 16, v188
	v_and_b32_e32 v29, 0xffff0000, v188
	v_pk_fma_f32 v[6:7], v[90:91], v[20:21], v[6:7] op_sel_hi:[0, 1, 1]
	v_pk_fma_f32 v[6:7], v[94:95], v[28:29], v[6:7] op_sel_hi:[0, 1, 1]
	s_waitcnt vmcnt(10)
	v_lshlrev_b32_e32 v20, 16, v192
	v_and_b32_e32 v21, 0xffff0000, v192
	v_lshlrev_b32_e32 v8, 16, v177
	v_and_b32_e32 v9, 0xffff0000, v177
	v_pk_fma_f32 v[6:7], v[102:103], v[20:21], v[6:7] op_sel_hi:[0, 1, 1]
	s_waitcnt vmcnt(9)
	v_lshlrev_b32_e32 v20, 16, v196
	v_and_b32_e32 v21, 0xffff0000, v196
	v_pk_fma_f32 v[6:7], v[100:101], v[20:21], v[6:7] op_sel_hi:[0, 1, 1]
	s_waitcnt vmcnt(8)
	v_lshlrev_b32_e32 v20, 16, v200
	v_and_b32_e32 v21, 0xffff0000, v200
	v_pk_fma_f32 v[8:9], v[86:87], v[8:9], v[10:11] op_sel_hi:[0, 1, 1]
	v_lshlrev_b32_e32 v10, 16, v181
	v_and_b32_e32 v11, 0xffff0000, v181
	v_lshlrev_b32_e32 v22, 16, v185
	v_and_b32_e32 v23, 0xffff0000, v185
	v_pk_fma_f32 v[6:7], v[98:99], v[20:21], v[6:7] op_sel_hi:[0, 1, 1]
	s_waitcnt vmcnt(7)
	v_lshlrev_b32_e32 v20, 16, v204
	v_and_b32_e32 v21, 0xffff0000, v204
	v_pk_fma_f32 v[8:9], v[88:89], v[10:11], v[8:9] op_sel_hi:[0, 1, 1]
	v_lshlrev_b32_e32 v30, 16, v189
	v_and_b32_e32 v31, 0xffff0000, v189
	v_pk_fma_f32 v[6:7], v[96:97], v[20:21], v[6:7] op_sel_hi:[0, 1, 1]
	s_waitcnt vmcnt(6)
	v_lshlrev_b32_e32 v20, 16, v222
	v_and_b32_e32 v21, 0xffff0000, v222
	v_pk_fma_f32 v[8:9], v[90:91], v[22:23], v[8:9] op_sel_hi:[0, 1, 1]
	v_pk_fma_f32 v[6:7], v[92:93], v[20:21], v[6:7] op_sel_hi:[0, 1, 1]
	v_pk_fma_f32 v[8:9], v[94:95], v[30:31], v[8:9] op_sel_hi:[0, 1, 1]
	v_lshlrev_b32_e32 v20, 16, v193
	v_and_b32_e32 v21, 0xffff0000, v193
	v_pk_fma_f32 v[8:9], v[102:103], v[20:21], v[8:9] op_sel_hi:[0, 1, 1]
	v_lshlrev_b32_e32 v20, 16, v197
	v_and_b32_e32 v21, 0xffff0000, v197
	v_pk_fma_f32 v[8:9], v[100:101], v[20:21], v[8:9] op_sel_hi:[0, 1, 1]
	v_lshlrev_b32_e32 v20, 16, v201
	v_and_b32_e32 v21, 0xffff0000, v201
	v_pk_fma_f32 v[8:9], v[98:99], v[20:21], v[8:9] op_sel_hi:[0, 1, 1]
	v_lshlrev_b32_e32 v20, 16, v205
	v_and_b32_e32 v21, 0xffff0000, v205
	v_pk_fma_f32 v[8:9], v[96:97], v[20:21], v[8:9] op_sel_hi:[0, 1, 1]
	v_lshlrev_b32_e32 v20, 16, v223
	v_and_b32_e32 v21, 0xffff0000, v223
	v_pk_fma_f32 v[8:9], v[92:93], v[20:21], v[8:9] op_sel_hi:[0, 1, 1]
	v_pk_fma_f32 v[6:7], v[82:83], v[6:7], v[40:41] op_sel_hi:[0, 1, 1] neg_lo:[0, 0, 1] neg_hi:[0, 0, 1]
	v_pk_fma_f32 v[8:9], v[82:83], v[8:9], v[10:11] op_sel_hi:[0, 1, 1] neg_lo:[0, 0, 1] neg_hi:[0, 0, 1]
	v_cvt_pk_bf16_f32 v6, v6, v7
	v_cvt_pk_bf16_f32 v7, v8, v9
	v_pk_fma_f32 v[8:9], v[86:87], v[16:17], v[14:15] op_sel_hi:[0, 1, 1]
	v_lshlrev_b32_e32 v10, 16, v182
	v_and_b32_e32 v11, 0xffff0000, v182
	v_lshlrev_b32_e32 v24, 16, v186
	v_and_b32_e32 v25, 0xffff0000, v186
	v_pk_fma_f32 v[8:9], v[88:89], v[10:11], v[8:9] op_sel_hi:[0, 1, 1]
	v_lshlrev_b32_e32 v32, 16, v190
	v_and_b32_e32 v33, 0xffff0000, v190
	v_pk_fma_f32 v[8:9], v[90:91], v[24:25], v[8:9] op_sel_hi:[0, 1, 1]
	v_pk_fma_f32 v[8:9], v[94:95], v[32:33], v[8:9] op_sel_hi:[0, 1, 1]
	v_lshlrev_b32_e32 v14, 16, v194
	v_and_b32_e32 v15, 0xffff0000, v194
	v_pk_fma_f32 v[8:9], v[102:103], v[14:15], v[8:9] op_sel_hi:[0, 1, 1]
	v_lshlrev_b32_e32 v14, 16, v198
	v_and_b32_e32 v15, 0xffff0000, v198
	v_pk_fma_f32 v[8:9], v[100:101], v[14:15], v[8:9] op_sel_hi:[0, 1, 1]
	v_lshlrev_b32_e32 v14, 16, v202
	v_and_b32_e32 v15, 0xffff0000, v202
	v_pk_fma_f32 v[8:9], v[98:99], v[14:15], v[8:9] op_sel_hi:[0, 1, 1]
	v_lshlrev_b32_e32 v14, 16, v206
	v_and_b32_e32 v15, 0xffff0000, v206
	v_pk_fma_f32 v[8:9], v[96:97], v[14:15], v[8:9] op_sel_hi:[0, 1, 1]
	v_lshlrev_b32_e32 v14, 16, v224
	v_and_b32_e32 v15, 0xffff0000, v224
	v_pk_fma_f32 v[8:9], v[92:93], v[14:15], v[8:9] op_sel_hi:[0, 1, 1]
	v_pk_fma_f32 v[8:9], v[82:83], v[8:9], v[10:11] op_sel_hi:[0, 1, 1] neg_lo:[0, 0, 1] neg_hi:[0, 0, 1]
	v_pk_fma_f32 v[10:11], v[86:87], v[18:19], v[12:13] op_sel_hi:[0, 1, 1]
	v_lshlrev_b32_e32 v12, 16, v183
	v_and_b32_e32 v13, 0xffff0000, v183
	v_lshlrev_b32_e32 v26, 16, v187
	v_and_b32_e32 v27, 0xffff0000, v187
	v_pk_fma_f32 v[10:11], v[88:89], v[12:13], v[10:11] op_sel_hi:[0, 1, 1]
	v_lshlrev_b32_e32 v38, 16, v191
	v_and_b32_e32 v39, 0xffff0000, v191
	v_pk_fma_f32 v[10:11], v[90:91], v[26:27], v[10:11] op_sel_hi:[0, 1, 1]
	v_pk_fma_f32 v[10:11], v[94:95], v[38:39], v[10:11] op_sel_hi:[0, 1, 1]
	v_lshlrev_b32_e32 v14, 16, v195
	v_and_b32_e32 v15, 0xffff0000, v195
	v_pk_fma_f32 v[10:11], v[102:103], v[14:15], v[10:11] op_sel_hi:[0, 1, 1]
	v_lshlrev_b32_e32 v14, 16, v199
	v_and_b32_e32 v15, 0xffff0000, v199
	v_pk_fma_f32 v[10:11], v[100:101], v[14:15], v[10:11] op_sel_hi:[0, 1, 1]
	v_lshlrev_b32_e32 v14, 16, v203
	v_and_b32_e32 v15, 0xffff0000, v203
	v_pk_fma_f32 v[10:11], v[98:99], v[14:15], v[10:11] op_sel_hi:[0, 1, 1]
	v_lshlrev_b32_e32 v14, 16, v207
	v_and_b32_e32 v15, 0xffff0000, v207
	v_pk_fma_f32 v[10:11], v[96:97], v[14:15], v[10:11] op_sel_hi:[0, 1, 1]
	v_lshlrev_b32_e32 v14, 16, v225
	v_and_b32_e32 v15, 0xffff0000, v225
	v_pk_fma_f32 v[10:11], v[92:93], v[14:15], v[10:11] op_sel_hi:[0, 1, 1]
	v_pk_fma_f32 v[10:11], v[82:83], v[10:11], v[12:13] op_sel_hi:[0, 1, 1] neg_lo:[0, 0, 1] neg_hi:[0, 0, 1]
	v_cvt_pk_bf16_f32 v8, v8, v9
	v_cvt_pk_bf16_f32 v9, v10, v11
	s_nop 0
	s_nop 0
	s_nop 0
	s_nop 0
	s_nop 0
	s_nop 0
	global_load_dwordx4 v[34:37], v[138:139], off offset:896
	global_load_dwordx4 v[38:41], v[122:123], off offset:896
	global_load_dwordx4 v[42:45], v[124:125], off offset:896
	global_load_dwordx4 v[46:49], v[76:77], off offset:896
	global_load_dwordx4 v[50:53], v[74:75], off offset:896
	global_load_dwordx4 v[54:57], v[70:71], off offset:896
	global_load_dwordx4 v[58:61], v[72:73], off offset:896
	global_load_dwordx4 v[62:65], v[116:117], off offset:896
	global_load_dwordx4 v[66:69], v[118:119], off offset:896
	global_load_dwordx4 v[140:143], v[120:121], off offset:896
	s_waitcnt vmcnt(15)
	v_lshlrev_b32_e32 v144, 16, v226
	v_and_b32_e32 v145, 0xffff0000, v226
	v_lshlrev_b32_e32 v10, 16, v227
	v_and_b32_e32 v11, 0xffff0000, v227
	s_waitcnt vmcnt(14)
	v_lshlrev_b32_e32 v146, 16, v230
	v_and_b32_e32 v147, 0xffff0000, v230
	v_pk_fma_f32 v[10:11], v[84:85], v[10:11], 0 op_sel_hi:[0, 1, 0]
	v_lshlrev_b32_e32 v14, 16, v231
	v_and_b32_e32 v15, 0xffff0000, v231
	v_pk_fma_f32 v[10:11], v[114:115], v[14:15], v[10:11] op_sel_hi:[0, 1, 1]
	s_waitcnt vmcnt(13)
	v_lshlrev_b32_e32 v14, 16, v235
	v_and_b32_e32 v15, 0xffff0000, v235
	v_pk_fma_f32 v[10:11], v[112:113], v[14:15], v[10:11] op_sel_hi:[0, 1, 1]
	s_waitcnt vmcnt(12)
	v_lshlrev_b32_e32 v14, 16, v239
	v_and_b32_e32 v15, 0xffff0000, v239
	v_pk_fma_f32 v[10:11], v[110:111], v[14:15], v[10:11] op_sel_hi:[0, 1, 1]
	s_waitcnt vmcnt(11)
	v_lshlrev_b32_e32 v14, 16, v243
	v_and_b32_e32 v15, 0xffff0000, v243
	v_pk_fma_f32 v[10:11], v[108:109], v[14:15], v[10:11] op_sel_hi:[0, 1, 1]
	s_waitcnt vmcnt(10)
	v_lshlrev_b32_e32 v14, 16, v247
	v_and_b32_e32 v15, 0xffff0000, v247
	v_pk_fma_f32 v[10:11], v[106:107], v[14:15], v[10:11] op_sel_hi:[0, 1, 1]
	s_waitcnt vmcnt(9)
	v_lshlrev_b32_e32 v14, 16, v35
	v_and_b32_e32 v15, 0xffff0000, v35
	v_pk_fma_f32 v[144:145], v[84:85], v[144:145], 0 op_sel_hi:[0, 1, 0]
	v_pk_fma_f32 v[14:15], v[104:105], v[14:15], v[10:11] op_sel_hi:[0, 1, 1]
	v_lshlrev_b32_e32 v10, 16, v228
	v_and_b32_e32 v11, 0xffff0000, v228
	v_pk_fma_f32 v[144:145], v[114:115], v[146:147], v[144:145] op_sel_hi:[0, 1, 1]
	v_lshlrev_b32_e32 v146, 16, v234
	v_and_b32_e32 v147, 0xffff0000, v234
	v_pk_fma_f32 v[10:11], v[84:85], v[10:11], 0 op_sel_hi:[0, 1, 0]
	v_lshlrev_b32_e32 v18, 16, v232
	v_and_b32_e32 v19, 0xffff0000, v232
	v_pk_fma_f32 v[10:11], v[114:115], v[18:19], v[10:11] op_sel_hi:[0, 1, 1]
	v_lshlrev_b32_e32 v18, 16, v236
	v_and_b32_e32 v19, 0xffff0000, v236
	v_pk_fma_f32 v[10:11], v[112:113], v[18:19], v[10:11] op_sel_hi:[0, 1, 1]
	v_lshlrev_b32_e32 v18, 16, v240
	v_and_b32_e32 v19, 0xffff0000, v240
	v_pk_fma_f32 v[10:11], v[110:111], v[18:19], v[10:11] op_sel_hi:[0, 1, 1]
	v_lshlrev_b32_e32 v18, 16, v244
	v_and_b32_e32 v19, 0xffff0000, v244
	v_pk_fma_f32 v[10:11], v[108:109], v[18:19], v[10:11] op_sel_hi:[0, 1, 1]
	v_lshlrev_b32_e32 v18, 16, v248
	v_and_b32_e32 v19, 0xffff0000, v248
	v_pk_fma_f32 v[10:11], v[106:107], v[18:19], v[10:11] op_sel_hi:[0, 1, 1]
	v_lshlrev_b32_e32 v18, 16, v36
	v_and_b32_e32 v19, 0xffff0000, v36
	v_pk_fma_f32 v[18:19], v[104:105], v[18:19], v[10:11] op_sel_hi:[0, 1, 1]
	v_lshlrev_b32_e32 v10, 16, v229
	v_and_b32_e32 v11, 0xffff0000, v229
	v_pk_fma_f32 v[10:11], v[84:85], v[10:11], 0 op_sel_hi:[0, 1, 0]
	v_lshlrev_b32_e32 v12, 16, v233
	v_and_b32_e32 v13, 0xffff0000, v233
	v_pk_fma_f32 v[10:11], v[114:115], v[12:13], v[10:11] op_sel_hi:[0, 1, 1]
	v_lshlrev_b32_e32 v12, 16, v237
	v_and_b32_e32 v13, 0xffff0000, v237
	v_pk_fma_f32 v[144:145], v[112:113], v[146:147], v[144:145] op_sel_hi:[0, 1, 1]
	v_lshlrev_b32_e32 v146, 16, v238
	v_and_b32_e32 v147, 0xffff0000, v238
	v_pk_fma_f32 v[10:11], v[112:113], v[12:13], v[10:11] op_sel_hi:[0, 1, 1]
	v_lshlrev_b32_e32 v12, 16, v241
	v_and_b32_e32 v13, 0xffff0000, v241
	v_pk_fma_f32 v[144:145], v[110:111], v[146:147], v[144:145] op_sel_hi:[0, 1, 1]
	v_lshlrev_b32_e32 v146, 16, v242
	v_and_b32_e32 v147, 0xffff0000, v242
	v_pk_fma_f32 v[10:11], v[110:111], v[12:13], v[10:11] op_sel_hi:[0, 1, 1]
	v_lshlrev_b32_e32 v12, 16, v245
	v_and_b32_e32 v13, 0xffff0000, v245
	v_pk_fma_f32 v[144:145], v[108:109], v[146:147], v[144:145] op_sel_hi:[0, 1, 1]
	v_lshlrev_b32_e32 v146, 16, v246
	v_and_b32_e32 v147, 0xffff0000, v246
	v_pk_fma_f32 v[10:11], v[108:109], v[12:13], v[10:11] op_sel_hi:[0, 1, 1]
	v_lshlrev_b32_e32 v12, 16, v249
	v_and_b32_e32 v13, 0xffff0000, v249
	v_pk_fma_f32 v[144:145], v[106:107], v[146:147], v[144:145] op_sel_hi:[0, 1, 1]
	v_lshlrev_b32_e32 v146, 16, v34
	v_and_b32_e32 v147, 0xffff0000, v34
	v_pk_fma_f32 v[10:11], v[106:107], v[12:13], v[10:11] op_sel_hi:[0, 1, 1]
	v_lshlrev_b32_e32 v12, 16, v37
	v_and_b32_e32 v13, 0xffff0000, v37
	v_pk_fma_f32 v[144:145], v[104:105], v[146:147], v[144:145] op_sel_hi:[0, 1, 1]
	v_pk_fma_f32 v[16:17], v[104:105], v[12:13], v[10:11] op_sel_hi:[0, 1, 1]
	s_waitcnt vmcnt(8)
	v_lshlrev_b32_e32 v10, 16, v38
	v_and_b32_e32 v11, 0xffff0000, v38
	v_lshlrev_b32_e32 v20, 16, v40
	v_and_b32_e32 v21, 0xffff0000, v40
	v_lshlrev_b32_e32 v22, 16, v41
	v_and_b32_e32 v23, 0xffff0000, v41
	v_pk_fma_f32 v[10:11], v[86:87], v[10:11], v[144:145] op_sel_hi:[0, 1, 1]
	s_waitcnt vmcnt(7)
	v_lshlrev_b32_e32 v40, 16, v42
	v_and_b32_e32 v41, 0xffff0000, v42
	s_waitcnt vmcnt(6)
	v_lshlrev_b32_e32 v24, 16, v46
	v_and_b32_e32 v25, 0xffff0000, v46
	v_pk_fma_f32 v[10:11], v[88:89], v[40:41], v[10:11] op_sel_hi:[0, 1, 1]
	s_waitcnt vmcnt(5)
	v_lshlrev_b32_e32 v32, 16, v50
	v_and_b32_e32 v33, 0xffff0000, v50
	v_pk_fma_f32 v[10:11], v[90:91], v[24:25], v[10:11] op_sel_hi:[0, 1, 1]
	v_pk_fma_f32 v[10:11], v[94:95], v[32:33], v[10:11] op_sel_hi:[0, 1, 1]
	s_waitcnt vmcnt(4)
	v_lshlrev_b32_e32 v24, 16, v54
	v_and_b32_e32 v25, 0xffff0000, v54
	v_lshlrev_b32_e32 v12, 16, v39
	v_and_b32_e32 v13, 0xffff0000, v39
	v_pk_fma_f32 v[10:11], v[102:103], v[24:25], v[10:11] op_sel_hi:[0, 1, 1]
	s_waitcnt vmcnt(3)
	v_lshlrev_b32_e32 v24, 16, v58
	v_and_b32_e32 v25, 0xffff0000, v58
	v_pk_fma_f32 v[10:11], v[100:101], v[24:25], v[10:11] op_sel_hi:[0, 1, 1]
	s_waitcnt vmcnt(2)
	v_lshlrev_b32_e32 v24, 16, v62
	v_and_b32_e32 v25, 0xffff0000, v62
	v_pk_fma_f32 v[12:13], v[86:87], v[12:13], v[14:15] op_sel_hi:[0, 1, 1]
	v_lshlrev_b32_e32 v14, 16, v43
	v_and_b32_e32 v15, 0xffff0000, v43
	v_lshlrev_b32_e32 v26, 16, v47
	v_and_b32_e32 v27, 0xffff0000, v47
	v_pk_fma_f32 v[10:11], v[98:99], v[24:25], v[10:11] op_sel_hi:[0, 1, 1]
	s_waitcnt vmcnt(1)
	v_lshlrev_b32_e32 v24, 16, v66
	v_and_b32_e32 v25, 0xffff0000, v66
	v_pk_fma_f32 v[12:13], v[88:89], v[14:15], v[12:13] op_sel_hi:[0, 1, 1]
	v_lshlrev_b32_e32 v34, 16, v51
	v_and_b32_e32 v35, 0xffff0000, v51
	v_pk_fma_f32 v[10:11], v[96:97], v[24:25], v[10:11] op_sel_hi:[0, 1, 1]
	s_waitcnt vmcnt(0)
	v_lshlrev_b32_e32 v24, 16, v140
	v_and_b32_e32 v25, 0xffff0000, v140
	v_pk_fma_f32 v[12:13], v[90:91], v[26:27], v[12:13] op_sel_hi:[0, 1, 1]
	v_pk_fma_f32 v[10:11], v[92:93], v[24:25], v[10:11] op_sel_hi:[0, 1, 1]
	v_pk_fma_f32 v[12:13], v[94:95], v[34:35], v[12:13] op_sel_hi:[0, 1, 1]
	v_lshlrev_b32_e32 v24, 16, v55
	v_and_b32_e32 v25, 0xffff0000, v55
	v_pk_fma_f32 v[12:13], v[102:103], v[24:25], v[12:13] op_sel_hi:[0, 1, 1]
	v_lshlrev_b32_e32 v24, 16, v59
	v_and_b32_e32 v25, 0xffff0000, v59
	v_pk_fma_f32 v[12:13], v[100:101], v[24:25], v[12:13] op_sel_hi:[0, 1, 1]
	v_lshlrev_b32_e32 v24, 16, v63
	v_and_b32_e32 v25, 0xffff0000, v63
	v_pk_fma_f32 v[12:13], v[98:99], v[24:25], v[12:13] op_sel_hi:[0, 1, 1]
	v_lshlrev_b32_e32 v24, 16, v67
	v_and_b32_e32 v25, 0xffff0000, v67
	v_pk_fma_f32 v[12:13], v[96:97], v[24:25], v[12:13] op_sel_hi:[0, 1, 1]
	v_lshlrev_b32_e32 v24, 16, v141
	v_and_b32_e32 v25, 0xffff0000, v141
	v_pk_fma_f32 v[12:13], v[92:93], v[24:25], v[12:13] op_sel_hi:[0, 1, 1]
	v_pk_fma_f32 v[10:11], v[82:83], v[10:11], v[40:41] op_sel_hi:[0, 1, 1] neg_lo:[0, 0, 1] neg_hi:[0, 0, 1]
	v_pk_fma_f32 v[12:13], v[82:83], v[12:13], v[14:15] op_sel_hi:[0, 1, 1] neg_lo:[0, 0, 1] neg_hi:[0, 0, 1]
	v_cvt_pk_bf16_f32 v10, v10, v11
	v_cvt_pk_bf16_f32 v11, v12, v13
	v_pk_fma_f32 v[12:13], v[86:87], v[20:21], v[18:19] op_sel_hi:[0, 1, 1]
	v_lshlrev_b32_e32 v14, 16, v44
	v_and_b32_e32 v15, 0xffff0000, v44
	v_lshlrev_b32_e32 v28, 16, v48
	v_and_b32_e32 v29, 0xffff0000, v48
	v_pk_fma_f32 v[12:13], v[88:89], v[14:15], v[12:13] op_sel_hi:[0, 1, 1]
	v_lshlrev_b32_e32 v36, 16, v52
	v_and_b32_e32 v37, 0xffff0000, v52
	v_pk_fma_f32 v[12:13], v[90:91], v[28:29], v[12:13] op_sel_hi:[0, 1, 1]
	v_pk_fma_f32 v[12:13], v[94:95], v[36:37], v[12:13] op_sel_hi:[0, 1, 1]
	v_lshlrev_b32_e32 v18, 16, v56
	v_and_b32_e32 v19, 0xffff0000, v56
	v_pk_fma_f32 v[12:13], v[102:103], v[18:19], v[12:13] op_sel_hi:[0, 1, 1]
	v_lshlrev_b32_e32 v18, 16, v60
	v_and_b32_e32 v19, 0xffff0000, v60
	v_pk_fma_f32 v[12:13], v[100:101], v[18:19], v[12:13] op_sel_hi:[0, 1, 1]
	v_lshlrev_b32_e32 v18, 16, v64
	v_and_b32_e32 v19, 0xffff0000, v64
	v_pk_fma_f32 v[12:13], v[98:99], v[18:19], v[12:13] op_sel_hi:[0, 1, 1]
	v_lshlrev_b32_e32 v18, 16, v68
	v_and_b32_e32 v19, 0xffff0000, v68
	v_pk_fma_f32 v[12:13], v[96:97], v[18:19], v[12:13] op_sel_hi:[0, 1, 1]
	v_lshlrev_b32_e32 v18, 16, v142
	v_and_b32_e32 v19, 0xffff0000, v142
	v_pk_fma_f32 v[12:13], v[92:93], v[18:19], v[12:13] op_sel_hi:[0, 1, 1]
	v_pk_fma_f32 v[12:13], v[82:83], v[12:13], v[14:15] op_sel_hi:[0, 1, 1] neg_lo:[0, 0, 1] neg_hi:[0, 0, 1]
	v_pk_fma_f32 v[14:15], v[86:87], v[22:23], v[16:17] op_sel_hi:[0, 1, 1]
	v_lshlrev_b32_e32 v16, 16, v45
	v_and_b32_e32 v17, 0xffff0000, v45
	v_lshlrev_b32_e32 v30, 16, v49
	v_and_b32_e32 v31, 0xffff0000, v49
	v_pk_fma_f32 v[14:15], v[88:89], v[16:17], v[14:15] op_sel_hi:[0, 1, 1]
	v_lshlrev_b32_e32 v38, 16, v53
	v_and_b32_e32 v39, 0xffff0000, v53
	v_pk_fma_f32 v[14:15], v[90:91], v[30:31], v[14:15] op_sel_hi:[0, 1, 1]
	v_pk_fma_f32 v[14:15], v[94:95], v[38:39], v[14:15] op_sel_hi:[0, 1, 1]
	v_lshlrev_b32_e32 v18, 16, v57
	v_and_b32_e32 v19, 0xffff0000, v57
	v_pk_fma_f32 v[14:15], v[102:103], v[18:19], v[14:15] op_sel_hi:[0, 1, 1]
	v_lshlrev_b32_e32 v18, 16, v61
	v_and_b32_e32 v19, 0xffff0000, v61
	v_pk_fma_f32 v[14:15], v[100:101], v[18:19], v[14:15] op_sel_hi:[0, 1, 1]
	v_lshlrev_b32_e32 v18, 16, v65
	v_and_b32_e32 v19, 0xffff0000, v65
	v_pk_fma_f32 v[14:15], v[98:99], v[18:19], v[14:15] op_sel_hi:[0, 1, 1]
	v_lshlrev_b32_e32 v18, 16, v69
	v_and_b32_e32 v19, 0xffff0000, v69
	v_pk_fma_f32 v[14:15], v[96:97], v[18:19], v[14:15] op_sel_hi:[0, 1, 1]
	v_lshlrev_b32_e32 v18, 16, v143
	v_and_b32_e32 v19, 0xffff0000, v143
	v_pk_fma_f32 v[14:15], v[92:93], v[18:19], v[14:15] op_sel_hi:[0, 1, 1]
	v_pk_fma_f32 v[14:15], v[82:83], v[14:15], v[16:17] op_sel_hi:[0, 1, 1] neg_lo:[0, 0, 1] neg_hi:[0, 0, 1]
	v_cvt_pk_bf16_f32 v12, v12, v13
	v_cvt_pk_bf16_f32 v13, v14, v15
	global_load_dwordx4 v[14:17], v[126:127], off offset:960
	global_load_dwordx4 v[18:21], v[128:129], off offset:960
	global_load_dwordx4 v[22:25], v[130:131], off offset:960
	global_load_dwordx4 v[26:29], v[132:133], off offset:960
	global_load_dwordx4 v[30:33], v[134:135], off offset:960
	global_load_dwordx4 v[34:37], v[136:137], off offset:960
	global_load_dwordx4 v[38:41], v[138:139], off offset:960
	global_load_dwordx4 v[50:53], v[122:123], off offset:960
	global_load_dwordx4 v[42:45], v[124:125], off offset:960
	global_load_dwordx4 v[62:65], v[76:77], off offset:960
	s_nop 0
	global_load_dwordx4 v[74:77], v[74:75], off offset:960
	s_nop 0
	global_load_dwordx4 v[46:49], v[70:71], off offset:960
	global_load_dwordx4 v[54:57], v[72:73], off offset:960
	global_load_dwordx4 v[58:61], v[116:117], off offset:960
	global_load_dwordx4 v[66:69], v[118:119], off offset:960
	s_nop 0
	global_load_dwordx4 v[70:73], v[120:121], off offset:960
	s_waitcnt vmcnt(15)
	v_lshlrev_b32_e32 v116, 16, v14
	v_and_b32_e32 v117, 0xffff0000, v14
	v_lshlrev_b32_e32 v14, 16, v15
	v_and_b32_e32 v15, 0xffff0000, v15
	s_waitcnt vmcnt(14)
	v_lshlrev_b32_e32 v118, 16, v18
	v_and_b32_e32 v119, 0xffff0000, v18
	v_pk_fma_f32 v[14:15], v[84:85], v[14:15], 0 op_sel_hi:[0, 1, 0]
	v_lshlrev_b32_e32 v18, 16, v19
	v_and_b32_e32 v19, 0xffff0000, v19
	v_pk_fma_f32 v[14:15], v[114:115], v[18:19], v[14:15] op_sel_hi:[0, 1, 1]
	s_waitcnt vmcnt(13)
	v_lshlrev_b32_e32 v18, 16, v23
	v_and_b32_e32 v19, 0xffff0000, v23
	v_pk_fma_f32 v[14:15], v[112:113], v[18:19], v[14:15] op_sel_hi:[0, 1, 1]
	s_waitcnt vmcnt(12)
	v_lshlrev_b32_e32 v18, 16, v27
	v_and_b32_e32 v19, 0xffff0000, v27
	v_pk_fma_f32 v[14:15], v[110:111], v[18:19], v[14:15] op_sel_hi:[0, 1, 1]
	s_waitcnt vmcnt(11)
	v_lshlrev_b32_e32 v18, 16, v31
	v_and_b32_e32 v19, 0xffff0000, v31
	v_pk_fma_f32 v[14:15], v[108:109], v[18:19], v[14:15] op_sel_hi:[0, 1, 1]
	s_waitcnt vmcnt(10)
	v_lshlrev_b32_e32 v18, 16, v35
	v_and_b32_e32 v19, 0xffff0000, v35
	v_pk_fma_f32 v[14:15], v[106:107], v[18:19], v[14:15] op_sel_hi:[0, 1, 1]
	s_waitcnt vmcnt(9)
	v_lshlrev_b32_e32 v18, 16, v39
	v_and_b32_e32 v19, 0xffff0000, v39
	v_pk_fma_f32 v[116:117], v[84:85], v[116:117], 0 op_sel_hi:[0, 1, 0]
	v_pk_fma_f32 v[18:19], v[104:105], v[18:19], v[14:15] op_sel_hi:[0, 1, 1]
	v_lshlrev_b32_e32 v14, 16, v16
	v_and_b32_e32 v15, 0xffff0000, v16
	v_pk_fma_f32 v[116:117], v[114:115], v[118:119], v[116:117] op_sel_hi:[0, 1, 1]
	v_lshlrev_b32_e32 v118, 16, v22
	v_and_b32_e32 v119, 0xffff0000, v22
	v_pk_fma_f32 v[14:15], v[84:85], v[14:15], 0 op_sel_hi:[0, 1, 0]
	v_lshlrev_b32_e32 v22, 16, v20
	v_and_b32_e32 v23, 0xffff0000, v20
	v_pk_fma_f32 v[14:15], v[114:115], v[22:23], v[14:15] op_sel_hi:[0, 1, 1]
	v_lshlrev_b32_e32 v22, 16, v24
	v_and_b32_e32 v23, 0xffff0000, v24
	v_pk_fma_f32 v[14:15], v[112:113], v[22:23], v[14:15] op_sel_hi:[0, 1, 1]
	v_lshlrev_b32_e32 v22, 16, v28
	v_and_b32_e32 v23, 0xffff0000, v28
	v_pk_fma_f32 v[14:15], v[110:111], v[22:23], v[14:15] op_sel_hi:[0, 1, 1]
	v_lshlrev_b32_e32 v22, 16, v32
	v_and_b32_e32 v23, 0xffff0000, v32
	v_pk_fma_f32 v[14:15], v[108:109], v[22:23], v[14:15] op_sel_hi:[0, 1, 1]
	v_lshlrev_b32_e32 v22, 16, v36
	v_and_b32_e32 v23, 0xffff0000, v36
	v_pk_fma_f32 v[14:15], v[106:107], v[22:23], v[14:15] op_sel_hi:[0, 1, 1]
	v_lshlrev_b32_e32 v22, 16, v40
	v_and_b32_e32 v23, 0xffff0000, v40
	v_pk_fma_f32 v[22:23], v[104:105], v[22:23], v[14:15] op_sel_hi:[0, 1, 1]
	v_lshlrev_b32_e32 v14, 16, v17
	v_and_b32_e32 v15, 0xffff0000, v17
	v_pk_fma_f32 v[14:15], v[84:85], v[14:15], 0 op_sel_hi:[0, 1, 0]
	v_lshlrev_b32_e32 v16, 16, v21
	v_and_b32_e32 v17, 0xffff0000, v21
	v_pk_fma_f32 v[14:15], v[114:115], v[16:17], v[14:15] op_sel_hi:[0, 1, 1]
	v_lshlrev_b32_e32 v16, 16, v25
	v_and_b32_e32 v17, 0xffff0000, v25
	v_pk_fma_f32 v[116:117], v[112:113], v[118:119], v[116:117] op_sel_hi:[0, 1, 1]
	v_lshlrev_b32_e32 v118, 16, v26
	v_and_b32_e32 v119, 0xffff0000, v26
	v_pk_fma_f32 v[14:15], v[112:113], v[16:17], v[14:15] op_sel_hi:[0, 1, 1]
	v_lshlrev_b32_e32 v16, 16, v29
	v_and_b32_e32 v17, 0xffff0000, v29
	v_pk_fma_f32 v[116:117], v[110:111], v[118:119], v[116:117] op_sel_hi:[0, 1, 1]
	v_lshlrev_b32_e32 v118, 16, v30
	v_and_b32_e32 v119, 0xffff0000, v30
	v_pk_fma_f32 v[14:15], v[110:111], v[16:17], v[14:15] op_sel_hi:[0, 1, 1]
	v_lshlrev_b32_e32 v16, 16, v33
	v_and_b32_e32 v17, 0xffff0000, v33
	v_pk_fma_f32 v[116:117], v[108:109], v[118:119], v[116:117] op_sel_hi:[0, 1, 1]
	v_lshlrev_b32_e32 v118, 16, v34
	v_and_b32_e32 v119, 0xffff0000, v34
	v_pk_fma_f32 v[14:15], v[108:109], v[16:17], v[14:15] op_sel_hi:[0, 1, 1]
	v_lshlrev_b32_e32 v16, 16, v37
	v_and_b32_e32 v17, 0xffff0000, v37
	v_pk_fma_f32 v[116:117], v[106:107], v[118:119], v[116:117] op_sel_hi:[0, 1, 1]
	v_lshlrev_b32_e32 v118, 16, v38
	v_and_b32_e32 v119, 0xffff0000, v38
	v_pk_fma_f32 v[14:15], v[106:107], v[16:17], v[14:15] op_sel_hi:[0, 1, 1]
	v_lshlrev_b32_e32 v16, 16, v41
	v_and_b32_e32 v17, 0xffff0000, v41
	v_pk_fma_f32 v[116:117], v[104:105], v[118:119], v[116:117] op_sel_hi:[0, 1, 1]
	v_pk_fma_f32 v[20:21], v[104:105], v[16:17], v[14:15] op_sel_hi:[0, 1, 1]
	s_waitcnt vmcnt(8)
	v_lshlrev_b32_e32 v14, 16, v50
	v_and_b32_e32 v15, 0xffff0000, v50
	v_lshlrev_b32_e32 v24, 16, v52
	v_and_b32_e32 v25, 0xffff0000, v52
	v_lshlrev_b32_e32 v26, 16, v53
	v_and_b32_e32 v27, 0xffff0000, v53
	v_pk_fma_f32 v[14:15], v[86:87], v[14:15], v[116:117] op_sel_hi:[0, 1, 1]
	s_waitcnt vmcnt(7)
	v_lshlrev_b32_e32 v52, 16, v42
	v_and_b32_e32 v53, 0xffff0000, v42
	s_waitcnt vmcnt(6)
	v_lshlrev_b32_e32 v28, 16, v62
	v_and_b32_e32 v29, 0xffff0000, v62
	v_pk_fma_f32 v[14:15], v[88:89], v[52:53], v[14:15] op_sel_hi:[0, 1, 1]
	s_waitcnt vmcnt(5)
	v_lshlrev_b32_e32 v36, 16, v74
	v_and_b32_e32 v37, 0xffff0000, v74
	v_pk_fma_f32 v[14:15], v[90:91], v[28:29], v[14:15] op_sel_hi:[0, 1, 1]
	v_pk_fma_f32 v[14:15], v[94:95], v[36:37], v[14:15] op_sel_hi:[0, 1, 1]
	s_waitcnt vmcnt(4)
	v_lshlrev_b32_e32 v28, 16, v46
	v_and_b32_e32 v29, 0xffff0000, v46
	v_lshlrev_b32_e32 v16, 16, v51
	v_and_b32_e32 v17, 0xffff0000, v51
	v_pk_fma_f32 v[14:15], v[102:103], v[28:29], v[14:15] op_sel_hi:[0, 1, 1]
	s_waitcnt vmcnt(3)
	v_lshlrev_b32_e32 v28, 16, v54
	v_and_b32_e32 v29, 0xffff0000, v54
	v_pk_fma_f32 v[14:15], v[100:101], v[28:29], v[14:15] op_sel_hi:[0, 1, 1]
	s_waitcnt vmcnt(2)
	v_lshlrev_b32_e32 v28, 16, v58
	v_and_b32_e32 v29, 0xffff0000, v58
	v_pk_fma_f32 v[16:17], v[86:87], v[16:17], v[18:19] op_sel_hi:[0, 1, 1]
	v_lshlrev_b32_e32 v18, 16, v43
	v_and_b32_e32 v19, 0xffff0000, v43
	v_lshlrev_b32_e32 v30, 16, v63
	v_and_b32_e32 v31, 0xffff0000, v63
	v_pk_fma_f32 v[14:15], v[98:99], v[28:29], v[14:15] op_sel_hi:[0, 1, 1]
	s_waitcnt vmcnt(1)
	v_lshlrev_b32_e32 v28, 16, v66
	v_and_b32_e32 v29, 0xffff0000, v66
	v_pk_fma_f32 v[16:17], v[88:89], v[18:19], v[16:17] op_sel_hi:[0, 1, 1]
	v_lshlrev_b32_e32 v38, 16, v75
	v_and_b32_e32 v39, 0xffff0000, v75
	v_pk_fma_f32 v[14:15], v[96:97], v[28:29], v[14:15] op_sel_hi:[0, 1, 1]
	s_waitcnt vmcnt(0)
	v_lshlrev_b32_e32 v28, 16, v70
	v_and_b32_e32 v29, 0xffff0000, v70
	v_pk_fma_f32 v[16:17], v[90:91], v[30:31], v[16:17] op_sel_hi:[0, 1, 1]
	v_pk_fma_f32 v[14:15], v[92:93], v[28:29], v[14:15] op_sel_hi:[0, 1, 1]
	v_pk_fma_f32 v[16:17], v[94:95], v[38:39], v[16:17] op_sel_hi:[0, 1, 1]
	v_lshlrev_b32_e32 v28, 16, v47
	v_and_b32_e32 v29, 0xffff0000, v47
	v_pk_fma_f32 v[16:17], v[102:103], v[28:29], v[16:17] op_sel_hi:[0, 1, 1]
	v_lshlrev_b32_e32 v28, 16, v55
	v_and_b32_e32 v29, 0xffff0000, v55
	v_pk_fma_f32 v[16:17], v[100:101], v[28:29], v[16:17] op_sel_hi:[0, 1, 1]
	v_lshlrev_b32_e32 v28, 16, v59
	v_and_b32_e32 v29, 0xffff0000, v59
	v_pk_fma_f32 v[16:17], v[98:99], v[28:29], v[16:17] op_sel_hi:[0, 1, 1]
	v_lshlrev_b32_e32 v28, 16, v67
	v_and_b32_e32 v29, 0xffff0000, v67
	v_pk_fma_f32 v[16:17], v[96:97], v[28:29], v[16:17] op_sel_hi:[0, 1, 1]
	v_lshlrev_b32_e32 v28, 16, v71
	v_and_b32_e32 v29, 0xffff0000, v71
	v_pk_fma_f32 v[16:17], v[92:93], v[28:29], v[16:17] op_sel_hi:[0, 1, 1]
	v_pk_fma_f32 v[14:15], v[82:83], v[14:15], v[52:53] op_sel_hi:[0, 1, 1] neg_lo:[0, 0, 1] neg_hi:[0, 0, 1]
	v_pk_fma_f32 v[16:17], v[82:83], v[16:17], v[18:19] op_sel_hi:[0, 1, 1] neg_lo:[0, 0, 1] neg_hi:[0, 0, 1]
	v_cvt_pk_bf16_f32 v14, v14, v15
	v_cvt_pk_bf16_f32 v15, v16, v17
	v_pk_fma_f32 v[16:17], v[86:87], v[24:25], v[22:23] op_sel_hi:[0, 1, 1]
	v_lshlrev_b32_e32 v18, 16, v44
	v_and_b32_e32 v19, 0xffff0000, v44
	v_lshlrev_b32_e32 v32, 16, v64
	v_and_b32_e32 v33, 0xffff0000, v64
	v_pk_fma_f32 v[16:17], v[88:89], v[18:19], v[16:17] op_sel_hi:[0, 1, 1]
	v_lshlrev_b32_e32 v40, 16, v76
	v_and_b32_e32 v41, 0xffff0000, v76
	v_pk_fma_f32 v[16:17], v[90:91], v[32:33], v[16:17] op_sel_hi:[0, 1, 1]
	v_pk_fma_f32 v[16:17], v[94:95], v[40:41], v[16:17] op_sel_hi:[0, 1, 1]
	v_lshlrev_b32_e32 v22, 16, v48
	v_and_b32_e32 v23, 0xffff0000, v48
	v_pk_fma_f32 v[16:17], v[102:103], v[22:23], v[16:17] op_sel_hi:[0, 1, 1]
	v_lshlrev_b32_e32 v22, 16, v56
	v_and_b32_e32 v23, 0xffff0000, v56
	v_pk_fma_f32 v[16:17], v[100:101], v[22:23], v[16:17] op_sel_hi:[0, 1, 1]
	v_lshlrev_b32_e32 v22, 16, v60
	v_and_b32_e32 v23, 0xffff0000, v60
	v_pk_fma_f32 v[16:17], v[98:99], v[22:23], v[16:17] op_sel_hi:[0, 1, 1]
	v_lshlrev_b32_e32 v22, 16, v68
	v_and_b32_e32 v23, 0xffff0000, v68
	v_pk_fma_f32 v[16:17], v[96:97], v[22:23], v[16:17] op_sel_hi:[0, 1, 1]
	v_lshlrev_b32_e32 v22, 16, v72
	v_and_b32_e32 v23, 0xffff0000, v72
	v_pk_fma_f32 v[16:17], v[92:93], v[22:23], v[16:17] op_sel_hi:[0, 1, 1]
	v_pk_fma_f32 v[16:17], v[82:83], v[16:17], v[18:19] op_sel_hi:[0, 1, 1] neg_lo:[0, 0, 1] neg_hi:[0, 0, 1]
	v_pk_fma_f32 v[18:19], v[86:87], v[26:27], v[20:21] op_sel_hi:[0, 1, 1]
	v_lshlrev_b32_e32 v20, 16, v45
	v_and_b32_e32 v21, 0xffff0000, v45
	v_lshlrev_b32_e32 v34, 16, v65
	v_and_b32_e32 v35, 0xffff0000, v65
	v_pk_fma_f32 v[18:19], v[88:89], v[20:21], v[18:19] op_sel_hi:[0, 1, 1]
	v_lshlrev_b32_e32 v50, 16, v77
	v_and_b32_e32 v51, 0xffff0000, v77
	v_pk_fma_f32 v[18:19], v[90:91], v[34:35], v[18:19] op_sel_hi:[0, 1, 1]
	v_pk_fma_f32 v[18:19], v[94:95], v[50:51], v[18:19] op_sel_hi:[0, 1, 1]
	v_lshlrev_b32_e32 v22, 16, v49
	v_and_b32_e32 v23, 0xffff0000, v49
	v_pk_fma_f32 v[18:19], v[102:103], v[22:23], v[18:19] op_sel_hi:[0, 1, 1]
	v_lshlrev_b32_e32 v22, 16, v57
	v_and_b32_e32 v23, 0xffff0000, v57
	v_pk_fma_f32 v[18:19], v[100:101], v[22:23], v[18:19] op_sel_hi:[0, 1, 1]
	v_lshlrev_b32_e32 v22, 16, v61
	v_and_b32_e32 v23, 0xffff0000, v61
	v_pk_fma_f32 v[18:19], v[98:99], v[22:23], v[18:19] op_sel_hi:[0, 1, 1]
	v_lshlrev_b32_e32 v22, 16, v69
	v_and_b32_e32 v23, 0xffff0000, v69
	v_pk_fma_f32 v[18:19], v[96:97], v[22:23], v[18:19] op_sel_hi:[0, 1, 1]
	v_lshlrev_b32_e32 v22, 16, v73
	v_and_b32_e32 v23, 0xffff0000, v73
	v_pk_fma_f32 v[18:19], v[92:93], v[22:23], v[18:19] op_sel_hi:[0, 1, 1]
	v_pk_fma_f32 v[18:19], v[82:83], v[18:19], v[20:21] op_sel_hi:[0, 1, 1] neg_lo:[0, 0, 1] neg_hi:[0, 0, 1]
	v_lshlrev_b64 v[20:21], 11, v[80:81]
	v_cvt_pk_bf16_f32 v16, v16, v17
	v_cvt_pk_bf16_f32 v17, v18, v19
	v_lshl_add_u64 v[18:19], s[74:75], 0, v[78:79]
	v_lshl_add_u64 v[30:31], s[84:85], 0, v[20:21]
	v_lshlrev_b32_e32 v20, 8, v85
	v_mov_b32_e32 v21, v1
	v_lshl_add_u64 v[28:29], v[18:19], 0, v[20:21]
	v_add_co_u32_e32 v56, vcc, 0x1000, v28
	s_nop 1
	v_addc_co_u32_e32 v57, vcc, 0, v29, vcc
	v_add_co_u32_e32 v58, vcc, 0x3000, v28
	s_nop 1
	v_addc_co_u32_e32 v59, vcc, 0, v29, vcc
	v_add_co_u32_e32 v60, vcc, 0x5000, v28
	s_nop 1
	v_addc_co_u32_e32 v61, vcc, 0, v29, vcc
	v_add_co_u32_e32 v62, vcc, 0x7000, v28
	s_nop 1
	v_addc_co_u32_e32 v63, vcc, 0, v29, vcc
	v_and_b32_e32 v56, 15, v209
	v_bfe_u32 v57, v209, 4, 2
	v_mul_u32_u24_e32 v56, 0x110, v56
	v_lshl_add_u32 v56, v57, 4, v56
	v_add_u32_e32 v56, 0x19800, v56
	v_add_u32_e32 v57, 0x22000, v78
	ds_read_b128 v[100:103], v57 offset:1536
	ds_read_b128 v[120:123], v57 offset:1600
	ds_read_b128 v[140:143], v57 offset:1664
	ds_read_b128 v[160:163], v57 offset:1728
	ds_read_b128 v[180:183], v57 offset:1792
	ds_read_b128 v[200:203], v57 offset:1856
	ds_read_b128 v[234:237], v57 offset:1920
	ds_read_b128 v[84:87], v56 offset:0
	ds_read_b128 v[88:91], v56 offset:64
	ds_read_b128 v[92:95], v56 offset:128
	ds_read_b128 v[96:99], v56 offset:192
	ds_read_b128 v[104:107], v56 offset:4352
	ds_read_b128 v[108:111], v56 offset:4416
	ds_read_b128 v[112:115], v56 offset:4480
	ds_read_b128 v[116:119], v56 offset:4544
	s_nop 0
	s_nop 0
	s_waitcnt lgkmcnt(4)
	v_mfma_f32_16x16x32_bf16 v[18:21], v[84:87], v[2:5], 0
	v_lshl_add_u64 v[26:27], v[30:31], 0, s[0:1]
	s_movk_i32 s0, 0x1000
	v_mfma_f32_16x16x32_bf16 v[18:21], v[88:91], v[6:9], v[18:21]
	s_nop 0
	v_mfma_f32_16x16x32_bf16 v[18:21], v[92:95], v[10:13], v[18:21]
	s_nop 0
	v_mfma_f32_16x16x32_bf16 v[18:21], v[96:99], v[14:17], v[18:21]
	ds_read_b128 v[124:127], v56 offset:8704
	ds_read_b128 v[128:131], v56 offset:8768
	ds_read_b128 v[132:135], v56 offset:8832
	ds_read_b128 v[136:139], v56 offset:8896
	s_nop 0
	s_nop 0
	s_nop 5
	v_pk_mul_f32 v[20:21], v[20:21], v[102:103]
	v_add_co_u32_e32 v24, vcc, s0, v28
	v_pk_mul_f32 v[18:19], v[18:19], v[100:101]
	s_nop 0
	v_addc_co_u32_e32 v25, vcc, 0, v29, vcc
	s_movk_i32 s0, 0x2000
	v_cvt_pk_bf16_f32 v22, v18, v19
	v_cvt_pk_bf16_f32 v23, v20, v21
	v_lshl_add_u64 v[18:19], v[30:31], 0, v[0:1]
	v_add_co_u32_e32 v34, vcc, s0, v28
	global_store_dwordx2 v[18:19], v[22:23], off offset:1792
	s_nop 0
	v_addc_co_u32_e32 v35, vcc, 0, v29, vcc
	s_nop 0
	s_nop 0
	s_waitcnt lgkmcnt(4)
	v_mfma_f32_16x16x32_bf16 v[20:23], v[104:107], v[2:5], 0
	s_movk_i32 s0, 0x3000
	v_mov_b32_e32 v0, 0x1f0
	v_lshl_or_b32 v0, v83, 2, v0
	v_mfma_f32_16x16x32_bf16 v[20:23], v[108:111], v[6:9], v[20:23]
	s_nop 0
	v_mfma_f32_16x16x32_bf16 v[20:23], v[112:115], v[10:13], v[20:23]
	s_nop 0
	v_add_co_u32_e32 v24, vcc, s0, v28
	v_mfma_f32_16x16x32_bf16 v[20:23], v[116:119], v[14:17], v[20:23]
	ds_read_b128 v[144:147], v56 offset:13056
	ds_read_b128 v[148:151], v56 offset:13120
	ds_read_b128 v[152:155], v56 offset:13184
	ds_read_b128 v[156:159], v56 offset:13248
	s_nop 0
	v_addc_co_u32_e32 v25, vcc, 0, v29, vcc
	s_movk_i32 s0, 0x4000
	s_nop 0
	s_nop 3
	v_pk_mul_f32 v[22:23], v[22:23], v[122:123]
	v_pk_mul_f32 v[20:21], v[20:21], v[120:121]
	s_nop 0
	v_cvt_pk_bf16_f32 v20, v20, v21
	v_cvt_pk_bf16_f32 v21, v22, v23
	global_store_dwordx2 v[18:19], v[20:21], off offset:1824
	s_nop 0
	s_nop 0
	s_nop 0
	s_waitcnt lgkmcnt(4)
	v_mfma_f32_16x16x32_bf16 v[20:23], v[124:127], v[2:5], 0
	v_mfma_f32_16x16x32_bf16 v[20:23], v[128:131], v[6:9], v[20:23]
	s_nop 0
	v_mfma_f32_16x16x32_bf16 v[20:23], v[132:135], v[10:13], v[20:23]
	s_nop 0
	v_add_co_u32_e32 v34, vcc, s0, v28
	v_mfma_f32_16x16x32_bf16 v[20:23], v[136:139], v[14:17], v[20:23]
	ds_read_b128 v[164:167], v56 offset:17408
	ds_read_b128 v[168:171], v56 offset:17472
	ds_read_b128 v[172:175], v56 offset:17536
	ds_read_b128 v[176:179], v56 offset:17600
	s_nop 0
	v_addc_co_u32_e32 v35, vcc, 0, v29, vcc
	s_movk_i32 s0, 0x5000
	s_nop 0
	s_nop 3
	v_pk_mul_f32 v[22:23], v[22:23], v[142:143]
	v_pk_mul_f32 v[20:21], v[20:21], v[140:141]
	s_nop 0
	v_cvt_pk_bf16_f32 v20, v20, v21
	v_cvt_pk_bf16_f32 v21, v22, v23
	global_store_dwordx2 v[18:19], v[20:21], off offset:1856
	s_nop 0
	s_nop 0
	s_nop 0
	s_waitcnt lgkmcnt(4)
	v_mfma_f32_16x16x32_bf16 v[20:23], v[144:147], v[2:5], 0
	v_mfma_f32_16x16x32_bf16 v[20:23], v[148:151], v[6:9], v[20:23]
	s_nop 0
	v_mfma_f32_16x16x32_bf16 v[20:23], v[152:155], v[10:13], v[20:23]
	s_nop 0
	v_add_co_u32_e32 v24, vcc, s0, v28
	v_mfma_f32_16x16x32_bf16 v[20:23], v[156:159], v[14:17], v[20:23]
	ds_read_b128 v[184:187], v56 offset:21760
	ds_read_b128 v[188:191], v56 offset:21824
	ds_read_b128 v[192:195], v56 offset:21888
	ds_read_b128 v[196:199], v56 offset:21952
	s_nop 0
	v_addc_co_u32_e32 v25, vcc, 0, v29, vcc
	s_movk_i32 s0, 0x6000
	s_nop 0
	s_nop 3
	v_pk_mul_f32 v[22:23], v[22:23], v[162:163]
	v_pk_mul_f32 v[20:21], v[20:21], v[160:161]
	s_nop 0
	v_cvt_pk_bf16_f32 v20, v20, v21
	v_cvt_pk_bf16_f32 v21, v22, v23
	global_store_dwordx2 v[18:19], v[20:21], off offset:1888
	s_nop 0
	s_nop 0
	s_nop 0
	s_waitcnt lgkmcnt(4)
	v_mfma_f32_16x16x32_bf16 v[20:23], v[164:167], v[2:5], 0
	v_mfma_f32_16x16x32_bf16 v[20:23], v[168:171], v[6:9], v[20:23]
	s_nop 0
	v_mfma_f32_16x16x32_bf16 v[20:23], v[172:175], v[10:13], v[20:23]
	s_nop 0
	v_add_co_u32_e32 v34, vcc, s0, v28
	v_mfma_f32_16x16x32_bf16 v[20:23], v[176:179], v[14:17], v[20:23]
	ds_read_b128 v[204:207], v56 offset:26112
	ds_read_b128 v[222:225], v56 offset:26176
	ds_read_b128 v[226:229], v56 offset:26240
	ds_read_b128 v[230:233], v56 offset:26304
	s_nop 0
	v_addc_co_u32_e32 v35, vcc, 0, v29, vcc
	s_nop 0
	s_nop 4
	v_pk_mul_f32 v[22:23], v[22:23], v[182:183]
	v_pk_mul_f32 v[20:21], v[20:21], v[180:181]
	s_nop 0
	v_cvt_pk_bf16_f32 v20, v20, v21
	v_cvt_pk_bf16_f32 v21, v22, v23
	global_store_dwordx2 v[18:19], v[20:21], off offset:1920
	s_nop 0
	s_nop 0
	s_nop 0
	s_waitcnt lgkmcnt(4)
	v_mfma_f32_16x16x32_bf16 v[20:23], v[184:187], v[2:5], 0
	v_mfma_f32_16x16x32_bf16 v[20:23], v[188:191], v[6:9], v[20:23]
	s_nop 0
	v_mfma_f32_16x16x32_bf16 v[20:23], v[192:195], v[10:13], v[20:23]
	s_nop 0
	v_mfma_f32_16x16x32_bf16 v[20:23], v[196:199], v[14:17], v[20:23]
	ds_read_b128 v[238:241], v56 offset:30464
	ds_read_b128 v[242:245], v56 offset:30528
	ds_read_b128 v[246:249], v56 offset:30592
	ds_read_b128 v[52:55], v56 offset:30656
	s_nop 0
	s_nop 0
	s_nop 5
	v_pk_mul_f32 v[22:23], v[22:23], v[202:203]
	v_pk_mul_f32 v[20:21], v[20:21], v[200:201]
	s_nop 0
	v_cvt_pk_bf16_f32 v20, v20, v21
	v_cvt_pk_bf16_f32 v21, v22, v23
	global_store_dwordx2 v[18:19], v[20:21], off offset:1952
	s_nop 0
	s_nop 0
	s_nop 0
	s_waitcnt lgkmcnt(4)
	v_mfma_f32_16x16x32_bf16 v[20:23], v[204:207], v[2:5], 0
	v_mfma_f32_16x16x32_bf16 v[20:23], v[222:225], v[6:9], v[20:23]
	s_nop 0
	v_mfma_f32_16x16x32_bf16 v[20:23], v[226:229], v[10:13], v[20:23]
	s_nop 0
	v_mfma_f32_16x16x32_bf16 v[20:23], v[230:233], v[14:17], v[20:23]
	s_nop 0
	s_nop 0
	s_nop 5
	v_pk_mul_f32 v[22:23], v[22:23], v[236:237]
	v_pk_mul_f32 v[20:21], v[20:21], v[234:235]
	s_nop 0
	v_cvt_pk_bf16_f32 v20, v20, v21
	v_cvt_pk_bf16_f32 v21, v22, v23
	v_add_co_u32_e32 v22, vcc, 0x7000, v28
	global_store_dwordx2 v[18:19], v[20:21], off offset:1984
	s_nop 0
	v_addc_co_u32_e32 v23, vcc, 0, v29, vcc
	s_nop 0
	s_waitcnt lgkmcnt(0)
	v_mfma_f32_16x16x32_bf16 v[2:5], v[238:241], v[2:5], 0
	s_nop 0
	v_mfma_f32_16x16x32_bf16 v[2:5], v[242:245], v[6:9], v[2:5]
	s_nop 0
	v_mfma_f32_16x16x32_bf16 v[2:5], v[246:249], v[10:13], v[2:5]
	s_nop 0
	v_mfma_f32_16x16x32_bf16 v[2:5], v[52:55], v[14:17], v[2:5]
	s_cbranch_execnz .LBB0_579
.LBB0_593:
	v_mov_b32_e32 v0, v209
	v_mov_b32_e32 v29, v1
	v_readfirstlane_b32 s0, v0
	s_ashr_i32 s0, s0, 2
	v_and_b32_e32 v23, 15, v0
	s_nop 1
	v_bfi_b32 v2, -16, s0, v0
	v_add_u32_e32 v20, s59, v2
	s_mov_b32 s0, 0x38e38e39
	v_bfe_u32 v34, v0, 4, 2
	v_mul_hi_i32 v0, v20, s0
	v_lshrrev_b32_e32 v3, 31, v0
	v_ashrrev_i32_e32 v0, 13, v0
	v_add_u32_e32 v0, v0, v3
	v_mul_i32_i24_e32 v0, 0x9000, v0
	v_sub_u32_e32 v0, v20, v0
	s_mov_b32 s0, 0x8000
	v_cmp_gt_i32_e32 vcc, s0, v0
	v_lshlrev_b32_e32 v28, 4, v34
	v_ashrrev_i32_e32 v21, 31, v20
	v_cndmask_b32_e32 v3, v220, v221, vcc
	v_and_b32_e32 v11, v3, v0
	v_cndmask_b32_e32 v10, v217, v210, vcc
	v_add_u32_e32 v3, -1, v11
	v_add_u32_e32 v4, 1, v11
	v_max_i32_e32 v0, 0, v3
	v_min_u32_e32 v4, v4, v10
	v_sub_u32_e32 v0, v4, v0
	v_cvt_f32_i32_e32 v0, v0
	v_div_scale_f32 v4, s[0:1], v0, v0, 1.0
	v_rcp_f32_e32 v5, v4
	v_readlane_b32 s0, v253, 62
	v_readlane_b32 s1, v253, 63
	v_fma_f32 v6, -v4, v5, 1.0
	v_fmac_f32_e32 v5, v6, v5
	v_div_scale_f32 v6, vcc, 1.0, v0, 1.0
	v_mul_f32_e32 v7, v6, v5
	v_fma_f32 v8, -v4, v7, v6
	v_fmac_f32_e32 v7, v8, v5
	v_fma_f32 v4, -v4, v7, v6
	v_div_fmas_f32 v4, v4, v5, v7
	v_cmp_lt_u32_e32 vcc, v3, v10
	v_lshl_add_u64 v[8:9], s[0:1], 0, v[28:29]
	v_lshlrev_b64 v[6:7], 10, v[20:21]
	v_cndmask_b32_e32 v3, v11, v3, vcc
	v_add_u32_e32 v2, v2, v3
	v_sub_u32_e32 v2, v2, v11
	v_add_u32_e32 v2, s59, v2
	v_ashrrev_i32_e32 v3, 31, v2
	v_lshlrev_b64 v[2:3], 10, v[2:3]
	v_lshl_add_u64 v[14:15], v[8:9], 0, v[2:3]
	v_div_fixup_f32 v18, v4, v0, 1.0
	global_load_dwordx4 v[2:5], v[14:15], off
	v_lshl_add_u64 v[16:17], v[8:9], 0, v[6:7]
	global_load_dwordx4 v[6:9], v[16:17], off
	global_load_dwordx4 v[92:95], v[14:15], off offset:64
	global_load_dwordx4 v[96:99], v[16:17], off offset:64
	global_load_dwordx4 v[100:103], v[14:15], off offset:128
	global_load_dwordx4 v[104:107], v[16:17], off offset:128
	global_load_dwordx4 v[108:111], v[14:15], off offset:192
	global_load_dwordx4 v[112:115], v[16:17], off offset:192
	v_cndmask_b32_e64 v22, 0, 1.0, vcc
	v_cmp_lt_u32_e32 vcc, v11, v10
	v_lshlrev_b64 v[20:21], 11, v[20:21]
	s_mov_b64 s[0:1], 0x400
	v_cndmask_b32_e64 v24, 0, 1.0, vcc
	v_lshlrev_b32_e32 v0, 3, v34
	s_waitcnt vmcnt(7)
	v_lshlrev_b32_e32 v10, 16, v2
	v_and_b32_e32 v11, 0xffff0000, v2
	v_pk_fma_f32 v[10:11], v[22:23], v[10:11], 0 op_sel_hi:[0, 1, 0]
	s_waitcnt vmcnt(6)
	v_lshlrev_b32_e32 v12, 16, v6
	v_and_b32_e32 v13, 0xffff0000, v6
	v_pk_fma_f32 v[10:11], v[24:25], v[12:13], v[10:11] op_sel_hi:[0, 1, 1]
	v_pk_fma_f32 v[10:11], v[18:19], v[10:11], v[12:13] op_sel_hi:[0, 1, 1] neg_lo:[0, 0, 1] neg_hi:[0, 0, 1]
	v_cvt_pk_bf16_f32 v2, v10, v11
	v_lshlrev_b32_e32 v10, 16, v3
	v_and_b32_e32 v11, 0xffff0000, v3
	v_pk_fma_f32 v[10:11], v[22:23], v[10:11], 0 op_sel_hi:[0, 1, 0]
	v_lshlrev_b32_e32 v6, 16, v7
	v_and_b32_e32 v7, 0xffff0000, v7
	v_pk_fma_f32 v[10:11], v[24:25], v[6:7], v[10:11] op_sel_hi:[0, 1, 1]
	v_pk_fma_f32 v[6:7], v[18:19], v[10:11], v[6:7] op_sel_hi:[0, 1, 1] neg_lo:[0, 0, 1] neg_hi:[0, 0, 1]
	v_cvt_pk_bf16_f32 v3, v6, v7
	v_lshlrev_b32_e32 v6, 16, v4
	v_and_b32_e32 v7, 0xffff0000, v4
	v_pk_fma_f32 v[6:7], v[22:23], v[6:7], 0 op_sel_hi:[0, 1, 0]
	v_lshlrev_b32_e32 v10, 16, v8
	v_and_b32_e32 v11, 0xffff0000, v8
	v_pk_fma_f32 v[6:7], v[24:25], v[10:11], v[6:7] op_sel_hi:[0, 1, 1]
	v_pk_fma_f32 v[6:7], v[18:19], v[6:7], v[10:11] op_sel_hi:[0, 1, 1] neg_lo:[0, 0, 1] neg_hi:[0, 0, 1]
	v_cvt_pk_bf16_f32 v4, v6, v7
	v_lshlrev_b32_e32 v6, 16, v5
	v_and_b32_e32 v7, 0xffff0000, v5
	v_pk_fma_f32 v[6:7], v[22:23], v[6:7], 0 op_sel_hi:[0, 1, 0]
	v_lshlrev_b32_e32 v8, 16, v9
	v_and_b32_e32 v9, 0xffff0000, v9
	v_pk_fma_f32 v[6:7], v[24:25], v[8:9], v[6:7] op_sel_hi:[0, 1, 1]
	v_pk_fma_f32 v[6:7], v[18:19], v[6:7], v[8:9] op_sel_hi:[0, 1, 1] neg_lo:[0, 0, 1] neg_hi:[0, 0, 1]
	v_cvt_pk_bf16_f32 v5, v6, v7
	s_nop 0
	s_nop 0
	s_waitcnt vmcnt(5)
	v_lshlrev_b32_e32 v26, 16, v92
	v_and_b32_e32 v27, 0xffff0000, v92
	v_pk_fma_f32 v[26:27], v[22:23], v[26:27], 0 op_sel_hi:[0, 1, 0]
	s_waitcnt vmcnt(4)
	v_lshlrev_b32_e32 v30, 16, v96
	v_and_b32_e32 v31, 0xffff0000, v96
	v_pk_fma_f32 v[26:27], v[24:25], v[30:31], v[26:27] op_sel_hi:[0, 1, 1]
	v_pk_fma_f32 v[26:27], v[18:19], v[26:27], v[30:31] op_sel_hi:[0, 1, 1] neg_lo:[0, 0, 1] neg_hi:[0, 0, 1]
	v_cvt_pk_bf16_f32 v6, v26, v27
	v_lshlrev_b32_e32 v26, 16, v93
	v_and_b32_e32 v27, 0xffff0000, v93
	v_pk_fma_f32 v[26:27], v[22:23], v[26:27], 0 op_sel_hi:[0, 1, 0]
	v_lshlrev_b32_e32 v10, 16, v97
	v_and_b32_e32 v11, 0xffff0000, v97
	v_pk_fma_f32 v[26:27], v[24:25], v[10:11], v[26:27] op_sel_hi:[0, 1, 1]
	v_pk_fma_f32 v[10:11], v[18:19], v[26:27], v[10:11] op_sel_hi:[0, 1, 1] neg_lo:[0, 0, 1] neg_hi:[0, 0, 1]
	v_cvt_pk_bf16_f32 v7, v10, v11
	v_lshlrev_b32_e32 v10, 16, v94
	v_and_b32_e32 v11, 0xffff0000, v94
	v_pk_fma_f32 v[10:11], v[22:23], v[10:11], 0 op_sel_hi:[0, 1, 0]
	v_lshlrev_b32_e32 v26, 16, v98
	v_and_b32_e32 v27, 0xffff0000, v98
	v_pk_fma_f32 v[10:11], v[24:25], v[26:27], v[10:11] op_sel_hi:[0, 1, 1]
	v_pk_fma_f32 v[10:11], v[18:19], v[10:11], v[26:27] op_sel_hi:[0, 1, 1] neg_lo:[0, 0, 1] neg_hi:[0, 0, 1]
	v_cvt_pk_bf16_f32 v8, v10, v11
	v_lshlrev_b32_e32 v10, 16, v95
	v_and_b32_e32 v11, 0xffff0000, v95
	v_pk_fma_f32 v[10:11], v[22:23], v[10:11], 0 op_sel_hi:[0, 1, 0]
	v_lshlrev_b32_e32 v12, 16, v99
	v_and_b32_e32 v13, 0xffff0000, v99
	v_pk_fma_f32 v[10:11], v[24:25], v[12:13], v[10:11] op_sel_hi:[0, 1, 1]
	v_pk_fma_f32 v[10:11], v[18:19], v[10:11], v[12:13] op_sel_hi:[0, 1, 1] neg_lo:[0, 0, 1] neg_hi:[0, 0, 1]
	v_cvt_pk_bf16_f32 v9, v10, v11
	s_nop 0
	s_nop 0
	s_waitcnt vmcnt(3)
	v_lshlrev_b32_e32 v26, 16, v100
	v_and_b32_e32 v27, 0xffff0000, v100
	v_pk_fma_f32 v[26:27], v[22:23], v[26:27], 0 op_sel_hi:[0, 1, 0]
	s_waitcnt vmcnt(2)
	v_lshlrev_b32_e32 v36, 16, v104
	v_and_b32_e32 v37, 0xffff0000, v104
	v_pk_fma_f32 v[26:27], v[24:25], v[36:37], v[26:27] op_sel_hi:[0, 1, 1]
	v_pk_fma_f32 v[26:27], v[18:19], v[26:27], v[36:37] op_sel_hi:[0, 1, 1] neg_lo:[0, 0, 1] neg_hi:[0, 0, 1]
	v_cvt_pk_bf16_f32 v10, v26, v27
	v_lshlrev_b32_e32 v26, 16, v101
	v_and_b32_e32 v27, 0xffff0000, v101
	v_pk_fma_f32 v[26:27], v[22:23], v[26:27], 0 op_sel_hi:[0, 1, 0]
	v_lshlrev_b32_e32 v30, 16, v105
	v_and_b32_e32 v31, 0xffff0000, v105
	v_pk_fma_f32 v[26:27], v[24:25], v[30:31], v[26:27] op_sel_hi:[0, 1, 1]
	v_pk_fma_f32 v[26:27], v[18:19], v[26:27], v[30:31] op_sel_hi:[0, 1, 1] neg_lo:[0, 0, 1] neg_hi:[0, 0, 1]
	v_cvt_pk_bf16_f32 v11, v26, v27
	v_lshlrev_b32_e32 v26, 16, v102
	v_and_b32_e32 v27, 0xffff0000, v102
	v_pk_fma_f32 v[26:27], v[22:23], v[26:27], 0 op_sel_hi:[0, 1, 0]
	v_lshlrev_b32_e32 v30, 16, v106
	v_and_b32_e32 v31, 0xffff0000, v106
	v_pk_fma_f32 v[26:27], v[24:25], v[30:31], v[26:27] op_sel_hi:[0, 1, 1]
	v_pk_fma_f32 v[26:27], v[18:19], v[26:27], v[30:31] op_sel_hi:[0, 1, 1] neg_lo:[0, 0, 1] neg_hi:[0, 0, 1]
	v_cvt_pk_bf16_f32 v12, v26, v27
	v_lshlrev_b32_e32 v26, 16, v103
	v_and_b32_e32 v27, 0xffff0000, v103
	v_pk_fma_f32 v[26:27], v[22:23], v[26:27], 0 op_sel_hi:[0, 1, 0]
	v_lshlrev_b32_e32 v30, 16, v107
	v_and_b32_e32 v31, 0xffff0000, v107
	v_pk_fma_f32 v[26:27], v[24:25], v[30:31], v[26:27] op_sel_hi:[0, 1, 1]
	v_pk_fma_f32 v[26:27], v[18:19], v[26:27], v[30:31] op_sel_hi:[0, 1, 1] neg_lo:[0, 0, 1] neg_hi:[0, 0, 1]
	s_nop 0
	s_nop 0
	s_nop 0
	v_cvt_pk_bf16_f32 v13, v26, v27
	s_waitcnt vmcnt(1)
	v_lshlrev_b32_e32 v26, 16, v108
	v_and_b32_e32 v27, 0xffff0000, v108
	v_pk_fma_f32 v[26:27], v[22:23], v[26:27], 0 op_sel_hi:[0, 1, 0]
	s_waitcnt vmcnt(0)
	v_lshlrev_b32_e32 v36, 16, v112
	v_and_b32_e32 v37, 0xffff0000, v112
	v_pk_fma_f32 v[26:27], v[24:25], v[36:37], v[26:27] op_sel_hi:[0, 1, 1]
	v_pk_fma_f32 v[26:27], v[18:19], v[26:27], v[36:37] op_sel_hi:[0, 1, 1] neg_lo:[0, 0, 1] neg_hi:[0, 0, 1]
	v_cvt_pk_bf16_f32 v14, v26, v27
	v_lshlrev_b32_e32 v26, 16, v109
	v_and_b32_e32 v27, 0xffff0000, v109
	v_pk_fma_f32 v[26:27], v[22:23], v[26:27], 0 op_sel_hi:[0, 1, 0]
	v_lshlrev_b32_e32 v30, 16, v113
	v_and_b32_e32 v31, 0xffff0000, v113
	v_pk_fma_f32 v[26:27], v[24:25], v[30:31], v[26:27] op_sel_hi:[0, 1, 1]
	v_pk_fma_f32 v[26:27], v[18:19], v[26:27], v[30:31] op_sel_hi:[0, 1, 1] neg_lo:[0, 0, 1] neg_hi:[0, 0, 1]
	v_cvt_pk_bf16_f32 v15, v26, v27
	v_lshlrev_b32_e32 v26, 16, v110
	v_and_b32_e32 v27, 0xffff0000, v110
	v_pk_fma_f32 v[26:27], v[22:23], v[26:27], 0 op_sel_hi:[0, 1, 0]
	v_lshlrev_b32_e32 v30, 16, v114
	v_and_b32_e32 v31, 0xffff0000, v114
	v_pk_fma_f32 v[26:27], v[24:25], v[30:31], v[26:27] op_sel_hi:[0, 1, 1]
	v_pk_fma_f32 v[26:27], v[18:19], v[26:27], v[30:31] op_sel_hi:[0, 1, 1] neg_lo:[0, 0, 1] neg_hi:[0, 0, 1]
	v_cvt_pk_bf16_f32 v16, v26, v27
	v_lshlrev_b32_e32 v26, 16, v111
	v_and_b32_e32 v27, 0xffff0000, v111
	v_pk_fma_f32 v[26:27], v[22:23], v[26:27], 0 op_sel_hi:[0, 1, 0]
	v_lshlrev_b32_e32 v30, 16, v115
	v_and_b32_e32 v31, 0xffff0000, v115
	v_pk_fma_f32 v[24:25], v[24:25], v[30:31], v[26:27] op_sel_hi:[0, 1, 1]
	v_pk_fma_f32 v[18:19], v[18:19], v[24:25], v[30:31] op_sel_hi:[0, 1, 1] neg_lo:[0, 0, 1] neg_hi:[0, 0, 1]
	v_cvt_pk_bf16_f32 v17, v18, v19
	v_lshl_add_u64 v[18:19], s[38:39], 0, v[28:29]
	v_lshl_add_u64 v[30:31], s[84:85], 0, v[20:21]
	v_lshlrev_b32_e32 v20, 8, v23
	v_mov_b32_e32 v21, v1
	v_lshl_add_u64 v[32:33], v[18:19], 0, v[20:21]
	v_add_co_u32_e32 v56, vcc, 0x1000, v32
	s_nop 1
	v_addc_co_u32_e32 v57, vcc, 0, v33, vcc
	v_add_co_u32_e32 v58, vcc, 0x3000, v32
	s_nop 1
	v_addc_co_u32_e32 v59, vcc, 0, v33, vcc
	v_add_co_u32_e32 v60, vcc, 0x5000, v32
	s_nop 1
	v_addc_co_u32_e32 v61, vcc, 0, v33, vcc
	v_add_co_u32_e32 v62, vcc, 0x7000, v32
	s_nop 1
	v_addc_co_u32_e32 v63, vcc, 0, v33, vcc
	v_and_b32_e32 v56, 15, v209
	v_bfe_u32 v57, v209, 4, 2
	v_mul_u32_u24_e32 v56, 0x110, v56
	v_lshl_add_u32 v56, v57, 4, v56
	v_add_u32_e32 v57, 0x22000, v28
	ds_read_b128 v[100:103], v57 offset:0
	ds_read_b128 v[120:123], v57 offset:64
	ds_read_b128 v[140:143], v57 offset:128
	ds_read_b128 v[160:163], v57 offset:192
	ds_read_b128 v[180:183], v57 offset:256
	ds_read_b128 v[200:203], v57 offset:320
	ds_read_b128 v[234:237], v57 offset:384
	ds_read_b128 v[84:87], v56 offset:0
	ds_read_b128 v[88:91], v56 offset:64
	ds_read_b128 v[92:95], v56 offset:128
	ds_read_b128 v[96:99], v56 offset:192
	ds_read_b128 v[104:107], v56 offset:4352
	ds_read_b128 v[108:111], v56 offset:4416
	ds_read_b128 v[112:115], v56 offset:4480
	ds_read_b128 v[116:119], v56 offset:4544
	s_nop 0
	s_nop 0
	s_waitcnt lgkmcnt(4)
	v_mfma_f32_16x16x32_bf16 v[18:21], v[84:87], v[2:5], 0
	v_lshl_add_u64 v[26:27], v[30:31], 0, s[0:1]
	s_movk_i32 s0, 0x1000
	v_mfma_f32_16x16x32_bf16 v[18:21], v[88:91], v[6:9], v[18:21]
	s_nop 0
	v_mfma_f32_16x16x32_bf16 v[18:21], v[92:95], v[10:13], v[18:21]
	s_nop 0
	v_mfma_f32_16x16x32_bf16 v[18:21], v[96:99], v[14:17], v[18:21]
	ds_read_b128 v[124:127], v56 offset:8704
	ds_read_b128 v[128:131], v56 offset:8768
	ds_read_b128 v[132:135], v56 offset:8832
	ds_read_b128 v[136:139], v56 offset:8896
	s_nop 0
	s_nop 0
	s_nop 5
	v_pk_mul_f32 v[20:21], v[20:21], v[102:103]
	v_add_co_u32_e32 v24, vcc, s0, v32
	v_pk_mul_f32 v[18:19], v[18:19], v[100:101]
	s_nop 0
	v_addc_co_u32_e32 v25, vcc, 0, v33, vcc
	s_movk_i32 s0, 0x2000
	v_cvt_pk_bf16_f32 v22, v18, v19
	v_cvt_pk_bf16_f32 v23, v20, v21
	v_lshl_add_u64 v[18:19], v[30:31], 0, v[0:1]
	v_add_co_u32_e32 v30, vcc, s0, v32
	global_store_dwordx2 v[18:19], v[22:23], off offset:1024
	s_nop 0
	v_addc_co_u32_e32 v31, vcc, 0, v33, vcc
	s_nop 0
	s_nop 0
	s_waitcnt lgkmcnt(4)
	v_mfma_f32_16x16x32_bf16 v[20:23], v[104:107], v[2:5], 0
	s_movk_i32 s0, 0x3000
	v_mov_b32_e32 v0, 0x70
	v_lshl_or_b32 v0, v34, 2, v0
	v_mfma_f32_16x16x32_bf16 v[20:23], v[108:111], v[6:9], v[20:23]
	s_nop 0
	v_mfma_f32_16x16x32_bf16 v[20:23], v[112:115], v[10:13], v[20:23]
	s_nop 0
	v_add_co_u32_e32 v24, vcc, s0, v32
	v_mfma_f32_16x16x32_bf16 v[20:23], v[116:119], v[14:17], v[20:23]
	ds_read_b128 v[144:147], v56 offset:13056
	ds_read_b128 v[148:151], v56 offset:13120
	ds_read_b128 v[152:155], v56 offset:13184
	ds_read_b128 v[156:159], v56 offset:13248
	s_nop 0
	v_addc_co_u32_e32 v25, vcc, 0, v33, vcc
	s_movk_i32 s0, 0x4000
	s_nop 0
	s_nop 3
	v_pk_mul_f32 v[22:23], v[22:23], v[122:123]
	v_pk_mul_f32 v[20:21], v[20:21], v[120:121]
	s_nop 0
	v_cvt_pk_bf16_f32 v20, v20, v21
	v_cvt_pk_bf16_f32 v21, v22, v23
	global_store_dwordx2 v[18:19], v[20:21], off offset:1056
	s_nop 0
	s_nop 0
	s_nop 0
	s_waitcnt lgkmcnt(4)
	v_mfma_f32_16x16x32_bf16 v[20:23], v[124:127], v[2:5], 0
	v_mfma_f32_16x16x32_bf16 v[20:23], v[128:131], v[6:9], v[20:23]
	s_nop 0
	v_mfma_f32_16x16x32_bf16 v[20:23], v[132:135], v[10:13], v[20:23]
	s_nop 0
	v_add_co_u32_e32 v30, vcc, s0, v32
	v_mfma_f32_16x16x32_bf16 v[20:23], v[136:139], v[14:17], v[20:23]
	ds_read_b128 v[164:167], v56 offset:17408
	ds_read_b128 v[168:171], v56 offset:17472
	ds_read_b128 v[172:175], v56 offset:17536
	ds_read_b128 v[176:179], v56 offset:17600
	s_nop 0
	v_addc_co_u32_e32 v31, vcc, 0, v33, vcc
	s_movk_i32 s0, 0x5000
	s_nop 0
	s_nop 3
	v_pk_mul_f32 v[22:23], v[22:23], v[142:143]
	v_pk_mul_f32 v[20:21], v[20:21], v[140:141]
	s_nop 0
	v_cvt_pk_bf16_f32 v20, v20, v21
	v_cvt_pk_bf16_f32 v21, v22, v23
	global_store_dwordx2 v[18:19], v[20:21], off offset:1088
	s_nop 0
	s_nop 0
	s_nop 0
	s_waitcnt lgkmcnt(4)
	v_mfma_f32_16x16x32_bf16 v[20:23], v[144:147], v[2:5], 0
	v_mfma_f32_16x16x32_bf16 v[20:23], v[148:151], v[6:9], v[20:23]
	s_nop 0
	v_mfma_f32_16x16x32_bf16 v[20:23], v[152:155], v[10:13], v[20:23]
	s_nop 0
	v_add_co_u32_e32 v24, vcc, s0, v32
	v_mfma_f32_16x16x32_bf16 v[20:23], v[156:159], v[14:17], v[20:23]
	ds_read_b128 v[184:187], v56 offset:21760
	ds_read_b128 v[188:191], v56 offset:21824
	ds_read_b128 v[192:195], v56 offset:21888
	ds_read_b128 v[196:199], v56 offset:21952
	s_nop 0
	v_addc_co_u32_e32 v25, vcc, 0, v33, vcc
	s_movk_i32 s0, 0x6000
	s_nop 0
	s_nop 3
	v_pk_mul_f32 v[22:23], v[22:23], v[162:163]
	v_pk_mul_f32 v[20:21], v[20:21], v[160:161]
	s_nop 0
	v_cvt_pk_bf16_f32 v20, v20, v21
	v_cvt_pk_bf16_f32 v21, v22, v23
	global_store_dwordx2 v[18:19], v[20:21], off offset:1120
	s_nop 0
	s_nop 0
	s_nop 0
	s_waitcnt lgkmcnt(4)
	v_mfma_f32_16x16x32_bf16 v[20:23], v[164:167], v[2:5], 0
	v_mfma_f32_16x16x32_bf16 v[20:23], v[168:171], v[6:9], v[20:23]
	s_nop 0
	v_mfma_f32_16x16x32_bf16 v[20:23], v[172:175], v[10:13], v[20:23]
	s_nop 0
	v_add_co_u32_e32 v30, vcc, s0, v32
	v_mfma_f32_16x16x32_bf16 v[20:23], v[176:179], v[14:17], v[20:23]
	ds_read_b128 v[204:207], v56 offset:26112
	ds_read_b128 v[222:225], v56 offset:26176
	ds_read_b128 v[226:229], v56 offset:26240
	ds_read_b128 v[230:233], v56 offset:26304
	s_nop 0
	v_addc_co_u32_e32 v31, vcc, 0, v33, vcc
	s_nop 0
	s_nop 4
	v_pk_mul_f32 v[22:23], v[22:23], v[182:183]
	v_pk_mul_f32 v[20:21], v[20:21], v[180:181]
	s_nop 0
	v_cvt_pk_bf16_f32 v20, v20, v21
	v_cvt_pk_bf16_f32 v21, v22, v23
	global_store_dwordx2 v[18:19], v[20:21], off offset:1152
	s_nop 0
	s_nop 0
	s_nop 0
	s_waitcnt lgkmcnt(4)
	v_mfma_f32_16x16x32_bf16 v[20:23], v[184:187], v[2:5], 0
	v_mfma_f32_16x16x32_bf16 v[20:23], v[188:191], v[6:9], v[20:23]
	s_nop 0
	v_mfma_f32_16x16x32_bf16 v[20:23], v[192:195], v[10:13], v[20:23]
	s_nop 0
	v_mfma_f32_16x16x32_bf16 v[20:23], v[196:199], v[14:17], v[20:23]
	ds_read_b128 v[238:241], v56 offset:30464
	ds_read_b128 v[242:245], v56 offset:30528
	ds_read_b128 v[246:249], v56 offset:30592
	ds_read_b128 v[52:55], v56 offset:30656
	s_nop 0
	s_nop 0
	s_nop 5
	v_pk_mul_f32 v[22:23], v[22:23], v[202:203]
	v_pk_mul_f32 v[20:21], v[20:21], v[200:201]
	s_nop 0
	v_cvt_pk_bf16_f32 v20, v20, v21
	v_cvt_pk_bf16_f32 v21, v22, v23
	global_store_dwordx2 v[18:19], v[20:21], off offset:1184
	s_nop 0
	s_nop 0
	s_nop 0
	s_waitcnt lgkmcnt(4)
	v_mfma_f32_16x16x32_bf16 v[20:23], v[204:207], v[2:5], 0
	v_mfma_f32_16x16x32_bf16 v[20:23], v[222:225], v[6:9], v[20:23]
	s_nop 0
	v_mfma_f32_16x16x32_bf16 v[20:23], v[226:229], v[10:13], v[20:23]
	s_nop 0
	s_nop 0
	s_nop 0
	v_mfma_f32_16x16x32_bf16 v[20:23], v[230:233], v[14:17], v[20:23]
	s_nop 0
	s_nop 6
	v_pk_mul_f32 v[22:23], v[22:23], v[236:237]
	v_pk_mul_f32 v[20:21], v[20:21], v[234:235]
	s_nop 0
	v_cvt_pk_bf16_f32 v20, v20, v21
	v_cvt_pk_bf16_f32 v21, v22, v23
	v_add_co_u32_e32 v22, vcc, 0x7000, v32
	global_store_dwordx2 v[18:19], v[20:21], off offset:1216
	s_nop 0
	v_addc_co_u32_e32 v23, vcc, 0, v33, vcc
	s_nop 0
	s_waitcnt lgkmcnt(0)
	v_mfma_f32_16x16x32_bf16 v[2:5], v[238:241], v[2:5], 0
	s_nop 0
	v_mfma_f32_16x16x32_bf16 v[2:5], v[242:245], v[6:9], v[2:5]
	s_nop 0
	v_mfma_f32_16x16x32_bf16 v[2:5], v[246:249], v[10:13], v[2:5]
	s_nop 0
	v_mfma_f32_16x16x32_bf16 v[2:5], v[52:55], v[14:17], v[2:5]
	s_branch .LBB0_579
